# v83 + loop-end bookkeeping hoisted into the last MFMA block + redundant post-barrier lgkmcnt(0) waits removed (the pre-barrier wait stays)
# speedup vs baseline: 1.0111x; 1.0111x over previous
.Lbal_first_21:
	s_add_u32 s26, s24, 0xfffc0080
	s_addc_u32 s27, s25, -1
	s_cmp_eq_u32 s55, 12
	s_cselect_b32 s29, s19, s27
	s_cselect_b32 s28, s51, s26
	s_cselect_b32 s27, s17, s54
	s_cselect_b32 s26, s52, s53
	s_add_i32 m0, s38, 0xc000
	s_nop 0
	global_load_lds_dwordx4 v138, s[24:25]
	s_add_i32 m0, s38, 0xe000
	s_nop 0
	global_load_lds_dwordx4 v136, s[24:25]
	ds_read_b128 v[144:147], v151
	ds_read_b128 v[156:159], v151 offset:1024
	ds_read_b128 v[160:163], v151 offset:2048
	ds_read_b128 v[164:167], v151 offset:3072
	ds_read_b128 v[168:171], v152
	ds_read_b128 v[172:175], v152 offset:1024
	ds_read_b128 v[176:179], v152 offset:2048
	ds_read_b128 v[180:183], v152 offset:3072
	ds_read_b128 v[184:187], v153
	ds_read_b128 v[188:191], v153 offset:1024
	ds_read_b128 v[192:195], v153 offset:2048
	ds_read_b128 v[196:199], v153 offset:3072
	ds_read_b128 v[200:203], v153 offset:4096
	ds_read_b128 v[208:211], v153 offset:5120
	ds_read_b128 v[212:215], v153 offset:6144
	ds_read_b128 v[216:219], v153 offset:7168
	s_waitcnt vmcnt(8)
	s_waitcnt lgkmcnt(0)
	s_barrier
	v_mfma_f32_16x16x32_bf16 v[124:127], v[144:147], v[184:187], v[124:127]
	v_mfma_f32_16x16x32_bf16 v[120:123], v[160:163], v[184:187], v[120:123]
	v_mfma_f32_16x16x32_bf16 v[108:111], v[144:147], v[192:195], v[108:111]
	v_mfma_f32_16x16x32_bf16 v[104:107], v[160:163], v[192:195], v[104:107]
	v_mfma_f32_16x16x32_bf16 v[92:95], v[144:147], v[200:203], v[92:95]
	v_mfma_f32_16x16x32_bf16 v[88:91], v[160:163], v[200:203], v[88:91]
	v_mfma_f32_16x16x32_bf16 v[76:79], v[144:147], v[212:215], v[76:79]
	v_mfma_f32_16x16x32_bf16 v[72:75], v[160:163], v[212:215], v[72:75]
	v_mfma_f32_16x16x32_bf16 v[124:127], v[156:159], v[188:191], v[124:127]
	v_mfma_f32_16x16x32_bf16 v[120:123], v[164:167], v[188:191], v[120:123]
	v_mfma_f32_16x16x32_bf16 v[108:111], v[156:159], v[196:199], v[108:111]
	v_mfma_f32_16x16x32_bf16 v[104:107], v[164:167], v[196:199], v[104:107]
	v_mfma_f32_16x16x32_bf16 v[92:95], v[156:159], v[208:211], v[92:95]
	v_mfma_f32_16x16x32_bf16 v[88:91], v[164:167], v[208:211], v[88:91]
	v_mfma_f32_16x16x32_bf16 v[76:79], v[156:159], v[216:219], v[76:79]
	v_mfma_f32_16x16x32_bf16 v[72:75], v[164:167], v[216:219], v[72:75]
	v_mfma_f32_16x16x32_bf16 v[116:119], v[168:171], v[184:187], v[116:119]
	v_mfma_f32_16x16x32_bf16 v[112:115], v[176:179], v[184:187], v[112:115]
	v_mfma_f32_16x16x32_bf16 v[100:103], v[168:171], v[192:195], v[100:103]
	v_mfma_f32_16x16x32_bf16 v[96:99], v[176:179], v[192:195], v[96:99]
	v_mfma_f32_16x16x32_bf16 v[84:87], v[168:171], v[200:203], v[84:87]
	v_mfma_f32_16x16x32_bf16 v[80:83], v[176:179], v[200:203], v[80:83]
	v_mfma_f32_16x16x32_bf16 v[68:71], v[168:171], v[212:215], v[68:71]
	v_mfma_f32_16x16x32_bf16 v[64:67], v[176:179], v[212:215], v[64:67]
	v_mfma_f32_16x16x32_bf16 v[116:119], v[172:175], v[188:191], v[116:119]
	v_mfma_f32_16x16x32_bf16 v[112:115], v[180:183], v[188:191], v[112:115]
	v_mfma_f32_16x16x32_bf16 v[100:103], v[172:175], v[196:199], v[100:103]
	v_mfma_f32_16x16x32_bf16 v[96:99], v[180:183], v[196:199], v[96:99]
	v_mfma_f32_16x16x32_bf16 v[84:87], v[172:175], v[208:211], v[84:87]
	v_mfma_f32_16x16x32_bf16 v[80:83], v[180:183], v[208:211], v[80:83]
	v_mfma_f32_16x16x32_bf16 v[68:71], v[172:175], v[216:219], v[68:71]
	v_mfma_f32_16x16x32_bf16 v[64:67], v[180:183], v[216:219], v[64:67]
	s_barrier
	s_add_i32 s56, s48, s35
	s_mov_b32 m0, s56
	s_nop 0
	global_load_lds_dwordx4 v132, s[26:27]
	s_add_i32 m0, s56, 0x2000
	s_add_u32 s56, s26, 0x40000
	s_mov_b64 s[98:99], s[26:27]
	s_addc_u32 s57, s27, 0
	s_add_i32 s58, s49, s35
	global_load_lds_dwordx4 v128, s[26:27]
	s_mov_b32 m0, s58
	s_mov_b64 s[100:101], s[28:29]
	global_load_lds_dwordx4 v132, s[56:57]
	s_add_i32 m0, s58, 0x2000
	s_nop 0
	global_load_lds_dwordx4 v128, s[56:57]
	ds_read_b128 v[184:187], v153 offset:16384
	ds_read_b128 v[188:191], v153 offset:17408
	ds_read_b128 v[192:195], v153 offset:18432
	ds_read_b128 v[196:199], v153 offset:19456
	ds_read_b128 v[200:203], v153 offset:20480
	ds_read_b128 v[208:211], v153 offset:21504
	ds_read_b128 v[212:215], v153 offset:22528
	ds_read_b128 v[216:219], v153 offset:23552
	s_waitcnt vmcnt(6)
	s_waitcnt lgkmcnt(0)
	s_barrier
	v_mfma_f32_16x16x32_bf16 v[60:63], v[144:147], v[184:187], v[60:63]
	v_mfma_f32_16x16x32_bf16 v[56:59], v[160:163], v[184:187], v[56:59]
	v_mfma_f32_16x16x32_bf16 v[44:47], v[144:147], v[192:195], v[44:47]
	v_mfma_f32_16x16x32_bf16 v[40:43], v[160:163], v[192:195], v[40:43]
	v_mfma_f32_16x16x32_bf16 v[28:31], v[144:147], v[200:203], v[28:31]
	v_mfma_f32_16x16x32_bf16 v[24:27], v[160:163], v[200:203], v[24:27]
	v_mfma_f32_16x16x32_bf16 v[12:15], v[144:147], v[212:215], v[12:15]
	v_mfma_f32_16x16x32_bf16 v[8:11], v[160:163], v[212:215], v[8:11]
	v_mfma_f32_16x16x32_bf16 v[60:63], v[156:159], v[188:191], v[60:63]
	v_mfma_f32_16x16x32_bf16 v[56:59], v[164:167], v[188:191], v[56:59]
	v_mfma_f32_16x16x32_bf16 v[44:47], v[156:159], v[196:199], v[44:47]
	v_mfma_f32_16x16x32_bf16 v[40:43], v[164:167], v[196:199], v[40:43]
	v_mfma_f32_16x16x32_bf16 v[28:31], v[156:159], v[208:211], v[28:31]
	v_mfma_f32_16x16x32_bf16 v[24:27], v[164:167], v[208:211], v[24:27]
	v_mfma_f32_16x16x32_bf16 v[12:15], v[156:159], v[216:219], v[12:15]
	v_mfma_f32_16x16x32_bf16 v[8:11], v[164:167], v[216:219], v[8:11]
	v_mfma_f32_16x16x32_bf16 v[52:55], v[168:171], v[184:187], v[52:55]
	v_mfma_f32_16x16x32_bf16 v[48:51], v[176:179], v[184:187], v[48:51]
	v_mfma_f32_16x16x32_bf16 v[36:39], v[168:171], v[192:195], v[36:39]
	v_mfma_f32_16x16x32_bf16 v[32:35], v[176:179], v[192:195], v[32:35]
	v_mfma_f32_16x16x32_bf16 v[20:23], v[168:171], v[200:203], v[20:23]
	v_mfma_f32_16x16x32_bf16 v[16:19], v[176:179], v[200:203], v[16:19]
	v_mfma_f32_16x16x32_bf16 v[4:7], v[168:171], v[212:215], v[4:7]
	v_mfma_f32_16x16x32_bf16 v[0:3], v[176:179], v[212:215], v[0:3]
	v_mfma_f32_16x16x32_bf16 v[52:55], v[172:175], v[188:191], v[52:55]
	v_mfma_f32_16x16x32_bf16 v[48:51], v[180:183], v[188:191], v[48:51]
	v_mfma_f32_16x16x32_bf16 v[36:39], v[172:175], v[196:199], v[36:39]
	v_mfma_f32_16x16x32_bf16 v[32:35], v[180:183], v[196:199], v[32:35]
	v_mfma_f32_16x16x32_bf16 v[20:23], v[172:175], v[208:211], v[20:23]
	v_mfma_f32_16x16x32_bf16 v[16:19], v[180:183], v[208:211], v[16:19]
	v_mfma_f32_16x16x32_bf16 v[4:7], v[172:175], v[216:219], v[4:7]
	v_mfma_f32_16x16x32_bf16 v[0:3], v[180:183], v[216:219], v[0:3]
	s_barrier
	s_mov_b32 m0, s38
	s_nop 0
	global_load_lds_dwordx4 v134, s[28:29]
	s_mov_b32 m0, s39
	s_nop 0
	global_load_lds_dwordx4 v130, s[28:29]
	s_add_i32 s56, 0, 0x18000
	s_add_i32 s57, 0, 0x1c000
	s_add_u32 s28, s28, 0x40000
	s_addc_u32 s29, s29, 0
	s_mov_b32 m0, s40
	s_nop 0
	global_load_lds_dwordx4 v134, s[28:29]
	s_mov_b32 m0, s41
	s_nop 0
	global_load_lds_dwordx4 v130, s[28:29]
	v_add_u32_e32 v164, s56, v149
	v_add_u32_e32 v180, s57, v149
	ds_read_b128 v[144:147], v164
	ds_read_b128 v[156:159], v164 offset:1024
	ds_read_b128 v[160:163], v164 offset:2048
	ds_read_b128 v[164:167], v164 offset:3072
	ds_read_b128 v[168:171], v180
	ds_read_b128 v[172:175], v180 offset:1024
	ds_read_b128 v[176:179], v180 offset:2048
	ds_read_b128 v[180:183], v180 offset:3072
	ds_read_b128 v[184:187], v153 offset:32768
	ds_read_b128 v[188:191], v153 offset:33792
	ds_read_b128 v[192:195], v153 offset:34816
	ds_read_b128 v[196:199], v153 offset:35840
	ds_read_b128 v[200:203], v153 offset:36864
	ds_read_b128 v[208:211], v153 offset:37888
	ds_read_b128 v[212:215], v153 offset:38912
	ds_read_b128 v[216:219], v153 offset:39936
	s_waitcnt vmcnt(8)
	s_waitcnt lgkmcnt(0)
	s_barrier
	v_mfma_f32_16x16x32_bf16 v[124:127], v[144:147], v[184:187], v[124:127]
	v_mfma_f32_16x16x32_bf16 v[120:123], v[160:163], v[184:187], v[120:123]
	v_mfma_f32_16x16x32_bf16 v[108:111], v[144:147], v[192:195], v[108:111]
	v_mfma_f32_16x16x32_bf16 v[104:107], v[160:163], v[192:195], v[104:107]
	v_mfma_f32_16x16x32_bf16 v[92:95], v[144:147], v[200:203], v[92:95]
	v_mfma_f32_16x16x32_bf16 v[88:91], v[160:163], v[200:203], v[88:91]
	v_mfma_f32_16x16x32_bf16 v[76:79], v[144:147], v[212:215], v[76:79]
	v_mfma_f32_16x16x32_bf16 v[72:75], v[160:163], v[212:215], v[72:75]
	v_mfma_f32_16x16x32_bf16 v[124:127], v[156:159], v[188:191], v[124:127]
	v_mfma_f32_16x16x32_bf16 v[120:123], v[164:167], v[188:191], v[120:123]
	v_mfma_f32_16x16x32_bf16 v[108:111], v[156:159], v[196:199], v[108:111]
	v_mfma_f32_16x16x32_bf16 v[104:107], v[164:167], v[196:199], v[104:107]
	v_mfma_f32_16x16x32_bf16 v[92:95], v[156:159], v[208:211], v[92:95]
	v_mfma_f32_16x16x32_bf16 v[88:91], v[164:167], v[208:211], v[88:91]
	v_mfma_f32_16x16x32_bf16 v[76:79], v[156:159], v[216:219], v[76:79]
	v_mfma_f32_16x16x32_bf16 v[72:75], v[164:167], v[216:219], v[72:75]
	v_mfma_f32_16x16x32_bf16 v[116:119], v[168:171], v[184:187], v[116:119]
	v_mfma_f32_16x16x32_bf16 v[112:115], v[176:179], v[184:187], v[112:115]
	v_mfma_f32_16x16x32_bf16 v[100:103], v[168:171], v[192:195], v[100:103]
	v_mfma_f32_16x16x32_bf16 v[96:99], v[176:179], v[192:195], v[96:99]
	v_mfma_f32_16x16x32_bf16 v[84:87], v[168:171], v[200:203], v[84:87]
	v_mfma_f32_16x16x32_bf16 v[80:83], v[176:179], v[200:203], v[80:83]
	v_mfma_f32_16x16x32_bf16 v[68:71], v[168:171], v[212:215], v[68:71]
	v_mfma_f32_16x16x32_bf16 v[64:67], v[176:179], v[212:215], v[64:67]
	v_mfma_f32_16x16x32_bf16 v[116:119], v[172:175], v[188:191], v[116:119]
	v_mfma_f32_16x16x32_bf16 v[112:115], v[180:183], v[188:191], v[112:115]
	v_mfma_f32_16x16x32_bf16 v[100:103], v[172:175], v[196:199], v[100:103]
	v_mfma_f32_16x16x32_bf16 v[96:99], v[180:183], v[196:199], v[96:99]
	v_mfma_f32_16x16x32_bf16 v[84:87], v[172:175], v[208:211], v[84:87]
	v_mfma_f32_16x16x32_bf16 v[80:83], v[180:183], v[208:211], v[80:83]
	v_mfma_f32_16x16x32_bf16 v[68:71], v[172:175], v[216:219], v[68:71]
	v_mfma_f32_16x16x32_bf16 v[64:67], v[180:183], v[216:219], v[64:67]
	s_barrier
	s_add_i32 s28, s56, s35
	s_mov_b32 m0, s28
	s_nop 0
	global_load_lds_dwordx4 v220, s[26:27]
	s_add_i32 m0, s28, 0x2000
	s_add_u32 s26, s26, 0x40080
	s_addc_u32 s27, s27, 0
	s_add_i32 s28, s57, s35
	global_load_lds_dwordx4 v204, s[98:99]
	s_mov_b32 m0, s28
	s_nop 0
	global_load_lds_dwordx4 v132, s[26:27]
	s_add_i32 m0, s28, 0x2000
	s_nop 0
	global_load_lds_dwordx4 v128, s[26:27]
	s_cmp_lg_u32 s55, 12
	s_cbranch_scc1 .Lbal_last_21
	s_mov_b32 m0, s45
	s_nop 0
	global_load_lds_dwordx4 v221, s[100:101]
	s_mov_b32 m0, s46
	s_nop 0
	global_load_lds_dwordx4 v205, s[100:101]
.Lbal_last_21:
	ds_read_b128 v[184:187], v153 offset:49152
	ds_read_b128 v[188:191], v153 offset:50176
	ds_read_b128 v[192:195], v153 offset:51200
	ds_read_b128 v[196:199], v153 offset:52224
	ds_read_b128 v[200:203], v153 offset:53248
	ds_read_b128 v[208:211], v153 offset:54272
	ds_read_b128 v[212:215], v153 offset:55296
	ds_read_b128 v[216:219], v153 offset:56320
	s_waitcnt vmcnt(6)
	s_waitcnt lgkmcnt(0)
	s_barrier
	v_mfma_f32_16x16x32_bf16 v[60:63], v[144:147], v[184:187], v[60:63]
	v_mfma_f32_16x16x32_bf16 v[56:59], v[160:163], v[184:187], v[56:59]
	v_mfma_f32_16x16x32_bf16 v[44:47], v[144:147], v[192:195], v[44:47]
	v_mfma_f32_16x16x32_bf16 v[40:43], v[160:163], v[192:195], v[40:43]
	s_add_i32 s55, s55, 2
	s_add_u32 s53, s53, 0x100
	s_addc_u32 s54, s54, 0
	s_add_u32 s24, s24, 0x100
	s_addc_u32 s25, s25, 0
	s_cmp_gt_u32 s55, 13
	v_mfma_f32_16x16x32_bf16 v[28:31], v[144:147], v[200:203], v[28:31]
	v_mfma_f32_16x16x32_bf16 v[24:27], v[160:163], v[200:203], v[24:27]
	v_mfma_f32_16x16x32_bf16 v[12:15], v[144:147], v[212:215], v[12:15]
	v_mfma_f32_16x16x32_bf16 v[8:11], v[160:163], v[212:215], v[8:11]
	v_mfma_f32_16x16x32_bf16 v[60:63], v[156:159], v[188:191], v[60:63]
	v_mfma_f32_16x16x32_bf16 v[56:59], v[164:167], v[188:191], v[56:59]
	v_mfma_f32_16x16x32_bf16 v[44:47], v[156:159], v[196:199], v[44:47]
	v_mfma_f32_16x16x32_bf16 v[40:43], v[164:167], v[196:199], v[40:43]
	v_mfma_f32_16x16x32_bf16 v[28:31], v[156:159], v[208:211], v[28:31]
	v_mfma_f32_16x16x32_bf16 v[24:27], v[164:167], v[208:211], v[24:27]
	v_mfma_f32_16x16x32_bf16 v[12:15], v[156:159], v[216:219], v[12:15]
	v_mfma_f32_16x16x32_bf16 v[8:11], v[164:167], v[216:219], v[8:11]
	v_mfma_f32_16x16x32_bf16 v[52:55], v[168:171], v[184:187], v[52:55]
	v_mfma_f32_16x16x32_bf16 v[48:51], v[176:179], v[184:187], v[48:51]
	v_mfma_f32_16x16x32_bf16 v[36:39], v[168:171], v[192:195], v[36:39]
	v_mfma_f32_16x16x32_bf16 v[32:35], v[176:179], v[192:195], v[32:35]
	v_mfma_f32_16x16x32_bf16 v[20:23], v[168:171], v[200:203], v[20:23]
	v_mfma_f32_16x16x32_bf16 v[16:19], v[176:179], v[200:203], v[16:19]
	v_mfma_f32_16x16x32_bf16 v[4:7], v[168:171], v[212:215], v[4:7]
	v_mfma_f32_16x16x32_bf16 v[0:3], v[176:179], v[212:215], v[0:3]
	v_mfma_f32_16x16x32_bf16 v[52:55], v[172:175], v[188:191], v[52:55]
	v_mfma_f32_16x16x32_bf16 v[48:51], v[180:183], v[188:191], v[48:51]
	v_mfma_f32_16x16x32_bf16 v[36:39], v[172:175], v[196:199], v[36:39]
	v_mfma_f32_16x16x32_bf16 v[32:35], v[180:183], v[196:199], v[32:35]
	v_mfma_f32_16x16x32_bf16 v[20:23], v[172:175], v[208:211], v[20:23]
	v_mfma_f32_16x16x32_bf16 v[16:19], v[180:183], v[208:211], v[16:19]
	v_mfma_f32_16x16x32_bf16 v[4:7], v[172:175], v[216:219], v[4:7]
	v_mfma_f32_16x16x32_bf16 v[0:3], v[180:183], v[216:219], v[0:3]
	s_barrier
	s_cbranch_scc0 .LBB0_163
	s_setprio 0
	s_and_b64 vcc, exec, s[14:15]
	s_cbranch_vccz .LBB0_166
	s_barrier

.Lbal_first_20:
	s_add_u32 s30, s28, 0x100
	s_addc_u32 s31, s29, 0
	s_cmp_eq_u32 s58, 12
	s_cselect_b32 s37, s21, s31
	s_cselect_b32 s36, s27, s30
	s_cselect_b32 s35, s19, s57
	s_cselect_b32 s34, s55, s56
	s_add_i32 m0, s44, 0xc000
	s_nop 0
	global_load_lds_dwordx4 v134, s[28:29]
	s_add_i32 m0, s44, 0xe000
	s_nop 0
	global_load_lds_dwordx4 v132, s[28:29]
	ds_read_b128 v[140:143], v147
	ds_read_b128 v[150:153], v147 offset:1024
	ds_read_b128 v[154:157], v147 offset:2048
	ds_read_b128 v[158:161], v147 offset:3072
	ds_read_b128 v[162:165], v148
	ds_read_b128 v[166:169], v148 offset:1024
	ds_read_b128 v[170:173], v148 offset:2048
	ds_read_b128 v[174:177], v148 offset:3072
	ds_read_b128 v[178:181], v149
	ds_read_b128 v[182:185], v149 offset:1024
	ds_read_b128 v[186:189], v149 offset:2048
	ds_read_b128 v[190:193], v149 offset:3072
	ds_read_b128 v[194:197], v149 offset:4096
	ds_read_b128 v[198:201], v149 offset:5120
	ds_read_b128 v[202:205], v149 offset:6144
	ds_read_b128 v[208:211], v149 offset:7168
	s_waitcnt vmcnt(8)
	s_waitcnt lgkmcnt(0)
	s_barrier
	v_mfma_f32_16x16x32_bf16 v[124:127], v[140:143], v[178:181], v[124:127]
	v_mfma_f32_16x16x32_bf16 v[120:123], v[154:157], v[178:181], v[120:123]
	v_mfma_f32_16x16x32_bf16 v[108:111], v[140:143], v[186:189], v[108:111]
	v_mfma_f32_16x16x32_bf16 v[104:107], v[154:157], v[186:189], v[104:107]
	v_mfma_f32_16x16x32_bf16 v[92:95], v[140:143], v[194:197], v[92:95]
	v_mfma_f32_16x16x32_bf16 v[88:91], v[154:157], v[194:197], v[88:91]
	v_mfma_f32_16x16x32_bf16 v[76:79], v[140:143], v[202:205], v[76:79]
	v_mfma_f32_16x16x32_bf16 v[72:75], v[154:157], v[202:205], v[72:75]
	v_mfma_f32_16x16x32_bf16 v[124:127], v[150:153], v[182:185], v[124:127]
	v_mfma_f32_16x16x32_bf16 v[120:123], v[158:161], v[182:185], v[120:123]
	v_mfma_f32_16x16x32_bf16 v[108:111], v[150:153], v[190:193], v[108:111]
	v_mfma_f32_16x16x32_bf16 v[104:107], v[158:161], v[190:193], v[104:107]
	v_mfma_f32_16x16x32_bf16 v[92:95], v[150:153], v[198:201], v[92:95]
	v_mfma_f32_16x16x32_bf16 v[88:91], v[158:161], v[198:201], v[88:91]
	v_mfma_f32_16x16x32_bf16 v[76:79], v[150:153], v[208:211], v[76:79]
	v_mfma_f32_16x16x32_bf16 v[72:75], v[158:161], v[208:211], v[72:75]
	v_mfma_f32_16x16x32_bf16 v[116:119], v[162:165], v[178:181], v[116:119]
	v_mfma_f32_16x16x32_bf16 v[112:115], v[170:173], v[178:181], v[112:115]
	v_mfma_f32_16x16x32_bf16 v[100:103], v[162:165], v[186:189], v[100:103]
	v_mfma_f32_16x16x32_bf16 v[96:99], v[170:173], v[186:189], v[96:99]
	v_mfma_f32_16x16x32_bf16 v[84:87], v[162:165], v[194:197], v[84:87]
	v_mfma_f32_16x16x32_bf16 v[80:83], v[170:173], v[194:197], v[80:83]
	v_mfma_f32_16x16x32_bf16 v[68:71], v[162:165], v[202:205], v[68:71]
	v_mfma_f32_16x16x32_bf16 v[64:67], v[170:173], v[202:205], v[64:67]
	v_mfma_f32_16x16x32_bf16 v[116:119], v[166:169], v[182:185], v[116:119]
	v_mfma_f32_16x16x32_bf16 v[112:115], v[174:177], v[182:185], v[112:115]
	v_mfma_f32_16x16x32_bf16 v[100:103], v[166:169], v[190:193], v[100:103]
	v_mfma_f32_16x16x32_bf16 v[96:99], v[174:177], v[190:193], v[96:99]
	v_mfma_f32_16x16x32_bf16 v[84:87], v[166:169], v[198:201], v[84:87]
	v_mfma_f32_16x16x32_bf16 v[80:83], v[174:177], v[198:201], v[80:83]
	v_mfma_f32_16x16x32_bf16 v[68:71], v[166:169], v[208:211], v[68:71]
	v_mfma_f32_16x16x32_bf16 v[64:67], v[174:177], v[208:211], v[64:67]
	s_barrier
	s_add_i32 s28, s52, s43
	s_mov_b32 m0, s28
	s_nop 0
	global_load_lds_dwordx4 v128, s[34:35]
	s_add_i32 m0, s28, 0x2000
	s_add_u32 s28, s34, 0x40000
	s_mov_b64 s[98:99], s[34:35]
	s_addc_u32 s29, s35, 0
	s_add_i32 s59, s53, s43
	global_load_lds_dwordx4 v130, s[34:35]
	s_mov_b32 m0, s59
	s_nop 0
	global_load_lds_dwordx4 v128, s[28:29]
	s_add_i32 m0, s59, 0x2000
	s_nop 0
	global_load_lds_dwordx4 v130, s[28:29]
	ds_read_b128 v[178:181], v149 offset:16384
	ds_read_b128 v[182:185], v149 offset:17408
	ds_read_b128 v[186:189], v149 offset:18432
	ds_read_b128 v[190:193], v149 offset:19456
	ds_read_b128 v[194:197], v149 offset:20480
	ds_read_b128 v[198:201], v149 offset:21504
	ds_read_b128 v[202:205], v149 offset:22528
	ds_read_b128 v[208:211], v149 offset:23552
	s_waitcnt vmcnt(6)
	s_waitcnt lgkmcnt(0)
	s_barrier
	v_mfma_f32_16x16x32_bf16 v[60:63], v[140:143], v[178:181], v[60:63]
	v_mfma_f32_16x16x32_bf16 v[56:59], v[154:157], v[178:181], v[56:59]
	v_mfma_f32_16x16x32_bf16 v[44:47], v[140:143], v[186:189], v[44:47]
	v_mfma_f32_16x16x32_bf16 v[40:43], v[154:157], v[186:189], v[40:43]
	v_mfma_f32_16x16x32_bf16 v[28:31], v[140:143], v[194:197], v[28:31]
	v_mfma_f32_16x16x32_bf16 v[24:27], v[154:157], v[194:197], v[24:27]
	v_mfma_f32_16x16x32_bf16 v[12:15], v[140:143], v[202:205], v[12:15]
	v_mfma_f32_16x16x32_bf16 v[8:11], v[154:157], v[202:205], v[8:11]
	v_mfma_f32_16x16x32_bf16 v[60:63], v[150:153], v[182:185], v[60:63]
	v_mfma_f32_16x16x32_bf16 v[56:59], v[158:161], v[182:185], v[56:59]
	v_mfma_f32_16x16x32_bf16 v[44:47], v[150:153], v[190:193], v[44:47]
	v_mfma_f32_16x16x32_bf16 v[40:43], v[158:161], v[190:193], v[40:43]
	v_mfma_f32_16x16x32_bf16 v[28:31], v[150:153], v[198:201], v[28:31]
	v_mfma_f32_16x16x32_bf16 v[24:27], v[158:161], v[198:201], v[24:27]
	v_mfma_f32_16x16x32_bf16 v[12:15], v[150:153], v[208:211], v[12:15]
	v_mfma_f32_16x16x32_bf16 v[8:11], v[158:161], v[208:211], v[8:11]
	v_mfma_f32_16x16x32_bf16 v[52:55], v[162:165], v[178:181], v[52:55]
	v_mfma_f32_16x16x32_bf16 v[48:51], v[170:173], v[178:181], v[48:51]
	v_mfma_f32_16x16x32_bf16 v[36:39], v[162:165], v[186:189], v[36:39]
	v_mfma_f32_16x16x32_bf16 v[32:35], v[170:173], v[186:189], v[32:35]
	v_mfma_f32_16x16x32_bf16 v[20:23], v[162:165], v[194:197], v[20:23]
	v_mfma_f32_16x16x32_bf16 v[16:19], v[170:173], v[194:197], v[16:19]
	v_mfma_f32_16x16x32_bf16 v[4:7], v[162:165], v[202:205], v[4:7]
	v_mfma_f32_16x16x32_bf16 v[0:3], v[170:173], v[202:205], v[0:3]
	v_mfma_f32_16x16x32_bf16 v[52:55], v[166:169], v[182:185], v[52:55]
	v_mfma_f32_16x16x32_bf16 v[48:51], v[174:177], v[182:185], v[48:51]
	v_mfma_f32_16x16x32_bf16 v[36:39], v[166:169], v[190:193], v[36:39]
	v_mfma_f32_16x16x32_bf16 v[32:35], v[174:177], v[190:193], v[32:35]
	v_mfma_f32_16x16x32_bf16 v[20:23], v[166:169], v[198:201], v[20:23]
	v_mfma_f32_16x16x32_bf16 v[16:19], v[174:177], v[198:201], v[16:19]
	v_mfma_f32_16x16x32_bf16 v[4:7], v[166:169], v[208:211], v[4:7]
	v_mfma_f32_16x16x32_bf16 v[0:3], v[174:177], v[208:211], v[0:3]
	s_barrier
	s_mov_b32 m0, s44
	s_nop 0
	global_load_lds_dwordx4 v128, s[36:37]
	s_mov_b32 m0, s45
	s_nop 0
	global_load_lds_dwordx4 v130, s[36:37]
	s_add_i32 s59, 0, 0x18000
	s_add_i32 s60, 0, 0x1c000
	s_add_u32 s28, s36, 0x40000
	s_addc_u32 s29, s37, 0
	s_mov_b32 m0, s46
	s_nop 0
	global_load_lds_dwordx4 v128, s[28:29]
	s_mov_b32 m0, s47
	s_nop 0
	global_load_lds_dwordx4 v130, s[28:29]
	v_add_u32_e32 v158, s59, v145
	v_add_u32_e32 v174, s60, v145
	ds_read_b128 v[140:143], v158
	ds_read_b128 v[150:153], v158 offset:1024
	ds_read_b128 v[154:157], v158 offset:2048
	ds_read_b128 v[158:161], v158 offset:3072
	ds_read_b128 v[162:165], v174
	ds_read_b128 v[166:169], v174 offset:1024
	ds_read_b128 v[170:173], v174 offset:2048
	ds_read_b128 v[174:177], v174 offset:3072
	ds_read_b128 v[178:181], v149 offset:32768
	ds_read_b128 v[182:185], v149 offset:33792
	ds_read_b128 v[186:189], v149 offset:34816
	ds_read_b128 v[190:193], v149 offset:35840
	ds_read_b128 v[194:197], v149 offset:36864
	ds_read_b128 v[198:201], v149 offset:37888
	ds_read_b128 v[202:205], v149 offset:38912
	ds_read_b128 v[208:211], v149 offset:39936
	s_waitcnt vmcnt(8)
	s_waitcnt lgkmcnt(0)
	s_barrier
	v_mfma_f32_16x16x32_bf16 v[124:127], v[140:143], v[178:181], v[124:127]
	v_mfma_f32_16x16x32_bf16 v[120:123], v[154:157], v[178:181], v[120:123]
	v_mfma_f32_16x16x32_bf16 v[108:111], v[140:143], v[186:189], v[108:111]
	v_mfma_f32_16x16x32_bf16 v[104:107], v[154:157], v[186:189], v[104:107]
	v_mfma_f32_16x16x32_bf16 v[92:95], v[140:143], v[194:197], v[92:95]
	v_mfma_f32_16x16x32_bf16 v[88:91], v[154:157], v[194:197], v[88:91]
	v_mfma_f32_16x16x32_bf16 v[76:79], v[140:143], v[202:205], v[76:79]
	v_mfma_f32_16x16x32_bf16 v[72:75], v[154:157], v[202:205], v[72:75]
	v_mfma_f32_16x16x32_bf16 v[124:127], v[150:153], v[182:185], v[124:127]
	v_mfma_f32_16x16x32_bf16 v[120:123], v[158:161], v[182:185], v[120:123]
	v_mfma_f32_16x16x32_bf16 v[108:111], v[150:153], v[190:193], v[108:111]
	v_mfma_f32_16x16x32_bf16 v[104:107], v[158:161], v[190:193], v[104:107]
	v_mfma_f32_16x16x32_bf16 v[92:95], v[150:153], v[198:201], v[92:95]
	v_mfma_f32_16x16x32_bf16 v[88:91], v[158:161], v[198:201], v[88:91]
	v_mfma_f32_16x16x32_bf16 v[76:79], v[150:153], v[208:211], v[76:79]
	v_mfma_f32_16x16x32_bf16 v[72:75], v[158:161], v[208:211], v[72:75]
	v_mfma_f32_16x16x32_bf16 v[116:119], v[162:165], v[178:181], v[116:119]
	v_mfma_f32_16x16x32_bf16 v[112:115], v[170:173], v[178:181], v[112:115]
	v_mfma_f32_16x16x32_bf16 v[100:103], v[162:165], v[186:189], v[100:103]
	v_mfma_f32_16x16x32_bf16 v[96:99], v[170:173], v[186:189], v[96:99]
	v_mfma_f32_16x16x32_bf16 v[84:87], v[162:165], v[194:197], v[84:87]
	v_mfma_f32_16x16x32_bf16 v[80:83], v[170:173], v[194:197], v[80:83]
	v_mfma_f32_16x16x32_bf16 v[68:71], v[162:165], v[202:205], v[68:71]
	v_mfma_f32_16x16x32_bf16 v[64:67], v[170:173], v[202:205], v[64:67]
	v_mfma_f32_16x16x32_bf16 v[116:119], v[166:169], v[182:185], v[116:119]
	v_mfma_f32_16x16x32_bf16 v[112:115], v[174:177], v[182:185], v[112:115]
	v_mfma_f32_16x16x32_bf16 v[100:103], v[166:169], v[190:193], v[100:103]
	v_mfma_f32_16x16x32_bf16 v[96:99], v[174:177], v[190:193], v[96:99]
	v_mfma_f32_16x16x32_bf16 v[84:87], v[166:169], v[198:201], v[84:87]
	v_mfma_f32_16x16x32_bf16 v[80:83], v[174:177], v[198:201], v[80:83]
	v_mfma_f32_16x16x32_bf16 v[68:71], v[166:169], v[208:211], v[68:71]
	v_mfma_f32_16x16x32_bf16 v[64:67], v[174:177], v[208:211], v[64:67]
	s_barrier
	s_add_i32 s28, s59, s43
	s_mov_b32 m0, s28
	s_nop 0
	global_load_lds_dwordx4 v212, s[34:35]
	s_add_i32 m0, s28, 0x2000
	s_add_u32 s28, s34, 0x40080
	s_addc_u32 s29, s35, 0
	s_add_i32 s34, s60, s43
	global_load_lds_dwordx4 v213, s[98:99]
	s_mov_b32 m0, s34
	s_nop 0
	global_load_lds_dwordx4 v128, s[28:29]
	s_add_i32 m0, s34, 0x2000
	s_nop 0
	global_load_lds_dwordx4 v130, s[28:29]
	s_cmp_lg_u32 s58, 12
	s_cbranch_scc1 .Lbal_last_20
	s_mov_b32 m0, s49
	s_nop 0
	global_load_lds_dwordx4 v212, s[36:37]
	s_mov_b32 m0, s50
	s_nop 0
	global_load_lds_dwordx4 v213, s[36:37]
.Lbal_last_20:
	ds_read_b128 v[178:181], v149 offset:49152
	ds_read_b128 v[182:185], v149 offset:50176
	ds_read_b128 v[186:189], v149 offset:51200
	ds_read_b128 v[190:193], v149 offset:52224
	ds_read_b128 v[194:197], v149 offset:53248
	ds_read_b128 v[198:201], v149 offset:54272
	ds_read_b128 v[202:205], v149 offset:55296
	ds_read_b128 v[208:211], v149 offset:56320
	s_waitcnt vmcnt(6)
	s_waitcnt lgkmcnt(0)
	s_barrier
	v_mfma_f32_16x16x32_bf16 v[60:63], v[140:143], v[178:181], v[60:63]
	v_mfma_f32_16x16x32_bf16 v[56:59], v[154:157], v[178:181], v[56:59]
	v_mfma_f32_16x16x32_bf16 v[44:47], v[140:143], v[186:189], v[44:47]
	v_mfma_f32_16x16x32_bf16 v[40:43], v[154:157], v[186:189], v[40:43]
	s_add_i32 s58, s58, 2
	s_add_u32 s56, s56, 0x100
	s_addc_u32 s57, s57, 0
	s_cmp_gt_u32 s58, 13
	s_mov_b64 s[28:29], s[30:31]
	v_mfma_f32_16x16x32_bf16 v[28:31], v[140:143], v[194:197], v[28:31]
	v_mfma_f32_16x16x32_bf16 v[24:27], v[154:157], v[194:197], v[24:27]
	v_mfma_f32_16x16x32_bf16 v[12:15], v[140:143], v[202:205], v[12:15]
	v_mfma_f32_16x16x32_bf16 v[8:11], v[154:157], v[202:205], v[8:11]
	v_mfma_f32_16x16x32_bf16 v[60:63], v[150:153], v[182:185], v[60:63]
	v_mfma_f32_16x16x32_bf16 v[56:59], v[158:161], v[182:185], v[56:59]
	v_mfma_f32_16x16x32_bf16 v[44:47], v[150:153], v[190:193], v[44:47]
	v_mfma_f32_16x16x32_bf16 v[40:43], v[158:161], v[190:193], v[40:43]
	v_mfma_f32_16x16x32_bf16 v[28:31], v[150:153], v[198:201], v[28:31]
	v_mfma_f32_16x16x32_bf16 v[24:27], v[158:161], v[198:201], v[24:27]
	v_mfma_f32_16x16x32_bf16 v[12:15], v[150:153], v[208:211], v[12:15]
	v_mfma_f32_16x16x32_bf16 v[8:11], v[158:161], v[208:211], v[8:11]
	v_mfma_f32_16x16x32_bf16 v[52:55], v[162:165], v[178:181], v[52:55]
	v_mfma_f32_16x16x32_bf16 v[48:51], v[170:173], v[178:181], v[48:51]
	v_mfma_f32_16x16x32_bf16 v[36:39], v[162:165], v[186:189], v[36:39]
	v_mfma_f32_16x16x32_bf16 v[32:35], v[170:173], v[186:189], v[32:35]
	v_mfma_f32_16x16x32_bf16 v[20:23], v[162:165], v[194:197], v[20:23]
	v_mfma_f32_16x16x32_bf16 v[16:19], v[170:173], v[194:197], v[16:19]
	v_mfma_f32_16x16x32_bf16 v[4:7], v[162:165], v[202:205], v[4:7]
	v_mfma_f32_16x16x32_bf16 v[0:3], v[170:173], v[202:205], v[0:3]
	v_mfma_f32_16x16x32_bf16 v[52:55], v[166:169], v[182:185], v[52:55]
	v_mfma_f32_16x16x32_bf16 v[48:51], v[174:177], v[182:185], v[48:51]
	v_mfma_f32_16x16x32_bf16 v[36:39], v[166:169], v[190:193], v[36:39]
	v_mfma_f32_16x16x32_bf16 v[32:35], v[174:177], v[190:193], v[32:35]
	v_mfma_f32_16x16x32_bf16 v[20:23], v[166:169], v[198:201], v[20:23]
	v_mfma_f32_16x16x32_bf16 v[16:19], v[174:177], v[198:201], v[16:19]
	v_mfma_f32_16x16x32_bf16 v[4:7], v[166:169], v[208:211], v[4:7]
	v_mfma_f32_16x16x32_bf16 v[0:3], v[174:177], v[208:211], v[0:3]
	s_barrier
	s_cbranch_scc0 .LBB0_606
	s_setprio 0
	s_and_b64 vcc, exec, s[16:17]
	s_cbranch_vccz .LBB0_609
	s_barrier

.Lbal_first_19:
	s_add_u32 s28, s26, 0xfffc0080
	s_addc_u32 s29, s27, -1
	s_cmp_eq_u32 s53, 12
	s_cselect_b32 s31, s21, s29
	s_cselect_b32 s30, s49, s28
	s_cselect_b32 s29, s19, s52
	s_cselect_b32 s28, s50, s51
	s_add_i32 m0, s39, 0xc000
	s_nop 0
	global_load_lds_dwordx4 v138, s[26:27]
	s_add_i32 m0, s39, 0xe000
	s_nop 0
	global_load_lds_dwordx4 v136, s[26:27]
	ds_read_b128 v[144:147], v151
	ds_read_b128 v[156:159], v151 offset:1024
	ds_read_b128 v[160:163], v151 offset:2048
	ds_read_b128 v[164:167], v151 offset:3072
	ds_read_b128 v[168:171], v152
	ds_read_b128 v[172:175], v152 offset:1024
	ds_read_b128 v[176:179], v152 offset:2048
	ds_read_b128 v[180:183], v152 offset:3072
	ds_read_b128 v[184:187], v153
	ds_read_b128 v[188:191], v153 offset:1024
	ds_read_b128 v[192:195], v153 offset:2048
	ds_read_b128 v[196:199], v153 offset:3072
	ds_read_b128 v[200:203], v153 offset:4096
	ds_read_b128 v[208:211], v153 offset:5120
	ds_read_b128 v[212:215], v153 offset:6144
	ds_read_b128 v[216:219], v153 offset:7168
	s_waitcnt vmcnt(8)
	s_waitcnt lgkmcnt(0)
	s_barrier
	v_mfma_f32_16x16x32_bf16 v[124:127], v[144:147], v[184:187], v[124:127]
	v_mfma_f32_16x16x32_bf16 v[120:123], v[160:163], v[184:187], v[120:123]
	v_mfma_f32_16x16x32_bf16 v[108:111], v[144:147], v[192:195], v[108:111]
	v_mfma_f32_16x16x32_bf16 v[104:107], v[160:163], v[192:195], v[104:107]
	v_mfma_f32_16x16x32_bf16 v[92:95], v[144:147], v[200:203], v[92:95]
	v_mfma_f32_16x16x32_bf16 v[88:91], v[160:163], v[200:203], v[88:91]
	v_mfma_f32_16x16x32_bf16 v[76:79], v[144:147], v[212:215], v[76:79]
	v_mfma_f32_16x16x32_bf16 v[72:75], v[160:163], v[212:215], v[72:75]
	v_mfma_f32_16x16x32_bf16 v[124:127], v[156:159], v[188:191], v[124:127]
	v_mfma_f32_16x16x32_bf16 v[120:123], v[164:167], v[188:191], v[120:123]
	v_mfma_f32_16x16x32_bf16 v[108:111], v[156:159], v[196:199], v[108:111]
	v_mfma_f32_16x16x32_bf16 v[104:107], v[164:167], v[196:199], v[104:107]
	v_mfma_f32_16x16x32_bf16 v[92:95], v[156:159], v[208:211], v[92:95]
	v_mfma_f32_16x16x32_bf16 v[88:91], v[164:167], v[208:211], v[88:91]
	v_mfma_f32_16x16x32_bf16 v[76:79], v[156:159], v[216:219], v[76:79]
	v_mfma_f32_16x16x32_bf16 v[72:75], v[164:167], v[216:219], v[72:75]
	v_mfma_f32_16x16x32_bf16 v[116:119], v[168:171], v[184:187], v[116:119]
	v_mfma_f32_16x16x32_bf16 v[112:115], v[176:179], v[184:187], v[112:115]
	v_mfma_f32_16x16x32_bf16 v[100:103], v[168:171], v[192:195], v[100:103]
	v_mfma_f32_16x16x32_bf16 v[96:99], v[176:179], v[192:195], v[96:99]
	v_mfma_f32_16x16x32_bf16 v[84:87], v[168:171], v[200:203], v[84:87]
	v_mfma_f32_16x16x32_bf16 v[80:83], v[176:179], v[200:203], v[80:83]
	v_mfma_f32_16x16x32_bf16 v[68:71], v[168:171], v[212:215], v[68:71]
	v_mfma_f32_16x16x32_bf16 v[64:67], v[176:179], v[212:215], v[64:67]
	v_mfma_f32_16x16x32_bf16 v[116:119], v[172:175], v[188:191], v[116:119]
	v_mfma_f32_16x16x32_bf16 v[112:115], v[180:183], v[188:191], v[112:115]
	v_mfma_f32_16x16x32_bf16 v[100:103], v[172:175], v[196:199], v[100:103]
	v_mfma_f32_16x16x32_bf16 v[96:99], v[180:183], v[196:199], v[96:99]
	v_mfma_f32_16x16x32_bf16 v[84:87], v[172:175], v[208:211], v[84:87]
	v_mfma_f32_16x16x32_bf16 v[80:83], v[180:183], v[208:211], v[80:83]
	v_mfma_f32_16x16x32_bf16 v[68:71], v[172:175], v[216:219], v[68:71]
	v_mfma_f32_16x16x32_bf16 v[64:67], v[180:183], v[216:219], v[64:67]
	s_barrier
	s_add_i32 s54, s46, s38
	s_mov_b32 m0, s54
	s_nop 0
	global_load_lds_dwordx4 v130, s[28:29]
	s_add_i32 m0, s54, 0x2000
	s_add_u32 s54, s28, 0x40000
	s_mov_b64 s[98:99], s[28:29]
	s_addc_u32 s55, s29, 0
	s_add_i32 s56, s47, s38
	global_load_lds_dwordx4 v134, s[28:29]
	s_mov_b32 m0, s56
	s_mov_b64 s[100:101], s[30:31]
	global_load_lds_dwordx4 v130, s[54:55]
	s_add_i32 m0, s56, 0x2000
	s_nop 0
	global_load_lds_dwordx4 v134, s[54:55]
	ds_read_b128 v[184:187], v153 offset:16384
	ds_read_b128 v[188:191], v153 offset:17408
	ds_read_b128 v[192:195], v153 offset:18432
	ds_read_b128 v[196:199], v153 offset:19456
	ds_read_b128 v[200:203], v153 offset:20480
	ds_read_b128 v[208:211], v153 offset:21504
	ds_read_b128 v[212:215], v153 offset:22528
	ds_read_b128 v[216:219], v153 offset:23552
	s_waitcnt vmcnt(6)
	s_waitcnt lgkmcnt(0)
	s_barrier
	v_mfma_f32_16x16x32_bf16 v[60:63], v[144:147], v[184:187], v[60:63]
	v_mfma_f32_16x16x32_bf16 v[56:59], v[160:163], v[184:187], v[56:59]
	v_mfma_f32_16x16x32_bf16 v[44:47], v[144:147], v[192:195], v[44:47]
	v_mfma_f32_16x16x32_bf16 v[40:43], v[160:163], v[192:195], v[40:43]
	v_mfma_f32_16x16x32_bf16 v[28:31], v[144:147], v[200:203], v[28:31]
	v_mfma_f32_16x16x32_bf16 v[24:27], v[160:163], v[200:203], v[24:27]
	v_mfma_f32_16x16x32_bf16 v[12:15], v[144:147], v[212:215], v[12:15]
	v_mfma_f32_16x16x32_bf16 v[8:11], v[160:163], v[212:215], v[8:11]
	v_mfma_f32_16x16x32_bf16 v[60:63], v[156:159], v[188:191], v[60:63]
	v_mfma_f32_16x16x32_bf16 v[56:59], v[164:167], v[188:191], v[56:59]
	v_mfma_f32_16x16x32_bf16 v[44:47], v[156:159], v[196:199], v[44:47]
	v_mfma_f32_16x16x32_bf16 v[40:43], v[164:167], v[196:199], v[40:43]
	v_mfma_f32_16x16x32_bf16 v[28:31], v[156:159], v[208:211], v[28:31]
	v_mfma_f32_16x16x32_bf16 v[24:27], v[164:167], v[208:211], v[24:27]
	v_mfma_f32_16x16x32_bf16 v[12:15], v[156:159], v[216:219], v[12:15]
	v_mfma_f32_16x16x32_bf16 v[8:11], v[164:167], v[216:219], v[8:11]
	v_mfma_f32_16x16x32_bf16 v[52:55], v[168:171], v[184:187], v[52:55]
	v_mfma_f32_16x16x32_bf16 v[48:51], v[176:179], v[184:187], v[48:51]
	v_mfma_f32_16x16x32_bf16 v[36:39], v[168:171], v[192:195], v[36:39]
	v_mfma_f32_16x16x32_bf16 v[32:35], v[176:179], v[192:195], v[32:35]
	v_mfma_f32_16x16x32_bf16 v[20:23], v[168:171], v[200:203], v[20:23]
	v_mfma_f32_16x16x32_bf16 v[16:19], v[176:179], v[200:203], v[16:19]
	v_mfma_f32_16x16x32_bf16 v[4:7], v[168:171], v[212:215], v[4:7]
	v_mfma_f32_16x16x32_bf16 v[0:3], v[176:179], v[212:215], v[0:3]
	v_mfma_f32_16x16x32_bf16 v[52:55], v[172:175], v[188:191], v[52:55]
	v_mfma_f32_16x16x32_bf16 v[48:51], v[180:183], v[188:191], v[48:51]
	v_mfma_f32_16x16x32_bf16 v[36:39], v[172:175], v[196:199], v[36:39]
	v_mfma_f32_16x16x32_bf16 v[32:35], v[180:183], v[196:199], v[32:35]
	v_mfma_f32_16x16x32_bf16 v[20:23], v[172:175], v[208:211], v[20:23]
	v_mfma_f32_16x16x32_bf16 v[16:19], v[180:183], v[208:211], v[16:19]
	v_mfma_f32_16x16x32_bf16 v[4:7], v[172:175], v[216:219], v[4:7]
	v_mfma_f32_16x16x32_bf16 v[0:3], v[180:183], v[216:219], v[0:3]
	s_barrier
	s_mov_b32 m0, s39
	s_nop 0
	global_load_lds_dwordx4 v128, s[30:31]
	s_mov_b32 m0, s40
	s_nop 0
	global_load_lds_dwordx4 v132, s[30:31]
	s_add_i32 s54, 0, 0x18000
	s_add_i32 s55, 0, 0x1c000
	s_add_u32 s30, s30, 0x40000
	s_addc_u32 s31, s31, 0
	s_mov_b32 m0, s41
	s_nop 0
	global_load_lds_dwordx4 v128, s[30:31]
	s_mov_b32 m0, s42
	s_nop 0
	global_load_lds_dwordx4 v132, s[30:31]
	v_add_u32_e32 v155, s54, v149
	ds_read_b128 v[144:147], v155
	ds_read_b128 v[156:159], v155 offset:1024
	ds_read_b128 v[160:163], v155 offset:2048
	ds_read_b128 v[164:167], v155 offset:3072
	v_add_u32_e32 v155, s55, v149
	ds_read_b128 v[168:171], v155
	ds_read_b128 v[172:175], v155 offset:1024
	ds_read_b128 v[176:179], v155 offset:2048
	ds_read_b128 v[180:183], v155 offset:3072
	ds_read_b128 v[184:187], v153 offset:32768
	ds_read_b128 v[188:191], v153 offset:33792
	ds_read_b128 v[192:195], v153 offset:34816
	ds_read_b128 v[196:199], v153 offset:35840
	ds_read_b128 v[200:203], v153 offset:36864
	ds_read_b128 v[208:211], v153 offset:37888
	ds_read_b128 v[212:215], v153 offset:38912
	ds_read_b128 v[216:219], v153 offset:39936
	s_waitcnt vmcnt(8)
	s_waitcnt lgkmcnt(0)
	s_barrier
	v_mfma_f32_16x16x32_bf16 v[124:127], v[144:147], v[184:187], v[124:127]
	v_mfma_f32_16x16x32_bf16 v[120:123], v[160:163], v[184:187], v[120:123]
	v_mfma_f32_16x16x32_bf16 v[108:111], v[144:147], v[192:195], v[108:111]
	v_mfma_f32_16x16x32_bf16 v[104:107], v[160:163], v[192:195], v[104:107]
	v_mfma_f32_16x16x32_bf16 v[92:95], v[144:147], v[200:203], v[92:95]
	v_mfma_f32_16x16x32_bf16 v[88:91], v[160:163], v[200:203], v[88:91]
	v_mfma_f32_16x16x32_bf16 v[76:79], v[144:147], v[212:215], v[76:79]
	v_mfma_f32_16x16x32_bf16 v[72:75], v[160:163], v[212:215], v[72:75]
	v_mfma_f32_16x16x32_bf16 v[124:127], v[156:159], v[188:191], v[124:127]
	v_mfma_f32_16x16x32_bf16 v[120:123], v[164:167], v[188:191], v[120:123]
	v_mfma_f32_16x16x32_bf16 v[108:111], v[156:159], v[196:199], v[108:111]
	v_mfma_f32_16x16x32_bf16 v[104:107], v[164:167], v[196:199], v[104:107]
	v_mfma_f32_16x16x32_bf16 v[92:95], v[156:159], v[208:211], v[92:95]
	v_mfma_f32_16x16x32_bf16 v[88:91], v[164:167], v[208:211], v[88:91]
	v_mfma_f32_16x16x32_bf16 v[76:79], v[156:159], v[216:219], v[76:79]
	v_mfma_f32_16x16x32_bf16 v[72:75], v[164:167], v[216:219], v[72:75]
	v_mfma_f32_16x16x32_bf16 v[116:119], v[168:171], v[184:187], v[116:119]
	v_mfma_f32_16x16x32_bf16 v[112:115], v[176:179], v[184:187], v[112:115]
	v_mfma_f32_16x16x32_bf16 v[100:103], v[168:171], v[192:195], v[100:103]
	v_mfma_f32_16x16x32_bf16 v[96:99], v[176:179], v[192:195], v[96:99]
	v_mfma_f32_16x16x32_bf16 v[84:87], v[168:171], v[200:203], v[84:87]
	v_mfma_f32_16x16x32_bf16 v[80:83], v[176:179], v[200:203], v[80:83]
	v_mfma_f32_16x16x32_bf16 v[68:71], v[168:171], v[212:215], v[68:71]
	v_mfma_f32_16x16x32_bf16 v[64:67], v[176:179], v[212:215], v[64:67]
	v_mfma_f32_16x16x32_bf16 v[116:119], v[172:175], v[188:191], v[116:119]
	v_mfma_f32_16x16x32_bf16 v[112:115], v[180:183], v[188:191], v[112:115]
	v_mfma_f32_16x16x32_bf16 v[100:103], v[172:175], v[196:199], v[100:103]
	v_mfma_f32_16x16x32_bf16 v[96:99], v[180:183], v[196:199], v[96:99]
	v_mfma_f32_16x16x32_bf16 v[84:87], v[172:175], v[208:211], v[84:87]
	v_mfma_f32_16x16x32_bf16 v[80:83], v[180:183], v[208:211], v[80:83]
	v_mfma_f32_16x16x32_bf16 v[68:71], v[172:175], v[216:219], v[68:71]
	v_mfma_f32_16x16x32_bf16 v[64:67], v[180:183], v[216:219], v[64:67]
	s_barrier
	s_add_i32 s30, s54, s38
	s_mov_b32 m0, s30
	s_nop 0
	global_load_lds_dwordx4 v205, s[28:29]
	s_add_i32 m0, s30, 0x2000
	s_add_u32 s28, s28, 0x40080
	s_addc_u32 s29, s29, 0
	s_add_i32 s30, s55, s38
	global_load_lds_dwordx4 v221, s[98:99]
	s_mov_b32 m0, s30
	s_nop 0
	global_load_lds_dwordx4 v130, s[28:29]
	s_add_i32 m0, s30, 0x2000
	s_nop 0
	global_load_lds_dwordx4 v134, s[28:29]
	s_cmp_lg_u32 s53, 12
	s_cbranch_scc1 .Lbal_last_19
	s_mov_b32 m0, s44
	s_nop 0
	global_load_lds_dwordx4 v204, s[100:101]
	s_mov_b32 m0, s45
	s_nop 0
	global_load_lds_dwordx4 v220, s[100:101]
.Lbal_last_19:
	ds_read_b128 v[184:187], v153 offset:49152
	ds_read_b128 v[188:191], v153 offset:50176
	ds_read_b128 v[192:195], v153 offset:51200
	ds_read_b128 v[196:199], v153 offset:52224
	ds_read_b128 v[200:203], v153 offset:53248
	ds_read_b128 v[208:211], v153 offset:54272
	ds_read_b128 v[212:215], v153 offset:55296
	ds_read_b128 v[216:219], v153 offset:56320
	s_waitcnt vmcnt(6)
	s_waitcnt lgkmcnt(0)
	s_barrier
	v_mfma_f32_16x16x32_bf16 v[60:63], v[144:147], v[184:187], v[60:63]
	v_mfma_f32_16x16x32_bf16 v[56:59], v[160:163], v[184:187], v[56:59]
	v_mfma_f32_16x16x32_bf16 v[44:47], v[144:147], v[192:195], v[44:47]
	v_mfma_f32_16x16x32_bf16 v[40:43], v[160:163], v[192:195], v[40:43]
	s_add_i32 s53, s53, 2
	s_add_u32 s51, s51, 0x100
	s_addc_u32 s52, s52, 0
	s_add_u32 s26, s26, 0x100
	s_addc_u32 s27, s27, 0
	s_cmp_gt_u32 s53, 13
	v_mfma_f32_16x16x32_bf16 v[28:31], v[144:147], v[200:203], v[28:31]
	v_mfma_f32_16x16x32_bf16 v[24:27], v[160:163], v[200:203], v[24:27]
	v_mfma_f32_16x16x32_bf16 v[12:15], v[144:147], v[212:215], v[12:15]
	v_mfma_f32_16x16x32_bf16 v[8:11], v[160:163], v[212:215], v[8:11]
	v_mfma_f32_16x16x32_bf16 v[60:63], v[156:159], v[188:191], v[60:63]
	v_mfma_f32_16x16x32_bf16 v[56:59], v[164:167], v[188:191], v[56:59]
	v_mfma_f32_16x16x32_bf16 v[44:47], v[156:159], v[196:199], v[44:47]
	v_mfma_f32_16x16x32_bf16 v[40:43], v[164:167], v[196:199], v[40:43]
	v_mfma_f32_16x16x32_bf16 v[28:31], v[156:159], v[208:211], v[28:31]
	v_mfma_f32_16x16x32_bf16 v[24:27], v[164:167], v[208:211], v[24:27]
	v_mfma_f32_16x16x32_bf16 v[12:15], v[156:159], v[216:219], v[12:15]
	v_mfma_f32_16x16x32_bf16 v[8:11], v[164:167], v[216:219], v[8:11]
	v_mfma_f32_16x16x32_bf16 v[52:55], v[168:171], v[184:187], v[52:55]
	v_mfma_f32_16x16x32_bf16 v[48:51], v[176:179], v[184:187], v[48:51]
	v_mfma_f32_16x16x32_bf16 v[36:39], v[168:171], v[192:195], v[36:39]
	v_mfma_f32_16x16x32_bf16 v[32:35], v[176:179], v[192:195], v[32:35]
	v_mfma_f32_16x16x32_bf16 v[20:23], v[168:171], v[200:203], v[20:23]
	v_mfma_f32_16x16x32_bf16 v[16:19], v[176:179], v[200:203], v[16:19]
	v_mfma_f32_16x16x32_bf16 v[4:7], v[168:171], v[212:215], v[4:7]
	v_mfma_f32_16x16x32_bf16 v[0:3], v[176:179], v[212:215], v[0:3]
	v_mfma_f32_16x16x32_bf16 v[52:55], v[172:175], v[188:191], v[52:55]
	v_mfma_f32_16x16x32_bf16 v[48:51], v[180:183], v[188:191], v[48:51]
	v_mfma_f32_16x16x32_bf16 v[36:39], v[172:175], v[196:199], v[36:39]
	v_mfma_f32_16x16x32_bf16 v[32:35], v[180:183], v[196:199], v[32:35]
	v_mfma_f32_16x16x32_bf16 v[20:23], v[172:175], v[208:211], v[20:23]
	v_mfma_f32_16x16x32_bf16 v[16:19], v[180:183], v[208:211], v[16:19]
	v_mfma_f32_16x16x32_bf16 v[4:7], v[172:175], v[216:219], v[4:7]
	v_mfma_f32_16x16x32_bf16 v[0:3], v[180:183], v[216:219], v[0:3]
	s_barrier
	s_cbranch_scc0 .LBB0_699
	s_setprio 0
	s_and_b64 vcc, exec, s[16:17]
	s_cbranch_vccz .LBB0_702
	s_barrier

.Lbal_first_18:
	s_add_u32 s30, s28, 0x100
	s_addc_u32 s31, s29, 0
	s_cmp_eq_u32 s58, 60
	s_cselect_b32 s37, s21, s31
	s_cselect_b32 s36, s27, s30
	s_cselect_b32 s35, s19, s57
	s_cselect_b32 s34, s55, s56
	s_add_i32 m0, s44, 0xc000
	s_nop 0
	global_load_lds_dwordx4 v134, s[28:29]
	s_add_i32 m0, s44, 0xe000
	s_nop 0
	global_load_lds_dwordx4 v132, s[28:29]
	ds_read_b128 v[140:143], v147
	ds_read_b128 v[150:153], v147 offset:1024
	ds_read_b128 v[154:157], v147 offset:2048
	ds_read_b128 v[158:161], v147 offset:3072
	ds_read_b128 v[162:165], v148
	ds_read_b128 v[166:169], v148 offset:1024
	ds_read_b128 v[170:173], v148 offset:2048
	ds_read_b128 v[174:177], v148 offset:3072
	ds_read_b128 v[178:181], v149
	ds_read_b128 v[182:185], v149 offset:1024
	ds_read_b128 v[186:189], v149 offset:2048
	ds_read_b128 v[190:193], v149 offset:3072
	ds_read_b128 v[194:197], v149 offset:4096
	ds_read_b128 v[198:201], v149 offset:5120
	ds_read_b128 v[202:205], v149 offset:6144
	ds_read_b128 v[208:211], v149 offset:7168
	s_waitcnt vmcnt(8)
	s_waitcnt lgkmcnt(0)
	s_barrier
	v_mfma_f32_16x16x32_bf16 v[124:127], v[140:143], v[178:181], v[124:127]
	v_mfma_f32_16x16x32_bf16 v[120:123], v[154:157], v[178:181], v[120:123]
	v_mfma_f32_16x16x32_bf16 v[108:111], v[140:143], v[186:189], v[108:111]
	v_mfma_f32_16x16x32_bf16 v[104:107], v[154:157], v[186:189], v[104:107]
	v_mfma_f32_16x16x32_bf16 v[92:95], v[140:143], v[194:197], v[92:95]
	v_mfma_f32_16x16x32_bf16 v[88:91], v[154:157], v[194:197], v[88:91]
	v_mfma_f32_16x16x32_bf16 v[76:79], v[140:143], v[202:205], v[76:79]
	v_mfma_f32_16x16x32_bf16 v[72:75], v[154:157], v[202:205], v[72:75]
	v_mfma_f32_16x16x32_bf16 v[124:127], v[150:153], v[182:185], v[124:127]
	v_mfma_f32_16x16x32_bf16 v[120:123], v[158:161], v[182:185], v[120:123]
	v_mfma_f32_16x16x32_bf16 v[108:111], v[150:153], v[190:193], v[108:111]
	v_mfma_f32_16x16x32_bf16 v[104:107], v[158:161], v[190:193], v[104:107]
	v_mfma_f32_16x16x32_bf16 v[92:95], v[150:153], v[198:201], v[92:95]
	v_mfma_f32_16x16x32_bf16 v[88:91], v[158:161], v[198:201], v[88:91]
	v_mfma_f32_16x16x32_bf16 v[76:79], v[150:153], v[208:211], v[76:79]
	v_mfma_f32_16x16x32_bf16 v[72:75], v[158:161], v[208:211], v[72:75]
	v_mfma_f32_16x16x32_bf16 v[116:119], v[162:165], v[178:181], v[116:119]
	v_mfma_f32_16x16x32_bf16 v[112:115], v[170:173], v[178:181], v[112:115]
	v_mfma_f32_16x16x32_bf16 v[100:103], v[162:165], v[186:189], v[100:103]
	v_mfma_f32_16x16x32_bf16 v[96:99], v[170:173], v[186:189], v[96:99]
	v_mfma_f32_16x16x32_bf16 v[84:87], v[162:165], v[194:197], v[84:87]
	v_mfma_f32_16x16x32_bf16 v[80:83], v[170:173], v[194:197], v[80:83]
	v_mfma_f32_16x16x32_bf16 v[68:71], v[162:165], v[202:205], v[68:71]
	v_mfma_f32_16x16x32_bf16 v[64:67], v[170:173], v[202:205], v[64:67]
	v_mfma_f32_16x16x32_bf16 v[116:119], v[166:169], v[182:185], v[116:119]
	v_mfma_f32_16x16x32_bf16 v[112:115], v[174:177], v[182:185], v[112:115]
	v_mfma_f32_16x16x32_bf16 v[100:103], v[166:169], v[190:193], v[100:103]
	v_mfma_f32_16x16x32_bf16 v[96:99], v[174:177], v[190:193], v[96:99]
	v_mfma_f32_16x16x32_bf16 v[84:87], v[166:169], v[198:201], v[84:87]
	v_mfma_f32_16x16x32_bf16 v[80:83], v[174:177], v[198:201], v[80:83]
	v_mfma_f32_16x16x32_bf16 v[68:71], v[166:169], v[208:211], v[68:71]
	v_mfma_f32_16x16x32_bf16 v[64:67], v[174:177], v[208:211], v[64:67]
	s_barrier
	s_add_i32 s28, s52, s43
	s_mov_b32 m0, s28
	s_nop 0
	global_load_lds_dwordx4 v128, s[34:35]
	s_add_i32 m0, s28, 0x2000
	s_add_u32 s28, s34, 0x100000
	s_mov_b64 s[98:99], s[34:35]
	s_addc_u32 s29, s35, 0
	s_add_i32 s59, s53, s43
	global_load_lds_dwordx4 v130, s[34:35]
	s_mov_b32 m0, s59
	s_nop 0
	global_load_lds_dwordx4 v128, s[28:29]
	s_add_i32 m0, s59, 0x2000
	s_nop 0
	global_load_lds_dwordx4 v130, s[28:29]
	ds_read_b128 v[178:181], v149 offset:16384
	ds_read_b128 v[182:185], v149 offset:17408
	ds_read_b128 v[186:189], v149 offset:18432
	ds_read_b128 v[190:193], v149 offset:19456
	ds_read_b128 v[194:197], v149 offset:20480
	ds_read_b128 v[198:201], v149 offset:21504
	ds_read_b128 v[202:205], v149 offset:22528
	ds_read_b128 v[208:211], v149 offset:23552
	s_waitcnt vmcnt(6)
	s_waitcnt lgkmcnt(0)
	s_barrier
	v_mfma_f32_16x16x32_bf16 v[60:63], v[140:143], v[178:181], v[60:63]
	v_mfma_f32_16x16x32_bf16 v[56:59], v[154:157], v[178:181], v[56:59]
	v_mfma_f32_16x16x32_bf16 v[44:47], v[140:143], v[186:189], v[44:47]
	v_mfma_f32_16x16x32_bf16 v[40:43], v[154:157], v[186:189], v[40:43]
	v_mfma_f32_16x16x32_bf16 v[28:31], v[140:143], v[194:197], v[28:31]
	v_mfma_f32_16x16x32_bf16 v[24:27], v[154:157], v[194:197], v[24:27]
	v_mfma_f32_16x16x32_bf16 v[12:15], v[140:143], v[202:205], v[12:15]
	v_mfma_f32_16x16x32_bf16 v[8:11], v[154:157], v[202:205], v[8:11]
	v_mfma_f32_16x16x32_bf16 v[60:63], v[150:153], v[182:185], v[60:63]
	v_mfma_f32_16x16x32_bf16 v[56:59], v[158:161], v[182:185], v[56:59]
	v_mfma_f32_16x16x32_bf16 v[44:47], v[150:153], v[190:193], v[44:47]
	v_mfma_f32_16x16x32_bf16 v[40:43], v[158:161], v[190:193], v[40:43]
	v_mfma_f32_16x16x32_bf16 v[28:31], v[150:153], v[198:201], v[28:31]
	v_mfma_f32_16x16x32_bf16 v[24:27], v[158:161], v[198:201], v[24:27]
	v_mfma_f32_16x16x32_bf16 v[12:15], v[150:153], v[208:211], v[12:15]
	v_mfma_f32_16x16x32_bf16 v[8:11], v[158:161], v[208:211], v[8:11]
	v_mfma_f32_16x16x32_bf16 v[52:55], v[162:165], v[178:181], v[52:55]
	v_mfma_f32_16x16x32_bf16 v[48:51], v[170:173], v[178:181], v[48:51]
	v_mfma_f32_16x16x32_bf16 v[36:39], v[162:165], v[186:189], v[36:39]
	v_mfma_f32_16x16x32_bf16 v[32:35], v[170:173], v[186:189], v[32:35]
	v_mfma_f32_16x16x32_bf16 v[20:23], v[162:165], v[194:197], v[20:23]
	v_mfma_f32_16x16x32_bf16 v[16:19], v[170:173], v[194:197], v[16:19]
	v_mfma_f32_16x16x32_bf16 v[4:7], v[162:165], v[202:205], v[4:7]
	v_mfma_f32_16x16x32_bf16 v[0:3], v[170:173], v[202:205], v[0:3]
	v_mfma_f32_16x16x32_bf16 v[52:55], v[166:169], v[182:185], v[52:55]
	v_mfma_f32_16x16x32_bf16 v[48:51], v[174:177], v[182:185], v[48:51]
	v_mfma_f32_16x16x32_bf16 v[36:39], v[166:169], v[190:193], v[36:39]
	v_mfma_f32_16x16x32_bf16 v[32:35], v[174:177], v[190:193], v[32:35]
	v_mfma_f32_16x16x32_bf16 v[20:23], v[166:169], v[198:201], v[20:23]
	v_mfma_f32_16x16x32_bf16 v[16:19], v[174:177], v[198:201], v[16:19]
	v_mfma_f32_16x16x32_bf16 v[4:7], v[166:169], v[208:211], v[4:7]
	v_mfma_f32_16x16x32_bf16 v[0:3], v[174:177], v[208:211], v[0:3]
	s_barrier
	s_mov_b32 m0, s44
	s_nop 0
	global_load_lds_dwordx4 v128, s[36:37]
	s_mov_b32 m0, s45
	s_nop 0
	global_load_lds_dwordx4 v130, s[36:37]
	s_add_i32 s59, 0, 0x18000
	s_add_i32 s60, 0, 0x1c000
	s_add_u32 s28, s36, 0x100000
	s_addc_u32 s29, s37, 0
	s_mov_b32 m0, s46
	s_nop 0
	global_load_lds_dwordx4 v128, s[28:29]
	s_mov_b32 m0, s47
	s_nop 0
	global_load_lds_dwordx4 v130, s[28:29]
	v_add_u32_e32 v158, s59, v145
	v_add_u32_e32 v174, s60, v145
	ds_read_b128 v[140:143], v158
	ds_read_b128 v[150:153], v158 offset:1024
	ds_read_b128 v[154:157], v158 offset:2048
	ds_read_b128 v[158:161], v158 offset:3072
	ds_read_b128 v[162:165], v174
	ds_read_b128 v[166:169], v174 offset:1024
	ds_read_b128 v[170:173], v174 offset:2048
	ds_read_b128 v[174:177], v174 offset:3072
	ds_read_b128 v[178:181], v149 offset:32768
	ds_read_b128 v[182:185], v149 offset:33792
	ds_read_b128 v[186:189], v149 offset:34816
	ds_read_b128 v[190:193], v149 offset:35840
	ds_read_b128 v[194:197], v149 offset:36864
	ds_read_b128 v[198:201], v149 offset:37888
	ds_read_b128 v[202:205], v149 offset:38912
	ds_read_b128 v[208:211], v149 offset:39936
	s_waitcnt vmcnt(8)
	s_waitcnt lgkmcnt(0)
	s_barrier
	v_mfma_f32_16x16x32_bf16 v[124:127], v[140:143], v[178:181], v[124:127]
	v_mfma_f32_16x16x32_bf16 v[120:123], v[154:157], v[178:181], v[120:123]
	v_mfma_f32_16x16x32_bf16 v[108:111], v[140:143], v[186:189], v[108:111]
	v_mfma_f32_16x16x32_bf16 v[104:107], v[154:157], v[186:189], v[104:107]
	v_mfma_f32_16x16x32_bf16 v[92:95], v[140:143], v[194:197], v[92:95]
	v_mfma_f32_16x16x32_bf16 v[88:91], v[154:157], v[194:197], v[88:91]
	v_mfma_f32_16x16x32_bf16 v[76:79], v[140:143], v[202:205], v[76:79]
	v_mfma_f32_16x16x32_bf16 v[72:75], v[154:157], v[202:205], v[72:75]
	v_mfma_f32_16x16x32_bf16 v[124:127], v[150:153], v[182:185], v[124:127]
	v_mfma_f32_16x16x32_bf16 v[120:123], v[158:161], v[182:185], v[120:123]
	v_mfma_f32_16x16x32_bf16 v[108:111], v[150:153], v[190:193], v[108:111]
	v_mfma_f32_16x16x32_bf16 v[104:107], v[158:161], v[190:193], v[104:107]
	v_mfma_f32_16x16x32_bf16 v[92:95], v[150:153], v[198:201], v[92:95]
	v_mfma_f32_16x16x32_bf16 v[88:91], v[158:161], v[198:201], v[88:91]
	v_mfma_f32_16x16x32_bf16 v[76:79], v[150:153], v[208:211], v[76:79]
	v_mfma_f32_16x16x32_bf16 v[72:75], v[158:161], v[208:211], v[72:75]
	v_mfma_f32_16x16x32_bf16 v[116:119], v[162:165], v[178:181], v[116:119]
	v_mfma_f32_16x16x32_bf16 v[112:115], v[170:173], v[178:181], v[112:115]
	v_mfma_f32_16x16x32_bf16 v[100:103], v[162:165], v[186:189], v[100:103]
	v_mfma_f32_16x16x32_bf16 v[96:99], v[170:173], v[186:189], v[96:99]
	v_mfma_f32_16x16x32_bf16 v[84:87], v[162:165], v[194:197], v[84:87]
	v_mfma_f32_16x16x32_bf16 v[80:83], v[170:173], v[194:197], v[80:83]
	v_mfma_f32_16x16x32_bf16 v[68:71], v[162:165], v[202:205], v[68:71]
	v_mfma_f32_16x16x32_bf16 v[64:67], v[170:173], v[202:205], v[64:67]
	v_mfma_f32_16x16x32_bf16 v[116:119], v[166:169], v[182:185], v[116:119]
	v_mfma_f32_16x16x32_bf16 v[112:115], v[174:177], v[182:185], v[112:115]
	v_mfma_f32_16x16x32_bf16 v[100:103], v[166:169], v[190:193], v[100:103]
	v_mfma_f32_16x16x32_bf16 v[96:99], v[174:177], v[190:193], v[96:99]
	v_mfma_f32_16x16x32_bf16 v[84:87], v[166:169], v[198:201], v[84:87]
	v_mfma_f32_16x16x32_bf16 v[80:83], v[174:177], v[198:201], v[80:83]
	v_mfma_f32_16x16x32_bf16 v[68:71], v[166:169], v[208:211], v[68:71]
	v_mfma_f32_16x16x32_bf16 v[64:67], v[174:177], v[208:211], v[64:67]
	s_barrier
	s_add_i32 s28, s59, s43
	s_mov_b32 m0, s28
	s_nop 0
	global_load_lds_dwordx4 v212, s[34:35]
	s_add_i32 m0, s28, 0x2000
	s_add_u32 s28, s34, 0x100080
	s_addc_u32 s29, s35, 0
	s_add_i32 s34, s60, s43
	global_load_lds_dwordx4 v213, s[98:99]
	s_mov_b32 m0, s34
	s_nop 0
	global_load_lds_dwordx4 v128, s[28:29]
	s_add_i32 m0, s34, 0x2000
	s_nop 0
	global_load_lds_dwordx4 v130, s[28:29]
	s_cmp_lg_u32 s58, 60
	s_cbranch_scc1 .Lbal_last_18
	s_mov_b32 m0, s49
	s_nop 0
	global_load_lds_dwordx4 v212, s[36:37]
	s_mov_b32 m0, s50
	s_nop 0
	global_load_lds_dwordx4 v213, s[36:37]
.Lbal_last_18:
	ds_read_b128 v[178:181], v149 offset:49152
	ds_read_b128 v[182:185], v149 offset:50176
	ds_read_b128 v[186:189], v149 offset:51200
	ds_read_b128 v[190:193], v149 offset:52224
	ds_read_b128 v[194:197], v149 offset:53248
	ds_read_b128 v[198:201], v149 offset:54272
	ds_read_b128 v[202:205], v149 offset:55296
	ds_read_b128 v[208:211], v149 offset:56320
	s_waitcnt vmcnt(6)
	s_waitcnt lgkmcnt(0)
	s_barrier
	v_mfma_f32_16x16x32_bf16 v[60:63], v[140:143], v[178:181], v[60:63]
	v_mfma_f32_16x16x32_bf16 v[56:59], v[154:157], v[178:181], v[56:59]
	v_mfma_f32_16x16x32_bf16 v[44:47], v[140:143], v[186:189], v[44:47]
	v_mfma_f32_16x16x32_bf16 v[40:43], v[154:157], v[186:189], v[40:43]
	s_add_i32 s58, s58, 2
	s_add_u32 s56, s56, 0x100
	s_addc_u32 s57, s57, 0
	s_cmp_gt_u32 s58, 61
	s_mov_b64 s[28:29], s[30:31]
	v_mfma_f32_16x16x32_bf16 v[28:31], v[140:143], v[194:197], v[28:31]
	v_mfma_f32_16x16x32_bf16 v[24:27], v[154:157], v[194:197], v[24:27]
	v_mfma_f32_16x16x32_bf16 v[12:15], v[140:143], v[202:205], v[12:15]
	v_mfma_f32_16x16x32_bf16 v[8:11], v[154:157], v[202:205], v[8:11]
	v_mfma_f32_16x16x32_bf16 v[60:63], v[150:153], v[182:185], v[60:63]
	v_mfma_f32_16x16x32_bf16 v[56:59], v[158:161], v[182:185], v[56:59]
	v_mfma_f32_16x16x32_bf16 v[44:47], v[150:153], v[190:193], v[44:47]
	v_mfma_f32_16x16x32_bf16 v[40:43], v[158:161], v[190:193], v[40:43]
	v_mfma_f32_16x16x32_bf16 v[28:31], v[150:153], v[198:201], v[28:31]
	v_mfma_f32_16x16x32_bf16 v[24:27], v[158:161], v[198:201], v[24:27]
	v_mfma_f32_16x16x32_bf16 v[12:15], v[150:153], v[208:211], v[12:15]
	v_mfma_f32_16x16x32_bf16 v[8:11], v[158:161], v[208:211], v[8:11]
	v_mfma_f32_16x16x32_bf16 v[52:55], v[162:165], v[178:181], v[52:55]
	v_mfma_f32_16x16x32_bf16 v[48:51], v[170:173], v[178:181], v[48:51]
	v_mfma_f32_16x16x32_bf16 v[36:39], v[162:165], v[186:189], v[36:39]
	v_mfma_f32_16x16x32_bf16 v[32:35], v[170:173], v[186:189], v[32:35]
	v_mfma_f32_16x16x32_bf16 v[20:23], v[162:165], v[194:197], v[20:23]
	v_mfma_f32_16x16x32_bf16 v[16:19], v[170:173], v[194:197], v[16:19]
	v_mfma_f32_16x16x32_bf16 v[4:7], v[162:165], v[202:205], v[4:7]
	v_mfma_f32_16x16x32_bf16 v[0:3], v[170:173], v[202:205], v[0:3]
	v_mfma_f32_16x16x32_bf16 v[52:55], v[166:169], v[182:185], v[52:55]
	v_mfma_f32_16x16x32_bf16 v[48:51], v[174:177], v[182:185], v[48:51]
	v_mfma_f32_16x16x32_bf16 v[36:39], v[166:169], v[190:193], v[36:39]
	v_mfma_f32_16x16x32_bf16 v[32:35], v[174:177], v[190:193], v[32:35]
	v_mfma_f32_16x16x32_bf16 v[20:23], v[166:169], v[198:201], v[20:23]
	v_mfma_f32_16x16x32_bf16 v[16:19], v[174:177], v[198:201], v[16:19]
	v_mfma_f32_16x16x32_bf16 v[4:7], v[166:169], v[208:211], v[4:7]
	v_mfma_f32_16x16x32_bf16 v[0:3], v[174:177], v[208:211], v[0:3]
	s_barrier
	s_cbranch_scc0 .LBB0_778
	s_setprio 0
	s_and_b64 vcc, exec, s[16:17]
	s_cbranch_vccz .LBB0_781
	s_barrier

.LBB0_817:
	ds_read_b128 v[0:3], v139
	ds_read_b128 v[4:7], v139 offset:1024
	ds_read_b128 v[8:11], v139 offset:2048
	ds_read_b128 v[12:15], v139 offset:3072
	ds_read_b128 v[16:19], v140
	ds_read_b128 v[20:23], v140 offset:1024
	ds_read_b128 v[24:27], v140 offset:2048
	ds_read_b128 v[28:31], v140 offset:3072
	s_ashr_i32 s29, s28, 31
	s_lshl_b64 s[30:31], s[28:29], 17
	s_add_u32 s30, s46, s30
	s_addc_u32 s31, s47, s31
	s_and_b64 s[34:35], s[4:5], exec
	s_cselect_b32 s45, s31, s39
	s_cselect_b32 s44, s30, s38
	s_ashr_i32 s27, s26, 31
	s_lshl_b64 s[34:35], s[26:27], 17
	s_add_u32 s34, s48, s34
	s_addc_u32 s35, s49, s35
	s_and_b64 s[42:43], s[4:5], exec
	s_cselect_b32 s43, s35, s41
	s_cselect_b32 s42, s34, s40
	s_add_u32 s64, s38, 0x10080
	s_addc_u32 s65, s39, 0
	s_add_i32 s67, s37, 0xc000
	v_lshl_add_u64 v[64:65], s[64:65], 0, v[128:129]
	s_mov_b32 m0, s67
	s_add_i32 s27, s37, 0xe000
	ds_read_b128 v[32:35], v141
	ds_read_b128 v[36:39], v141 offset:1024
	ds_read_b128 v[40:43], v141 offset:2048
	ds_read_b128 v[44:47], v141 offset:3072
	ds_read_b128 v[48:51], v141 offset:4096
	ds_read_b128 v[52:55], v141 offset:5120
	ds_read_b128 v[56:59], v141 offset:6144
	ds_read_b128 v[60:63], v141 offset:7168
	global_load_lds_dwordx4 v[64:65], off
	v_lshl_add_u64 v[64:65], s[64:65], 0, v[130:131]
	s_mov_b32 m0, s27
	s_nop 0
	global_load_lds_dwordx4 v[64:65], off
	s_waitcnt vmcnt(8)
	s_waitcnt lgkmcnt(0)
	s_barrier
	v_mfma_f32_16x16x32_bf16 v[64:67], v[0:3], v[32:35], 0
	v_mfma_f32_16x16x32_bf16 v[68:71], v[8:11], v[32:35], 0
	v_mfma_f32_16x16x32_bf16 v[72:75], v[0:3], v[40:43], 0
	v_mfma_f32_16x16x32_bf16 v[76:79], v[8:11], v[40:43], 0
	v_mfma_f32_16x16x32_bf16 v[80:83], v[0:3], v[48:51], 0
	v_mfma_f32_16x16x32_bf16 v[84:87], v[8:11], v[48:51], 0
	v_mfma_f32_16x16x32_bf16 v[88:91], v[0:3], v[56:59], 0
	v_mfma_f32_16x16x32_bf16 v[92:95], v[8:11], v[56:59], 0
	v_mfma_f32_16x16x32_bf16 v[64:67], v[4:7], v[36:39], v[64:67]
	v_mfma_f32_16x16x32_bf16 v[68:71], v[12:15], v[36:39], v[68:71]
	v_mfma_f32_16x16x32_bf16 v[72:75], v[4:7], v[44:47], v[72:75]
	v_mfma_f32_16x16x32_bf16 v[76:79], v[12:15], v[44:47], v[76:79]
	v_mfma_f32_16x16x32_bf16 v[80:83], v[4:7], v[52:55], v[80:83]
	v_mfma_f32_16x16x32_bf16 v[84:87], v[12:15], v[52:55], v[84:87]
	v_mfma_f32_16x16x32_bf16 v[88:91], v[4:7], v[60:63], v[88:91]
	v_mfma_f32_16x16x32_bf16 v[92:95], v[12:15], v[60:63], v[92:95]
	v_mfma_f32_16x16x32_bf16 v[96:99], v[16:19], v[32:35], 0
	v_mfma_f32_16x16x32_bf16 v[32:35], v[24:27], v[32:35], 0
	v_mfma_f32_16x16x32_bf16 v[96:99], v[20:23], v[36:39], v[96:99]
	v_mfma_f32_16x16x32_bf16 v[32:35], v[28:31], v[36:39], v[32:35]
	v_mfma_f32_16x16x32_bf16 v[36:39], v[16:19], v[40:43], 0
	v_mfma_f32_16x16x32_bf16 v[40:43], v[24:27], v[40:43], 0
	v_mfma_f32_16x16x32_bf16 v[36:39], v[20:23], v[44:47], v[36:39]
	v_mfma_f32_16x16x32_bf16 v[40:43], v[28:31], v[44:47], v[40:43]
	v_mfma_f32_16x16x32_bf16 v[44:47], v[16:19], v[48:51], 0
	v_mfma_f32_16x16x32_bf16 v[48:51], v[24:27], v[48:51], 0
	v_mfma_f32_16x16x32_bf16 v[44:47], v[20:23], v[52:55], v[44:47]
	v_mfma_f32_16x16x32_bf16 v[48:51], v[28:31], v[52:55], v[48:51]
	v_mfma_f32_16x16x32_bf16 v[52:55], v[16:19], v[56:59], 0
	v_mfma_f32_16x16x32_bf16 v[56:59], v[24:27], v[56:59], 0
	v_mfma_f32_16x16x32_bf16 v[52:55], v[20:23], v[60:63], v[52:55]
	v_mfma_f32_16x16x32_bf16 v[56:59], v[28:31], v[60:63], v[56:59]
	s_barrier
	s_add_i32 s65, s56, s50
	v_lshl_add_u64 v[208:209], s[40:41], 0, v[128:129]
	s_add_i32 s29, s65, 0x2000
	v_lshl_add_u64 v[142:143], v[208:209], 0, s[14:15]
	s_mov_b32 m0, s65
	v_lshl_add_u64 v[210:211], s[40:41], 0, v[130:131]
	s_add_u32 s68, s40, 0x10100
	ds_read_b128 v[60:63], v141 offset:16384
	ds_read_b128 v[100:103], v141 offset:17408
	ds_read_b128 v[104:107], v141 offset:18432
	ds_read_b128 v[108:111], v141 offset:19456
	ds_read_b128 v[112:115], v141 offset:20480
	ds_read_b128 v[116:119], v141 offset:21504
	ds_read_b128 v[120:123], v141 offset:22528
	ds_read_b128 v[124:127], v141 offset:23552
	global_load_lds_dwordx4 v[142:143], off
	v_lshl_add_u64 v[142:143], v[210:211], 0, s[14:15]
	s_mov_b32 m0, s29
	s_addc_u32 s69, s41, 0
	s_add_i32 s63, s57, s50
	global_load_lds_dwordx4 v[142:143], off
	v_lshl_add_u64 v[142:143], s[68:69], 0, v[128:129]
	s_mov_b32 m0, s63
	s_add_i32 s64, s63, 0x2000
	global_load_lds_dwordx4 v[142:143], off
	v_lshl_add_u64 v[142:143], s[68:69], 0, v[130:131]
	s_mov_b32 m0, s64
	v_lshl_add_u64 v[212:213], s[38:39], 0, v[128:129]
	global_load_lds_dwordx4 v[142:143], off
	v_lshl_add_u64 v[142:143], v[212:213], 0, s[14:15]
	s_mov_b32 m0, s37
	v_lshl_add_u64 v[214:215], s[38:39], 0, v[130:131]
	global_load_lds_dwordx4 v[142:143], off
	v_lshl_add_u64 v[142:143], v[214:215], 0, s[14:15]
	s_mov_b32 m0, s51
	s_nop 0
	global_load_lds_dwordx4 v[142:143], off
	s_waitcnt vmcnt(8)
	s_waitcnt lgkmcnt(0)
	s_barrier
	v_mfma_f32_16x16x32_bf16 v[142:145], v[0:3], v[60:63], 0
	v_mfma_f32_16x16x32_bf16 v[150:153], v[0:3], v[104:107], 0
	v_mfma_f32_16x16x32_bf16 v[158:161], v[0:3], v[112:115], 0
	v_mfma_f32_16x16x32_bf16 v[0:3], v[0:3], v[120:123], 0
	v_mfma_f32_16x16x32_bf16 v[142:145], v[4:7], v[100:103], v[142:145]
	v_mfma_f32_16x16x32_bf16 v[150:153], v[4:7], v[108:111], v[150:153]
	v_mfma_f32_16x16x32_bf16 v[158:161], v[4:7], v[116:119], v[158:161]
	v_mfma_f32_16x16x32_bf16 v[0:3], v[4:7], v[124:127], v[0:3]
	v_mfma_f32_16x16x32_bf16 v[4:7], v[8:11], v[120:123], 0
	v_mfma_f32_16x16x32_bf16 v[146:149], v[8:11], v[60:63], 0
	v_mfma_f32_16x16x32_bf16 v[154:157], v[8:11], v[104:107], 0
	v_mfma_f32_16x16x32_bf16 v[162:165], v[8:11], v[112:115], 0
	v_mfma_f32_16x16x32_bf16 v[4:7], v[12:15], v[124:127], v[4:7]
	v_mfma_f32_16x16x32_bf16 v[146:149], v[12:15], v[100:103], v[146:149]
	v_mfma_f32_16x16x32_bf16 v[154:157], v[12:15], v[108:111], v[154:157]
	v_mfma_f32_16x16x32_bf16 v[162:165], v[12:15], v[116:119], v[162:165]
	v_mfma_f32_16x16x32_bf16 v[8:11], v[16:19], v[60:63], 0
	v_mfma_f32_16x16x32_bf16 v[12:15], v[24:27], v[60:63], 0
	v_mfma_f32_16x16x32_bf16 v[8:11], v[20:23], v[100:103], v[8:11]
	v_mfma_f32_16x16x32_bf16 v[12:15], v[28:31], v[100:103], v[12:15]
	v_mfma_f32_16x16x32_bf16 v[60:63], v[16:19], v[104:107], 0
	v_mfma_f32_16x16x32_bf16 v[100:103], v[24:27], v[104:107], 0
	v_mfma_f32_16x16x32_bf16 v[104:107], v[16:19], v[112:115], 0
	v_mfma_f32_16x16x32_bf16 v[16:19], v[16:19], v[120:123], 0
	v_mfma_f32_16x16x32_bf16 v[60:63], v[20:23], v[108:111], v[60:63]
	v_mfma_f32_16x16x32_bf16 v[100:103], v[28:31], v[108:111], v[100:103]
	v_mfma_f32_16x16x32_bf16 v[104:107], v[20:23], v[116:119], v[104:107]
	v_mfma_f32_16x16x32_bf16 v[108:111], v[24:27], v[112:115], 0
	v_mfma_f32_16x16x32_bf16 v[16:19], v[20:23], v[124:127], v[16:19]
	v_mfma_f32_16x16x32_bf16 v[20:23], v[24:27], v[120:123], 0
	v_mfma_f32_16x16x32_bf16 v[108:111], v[28:31], v[116:119], v[108:111]
	v_mfma_f32_16x16x32_bf16 v[20:23], v[28:31], v[124:127], v[20:23]
	s_barrier
	s_add_i32 s66, 0, 0x18000
	s_add_i32 s72, 0, 0x1c000
	v_add_u32_e32 v207, s66, v137
	v_add_u32_e32 v228, s72, v137
	ds_read_b128 v[24:27], v207
	ds_read_b128 v[28:31], v207 offset:1024
	ds_read_b128 v[112:115], v207 offset:2048
	ds_read_b128 v[116:119], v207 offset:3072
	ds_read_b128 v[120:123], v228
	ds_read_b128 v[124:127], v228 offset:1024
	ds_read_b128 v[166:169], v228 offset:2048
	ds_read_b128 v[170:173], v228 offset:3072
	s_add_u32 s68, s38, 0x10100
	s_addc_u32 s69, s39, 0
	s_mov_b32 m0, s52
	v_lshl_add_u64 v[216:217], s[68:69], 0, v[128:129]
	ds_read_b128 v[174:177], v141 offset:32768
	ds_read_b128 v[178:181], v141 offset:33792
	ds_read_b128 v[182:185], v141 offset:34816
	ds_read_b128 v[186:189], v141 offset:35840
	ds_read_b128 v[190:193], v141 offset:36864
	ds_read_b128 v[194:197], v141 offset:37888
	ds_read_b128 v[198:201], v141 offset:38912
	ds_read_b128 v[202:205], v141 offset:39936
	global_load_lds_dwordx4 v[216:217], off
	v_lshl_add_u64 v[216:217], s[68:69], 0, v[130:131]
	s_mov_b32 m0, s53
	s_nop 0
	global_load_lds_dwordx4 v[216:217], off
	s_waitcnt vmcnt(8)
	s_waitcnt lgkmcnt(0)
	s_barrier
	v_mfma_f32_16x16x32_bf16 v[64:67], v[24:27], v[174:177], v[64:67]
	v_mfma_f32_16x16x32_bf16 v[68:71], v[112:115], v[174:177], v[68:71]
	v_mfma_f32_16x16x32_bf16 v[72:75], v[24:27], v[182:185], v[72:75]
	v_mfma_f32_16x16x32_bf16 v[76:79], v[112:115], v[182:185], v[76:79]
	v_mfma_f32_16x16x32_bf16 v[80:83], v[24:27], v[190:193], v[80:83]
	v_mfma_f32_16x16x32_bf16 v[84:87], v[112:115], v[190:193], v[84:87]
	v_mfma_f32_16x16x32_bf16 v[88:91], v[24:27], v[198:201], v[88:91]
	v_mfma_f32_16x16x32_bf16 v[92:95], v[112:115], v[198:201], v[92:95]
	v_mfma_f32_16x16x32_bf16 v[64:67], v[28:31], v[178:181], v[64:67]
	v_mfma_f32_16x16x32_bf16 v[68:71], v[116:119], v[178:181], v[68:71]
	v_mfma_f32_16x16x32_bf16 v[72:75], v[28:31], v[186:189], v[72:75]
	v_mfma_f32_16x16x32_bf16 v[76:79], v[116:119], v[186:189], v[76:79]
	v_mfma_f32_16x16x32_bf16 v[80:83], v[28:31], v[194:197], v[80:83]
	v_mfma_f32_16x16x32_bf16 v[84:87], v[116:119], v[194:197], v[84:87]
	v_mfma_f32_16x16x32_bf16 v[88:91], v[28:31], v[202:205], v[88:91]
	v_mfma_f32_16x16x32_bf16 v[92:95], v[116:119], v[202:205], v[92:95]
	v_mfma_f32_16x16x32_bf16 v[96:99], v[120:123], v[174:177], v[96:99]
	v_mfma_f32_16x16x32_bf16 v[32:35], v[166:169], v[174:177], v[32:35]
	v_mfma_f32_16x16x32_bf16 v[36:39], v[120:123], v[182:185], v[36:39]
	v_mfma_f32_16x16x32_bf16 v[40:43], v[166:169], v[182:185], v[40:43]
	v_mfma_f32_16x16x32_bf16 v[44:47], v[120:123], v[190:193], v[44:47]
	v_mfma_f32_16x16x32_bf16 v[48:51], v[166:169], v[190:193], v[48:51]
	v_mfma_f32_16x16x32_bf16 v[52:55], v[120:123], v[198:201], v[52:55]
	v_mfma_f32_16x16x32_bf16 v[56:59], v[166:169], v[198:201], v[56:59]
	v_mfma_f32_16x16x32_bf16 v[96:99], v[124:127], v[178:181], v[96:99]
	v_mfma_f32_16x16x32_bf16 v[32:35], v[170:173], v[178:181], v[32:35]
	v_mfma_f32_16x16x32_bf16 v[36:39], v[124:127], v[186:189], v[36:39]
	v_mfma_f32_16x16x32_bf16 v[40:43], v[170:173], v[186:189], v[40:43]
	v_mfma_f32_16x16x32_bf16 v[44:47], v[124:127], v[194:197], v[44:47]
	v_mfma_f32_16x16x32_bf16 v[48:51], v[170:173], v[194:197], v[48:51]
	v_mfma_f32_16x16x32_bf16 v[52:55], v[124:127], v[202:205], v[52:55]
	v_mfma_f32_16x16x32_bf16 v[56:59], v[170:173], v[202:205], v[56:59]
	s_barrier
	s_add_i32 s68, s66, s50
	s_add_i32 s66, s68, 0x2000
	v_lshl_add_u64 v[208:209], v[208:209], 0, s[16:17]
	s_mov_b32 m0, s68
	s_add_u32 s70, s40, 0x10180
	ds_read_b128 v[174:177], v141 offset:49152
	ds_read_b128 v[178:181], v141 offset:50176
	ds_read_b128 v[182:185], v141 offset:51200
	ds_read_b128 v[186:189], v141 offset:52224
	ds_read_b128 v[190:193], v141 offset:53248
	ds_read_b128 v[194:197], v141 offset:54272
	ds_read_b128 v[198:201], v141 offset:55296
	ds_read_b128 v[202:205], v141 offset:56320
	global_load_lds_dwordx4 v[208:209], off
	v_lshl_add_u64 v[208:209], v[210:211], 0, s[16:17]
	s_mov_b32 m0, s66
	s_addc_u32 s71, s41, 0
	s_add_i32 s40, s72, s50
	global_load_lds_dwordx4 v[208:209], off
	v_lshl_add_u64 v[208:209], s[70:71], 0, v[128:129]
	s_mov_b32 m0, s40
	s_add_i32 s41, s40, 0x2000
	global_load_lds_dwordx4 v[208:209], off
	v_lshl_add_u64 v[208:209], s[70:71], 0, v[130:131]
	s_mov_b32 m0, s41
	s_nop 0
	global_load_lds_dwordx4 v[208:209], off
	v_lshl_add_u64 v[208:209], v[212:213], 0, s[16:17]
	s_mov_b32 m0, s54
	s_nop 0
	global_load_lds_dwordx4 v[208:209], off
	v_lshl_add_u64 v[208:209], v[214:215], 0, s[16:17]
	s_mov_b32 m0, s55
	s_nop 0
	global_load_lds_dwordx4 v[208:209], off
	s_waitcnt vmcnt(8)
	s_waitcnt lgkmcnt(0)
	s_barrier
	v_mfma_f32_16x16x32_bf16 v[0:3], v[24:27], v[198:201], v[0:3]
	v_mfma_f32_16x16x32_bf16 v[4:7], v[112:115], v[198:201], v[4:7]
	v_mfma_f32_16x16x32_bf16 v[142:145], v[24:27], v[174:177], v[142:145]
	v_mfma_f32_16x16x32_bf16 v[146:149], v[112:115], v[174:177], v[146:149]
	v_mfma_f32_16x16x32_bf16 v[150:153], v[24:27], v[182:185], v[150:153]
	v_mfma_f32_16x16x32_bf16 v[154:157], v[112:115], v[182:185], v[154:157]
	v_mfma_f32_16x16x32_bf16 v[158:161], v[24:27], v[190:193], v[158:161]
	v_mfma_f32_16x16x32_bf16 v[162:165], v[112:115], v[190:193], v[162:165]
	v_mfma_f32_16x16x32_bf16 v[0:3], v[28:31], v[202:205], v[0:3]
	v_mfma_f32_16x16x32_bf16 v[4:7], v[116:119], v[202:205], v[4:7]
	v_mfma_f32_16x16x32_bf16 v[142:145], v[28:31], v[178:181], v[142:145]
	v_mfma_f32_16x16x32_bf16 v[146:149], v[116:119], v[178:181], v[146:149]
	v_mfma_f32_16x16x32_bf16 v[150:153], v[28:31], v[186:189], v[150:153]
	v_mfma_f32_16x16x32_bf16 v[154:157], v[116:119], v[186:189], v[154:157]
	v_mfma_f32_16x16x32_bf16 v[158:161], v[28:31], v[194:197], v[158:161]
	v_mfma_f32_16x16x32_bf16 v[162:165], v[116:119], v[194:197], v[162:165]
	v_mfma_f32_16x16x32_bf16 v[8:11], v[120:123], v[174:177], v[8:11]
	v_mfma_f32_16x16x32_bf16 v[12:15], v[166:169], v[174:177], v[12:15]
	v_mfma_f32_16x16x32_bf16 v[24:27], v[120:123], v[182:185], v[60:63]
	v_mfma_f32_16x16x32_bf16 v[28:31], v[166:169], v[182:185], v[100:103]
	v_mfma_f32_16x16x32_bf16 v[60:63], v[120:123], v[190:193], v[104:107]
	v_mfma_f32_16x16x32_bf16 v[100:103], v[166:169], v[190:193], v[108:111]
	v_mfma_f32_16x16x32_bf16 v[16:19], v[120:123], v[198:201], v[16:19]
	v_mfma_f32_16x16x32_bf16 v[20:23], v[166:169], v[198:201], v[20:23]
	v_mfma_f32_16x16x32_bf16 v[8:11], v[124:127], v[178:181], v[8:11]
	v_mfma_f32_16x16x32_bf16 v[12:15], v[170:173], v[178:181], v[12:15]
	v_mfma_f32_16x16x32_bf16 v[24:27], v[124:127], v[186:189], v[24:27]
	v_mfma_f32_16x16x32_bf16 v[28:31], v[170:173], v[186:189], v[28:31]
	v_mfma_f32_16x16x32_bf16 v[60:63], v[124:127], v[194:197], v[60:63]
	v_mfma_f32_16x16x32_bf16 v[100:103], v[170:173], v[194:197], v[100:103]
	v_mfma_f32_16x16x32_bf16 v[16:19], v[124:127], v[202:205], v[16:19]
	v_mfma_f32_16x16x32_bf16 v[20:23], v[170:173], v[202:205], v[20:23]
	s_barrier
	ds_read_b128 v[104:107], v139
	ds_read_b128 v[108:111], v139 offset:1024
	ds_read_b128 v[112:115], v139 offset:2048
	ds_read_b128 v[116:119], v139 offset:3072
	ds_read_b128 v[120:123], v140
	ds_read_b128 v[124:127], v140 offset:1024
	ds_read_b128 v[166:169], v140 offset:2048
	ds_read_b128 v[170:173], v140 offset:3072
	s_add_u32 s38, s38, 0x10180
	s_addc_u32 s39, s39, 0
	s_mov_b32 m0, s67
	v_lshl_add_u64 v[208:209], s[38:39], 0, v[128:129]
	ds_read_b128 v[174:177], v141
	ds_read_b128 v[178:181], v141 offset:1024
	ds_read_b128 v[182:185], v141 offset:2048
	ds_read_b128 v[186:189], v141 offset:3072
	ds_read_b128 v[190:193], v141 offset:4096
	ds_read_b128 v[194:197], v141 offset:5120
	ds_read_b128 v[198:201], v141 offset:6144
	ds_read_b128 v[202:205], v141 offset:7168
	global_load_lds_dwordx4 v[208:209], off
	v_lshl_add_u64 v[208:209], s[38:39], 0, v[130:131]
	s_mov_b32 m0, s27
	s_nop 0
	global_load_lds_dwordx4 v[208:209], off
	s_waitcnt vmcnt(8)
	s_waitcnt lgkmcnt(0)
	s_barrier
	v_mfma_f32_16x16x32_bf16 v[64:67], v[104:107], v[174:177], v[64:67]
	v_mfma_f32_16x16x32_bf16 v[68:71], v[112:115], v[174:177], v[68:71]
	v_mfma_f32_16x16x32_bf16 v[72:75], v[104:107], v[182:185], v[72:75]
	v_mfma_f32_16x16x32_bf16 v[76:79], v[112:115], v[182:185], v[76:79]
	v_mfma_f32_16x16x32_bf16 v[80:83], v[104:107], v[190:193], v[80:83]
	v_mfma_f32_16x16x32_bf16 v[84:87], v[112:115], v[190:193], v[84:87]
	v_mfma_f32_16x16x32_bf16 v[88:91], v[104:107], v[198:201], v[88:91]
	v_mfma_f32_16x16x32_bf16 v[64:67], v[108:111], v[178:181], v[64:67]
	v_mfma_f32_16x16x32_bf16 v[68:71], v[116:119], v[178:181], v[68:71]
	v_mfma_f32_16x16x32_bf16 v[72:75], v[108:111], v[186:189], v[72:75]
	v_mfma_f32_16x16x32_bf16 v[76:79], v[116:119], v[186:189], v[76:79]
	v_mfma_f32_16x16x32_bf16 v[80:83], v[108:111], v[194:197], v[80:83]
	v_mfma_f32_16x16x32_bf16 v[84:87], v[116:119], v[194:197], v[84:87]
	v_mfma_f32_16x16x32_bf16 v[88:91], v[108:111], v[202:205], v[88:91]
	v_mfma_f32_16x16x32_bf16 v[92:95], v[112:115], v[198:201], v[92:95]
	v_mfma_f32_16x16x32_bf16 v[208:211], v[116:119], v[202:205], v[92:95]
	v_mfma_f32_16x16x32_bf16 v[48:51], v[166:169], v[190:193], v[48:51]
	v_mfma_f32_16x16x32_bf16 v[92:95], v[120:123], v[174:177], v[96:99]
	v_mfma_f32_16x16x32_bf16 v[32:35], v[166:169], v[174:177], v[32:35]
	v_mfma_f32_16x16x32_bf16 v[36:39], v[120:123], v[182:185], v[36:39]
	v_mfma_f32_16x16x32_bf16 v[40:43], v[166:169], v[182:185], v[40:43]
	v_mfma_f32_16x16x32_bf16 v[44:47], v[120:123], v[190:193], v[44:47]
	v_mfma_f32_16x16x32_bf16 v[174:177], v[170:173], v[194:197], v[48:51]
	v_mfma_f32_16x16x32_bf16 v[48:51], v[120:123], v[198:201], v[52:55]
	v_mfma_f32_16x16x32_bf16 v[32:35], v[170:173], v[178:181], v[32:35]
	v_mfma_f32_16x16x32_bf16 v[36:39], v[124:127], v[186:189], v[36:39]
	v_mfma_f32_16x16x32_bf16 v[40:43], v[170:173], v[186:189], v[40:43]
	v_mfma_f32_16x16x32_bf16 v[44:47], v[124:127], v[194:197], v[44:47]
	v_mfma_f32_16x16x32_bf16 v[52:55], v[124:127], v[202:205], v[48:51]
	v_mfma_f32_16x16x32_bf16 v[48:51], v[166:169], v[198:201], v[56:59]
	v_mfma_f32_16x16x32_bf16 v[212:215], v[124:127], v[178:181], v[92:95]
	v_mfma_f32_16x16x32_bf16 v[178:181], v[170:173], v[202:205], v[48:51]
	s_barrier
	s_mov_b32 m0, s65
	v_lshl_add_u64 v[248:249], s[42:43], 0, v[128:129]
	s_add_u32 s38, s42, 0x10000
	s_nop 0
	ds_read_b128 v[48:51], v141 offset:16384
	ds_read_b128 v[56:59], v141 offset:17408
	ds_read_b128 v[92:95], v141 offset:18432
	ds_read_b128 v[96:99], v141 offset:19456
	ds_read_b128 v[182:185], v141 offset:20480
	ds_read_b128 v[186:189], v141 offset:21504
	ds_read_b128 v[190:193], v141 offset:22528
	ds_read_b128 v[194:197], v141 offset:23552
	global_load_lds_dwordx4 v[248:249], off
	v_lshl_add_u64 v[250:251], s[42:43], 0, v[130:131]
	s_mov_b32 m0, s29
	s_addc_u32 s39, s43, 0
	global_load_lds_dwordx4 v[250:251], off
	v_lshl_add_u64 v[198:199], s[38:39], 0, v[128:129]
	s_mov_b32 m0, s63
	v_lshl_add_u64 v[252:253], s[44:45], 0, v[128:129]
	global_load_lds_dwordx4 v[198:199], off
	v_lshl_add_u64 v[198:199], s[38:39], 0, v[130:131]
	s_mov_b32 m0, s64
	v_lshl_add_u64 v[132:133], s[44:45], 0, v[130:131]
	global_load_lds_dwordx4 v[198:199], off
	s_mov_b32 m0, s37
	s_nop 0
	global_load_lds_dwordx4 v[252:253], off
	s_mov_b32 m0, s51
	s_nop 0
	global_load_lds_dwordx4 v[132:133], off
	s_waitcnt vmcnt(8)
	s_waitcnt lgkmcnt(0)
	s_barrier
	v_mfma_f32_16x16x32_bf16 v[0:3], v[104:107], v[190:193], v[0:3]
	v_mfma_f32_16x16x32_bf16 v[4:7], v[112:115], v[190:193], v[4:7]
	v_mfma_f32_16x16x32_bf16 v[142:145], v[104:107], v[48:51], v[142:145]
	v_mfma_f32_16x16x32_bf16 v[146:149], v[112:115], v[48:51], v[146:149]
	v_mfma_f32_16x16x32_bf16 v[150:153], v[104:107], v[92:95], v[150:153]
	v_mfma_f32_16x16x32_bf16 v[154:157], v[112:115], v[92:95], v[154:157]
	v_mfma_f32_16x16x32_bf16 v[158:161], v[104:107], v[182:185], v[158:161]
	v_mfma_f32_16x16x32_bf16 v[162:165], v[112:115], v[182:185], v[162:165]
	v_mfma_f32_16x16x32_bf16 v[0:3], v[108:111], v[194:197], v[0:3]
	v_mfma_f32_16x16x32_bf16 v[4:7], v[116:119], v[194:197], v[4:7]
	v_mfma_f32_16x16x32_bf16 v[142:145], v[108:111], v[56:59], v[142:145]
	v_mfma_f32_16x16x32_bf16 v[146:149], v[116:119], v[56:59], v[146:149]
	v_mfma_f32_16x16x32_bf16 v[150:153], v[108:111], v[96:99], v[150:153]
	v_mfma_f32_16x16x32_bf16 v[154:157], v[116:119], v[96:99], v[154:157]
	v_mfma_f32_16x16x32_bf16 v[158:161], v[108:111], v[186:189], v[158:161]
	v_mfma_f32_16x16x32_bf16 v[162:165], v[116:119], v[186:189], v[162:165]
	v_mfma_f32_16x16x32_bf16 v[12:15], v[166:169], v[48:51], v[12:15]
	v_mfma_f32_16x16x32_bf16 v[198:201], v[170:173], v[56:59], v[12:15]
	v_mfma_f32_16x16x32_bf16 v[12:15], v[120:123], v[92:95], v[24:27]
	v_mfma_f32_16x16x32_bf16 v[24:27], v[124:127], v[96:99], v[12:15]
	v_mfma_f32_16x16x32_bf16 v[12:15], v[166:169], v[92:95], v[28:31]
	v_mfma_f32_16x16x32_bf16 v[202:205], v[170:173], v[96:99], v[12:15]
	v_mfma_f32_16x16x32_bf16 v[12:15], v[120:123], v[182:185], v[60:63]
	v_mfma_f32_16x16x32_bf16 v[216:219], v[124:127], v[186:189], v[12:15]
	v_mfma_f32_16x16x32_bf16 v[12:15], v[166:169], v[182:185], v[100:103]
	v_mfma_f32_16x16x32_bf16 v[8:11], v[120:123], v[48:51], v[8:11]
	v_mfma_f32_16x16x32_bf16 v[182:185], v[170:173], v[186:189], v[12:15]
	v_mfma_f32_16x16x32_bf16 v[12:15], v[120:123], v[190:193], v[16:19]
	v_mfma_f32_16x16x32_bf16 v[8:11], v[124:127], v[56:59], v[8:11]
	v_mfma_f32_16x16x32_bf16 v[186:189], v[124:127], v[194:197], v[12:15]
	v_mfma_f32_16x16x32_bf16 v[12:15], v[166:169], v[190:193], v[20:23]
	v_mfma_f32_16x16x32_bf16 v[166:169], v[170:173], v[194:197], v[12:15]
	s_barrier
	s_nop 4
	ds_read_b128 v[12:15], v207
	ds_read_b128 v[20:23], v207 offset:1024
	ds_read_b128 v[170:173], v207 offset:2048
	ds_read_b128 v[190:193], v207 offset:3072
	ds_read_b128 v[194:197], v228
	ds_read_b128 v[220:223], v228 offset:1024
	ds_read_b128 v[224:227], v228 offset:2048
	ds_read_b128 v[228:231], v228 offset:3072
	s_add_u32 s38, s44, 0x10000
	s_addc_u32 s39, s45, 0
	s_mov_b32 m0, s52
	v_lshl_add_u64 v[48:49], s[38:39], 0, v[128:129]
	ds_read_b128 v[16:19], v141 offset:32768
	ds_read_b128 v[28:31], v141 offset:33792
	ds_read_b128 v[56:59], v141 offset:34816
	ds_read_b128 v[100:103], v141 offset:35840
	ds_read_b128 v[232:235], v141 offset:36864
	ds_read_b128 v[236:239], v141 offset:37888
	ds_read_b128 v[240:243], v141 offset:38912
	ds_read_b128 v[244:247], v141 offset:39936
	global_load_lds_dwordx4 v[48:49], off
	v_lshl_add_u64 v[48:49], s[38:39], 0, v[130:131]
	s_mov_b32 m0, s53
	s_nop 0
	global_load_lds_dwordx4 v[48:49], off
	s_waitcnt vmcnt(8)
	s_waitcnt lgkmcnt(0)
	s_barrier
	v_mfma_f32_16x16x32_bf16 v[48:51], v[12:15], v[16:19], v[64:67]
	v_mfma_f32_16x16x32_bf16 v[124:127], v[20:23], v[28:31], v[48:51]
	v_mfma_f32_16x16x32_bf16 v[48:51], v[170:173], v[16:19], v[68:71]
	v_mfma_f32_16x16x32_bf16 v[112:115], v[190:193], v[28:31], v[48:51]
	v_mfma_f32_16x16x32_bf16 v[48:51], v[12:15], v[56:59], v[72:75]
	v_mfma_f32_16x16x32_bf16 v[108:111], v[20:23], v[100:103], v[48:51]
	v_mfma_f32_16x16x32_bf16 v[48:51], v[170:173], v[56:59], v[76:79]
	v_mfma_f32_16x16x32_bf16 v[96:99], v[190:193], v[100:103], v[48:51]
	v_mfma_f32_16x16x32_bf16 v[48:51], v[12:15], v[232:235], v[80:83]
	v_mfma_f32_16x16x32_bf16 v[92:95], v[20:23], v[236:239], v[48:51]
	v_mfma_f32_16x16x32_bf16 v[48:51], v[170:173], v[232:235], v[84:87]
	v_mfma_f32_16x16x32_bf16 v[80:83], v[190:193], v[236:239], v[48:51]
	v_mfma_f32_16x16x32_bf16 v[48:51], v[12:15], v[240:243], v[88:91]
	v_mfma_f32_16x16x32_bf16 v[60:63], v[20:23], v[244:247], v[48:51]
	v_mfma_f32_16x16x32_bf16 v[48:51], v[170:173], v[240:243], v[208:211]
	v_mfma_f32_16x16x32_bf16 v[48:51], v[190:193], v[244:247], v[48:51]
	v_mfma_f32_16x16x32_bf16 v[64:67], v[194:197], v[16:19], v[212:215]
	v_mfma_f32_16x16x32_bf16 v[16:19], v[224:227], v[16:19], v[32:35]
	v_mfma_f32_16x16x32_bf16 v[116:119], v[228:231], v[28:31], v[16:19]
	v_mfma_f32_16x16x32_bf16 v[16:19], v[194:197], v[56:59], v[36:39]
	v_mfma_f32_16x16x32_bf16 v[104:107], v[220:223], v[100:103], v[16:19]
	v_mfma_f32_16x16x32_bf16 v[16:19], v[224:227], v[56:59], v[40:43]
	v_mfma_f32_16x16x32_bf16 v[100:103], v[228:231], v[100:103], v[16:19]
	v_mfma_f32_16x16x32_bf16 v[16:19], v[194:197], v[232:235], v[44:47]
	v_mfma_f32_16x16x32_bf16 v[88:91], v[220:223], v[236:239], v[16:19]
	v_mfma_f32_16x16x32_bf16 v[16:19], v[224:227], v[232:235], v[174:177]
	v_mfma_f32_16x16x32_bf16 v[84:87], v[228:231], v[236:239], v[16:19]
	v_mfma_f32_16x16x32_bf16 v[16:19], v[194:197], v[240:243], v[52:55]
	v_mfma_f32_16x16x32_bf16 v[56:59], v[220:223], v[244:247], v[16:19]
	v_mfma_f32_16x16x32_bf16 v[16:19], v[224:227], v[240:243], v[178:181]
	v_mfma_f32_16x16x32_bf16 v[120:123], v[220:223], v[28:31], v[64:67]
	v_mfma_f32_16x16x32_bf16 v[52:55], v[228:231], v[244:247], v[16:19]
	s_barrier
	s_mov_b32 m0, s68
	s_nop 2
	v_lshl_add_u64 v[16:17], v[248:249], 0, s[8:9]
	s_add_u32 s38, s42, 0x10080
	ds_read_b128 v[36:39], v141 offset:49152
	ds_read_b128 v[40:43], v141 offset:50176
	ds_read_b128 v[174:177], v141 offset:51200
	ds_read_b128 v[178:181], v141 offset:52224
	ds_read_b128 v[208:211], v141 offset:53248
	ds_read_b128 v[212:215], v141 offset:54272
	ds_read_b128 v[232:235], v141 offset:55296
	ds_read_b128 v[236:239], v141 offset:56320
	global_load_lds_dwordx4 v[16:17], off
	v_lshl_add_u64 v[16:17], v[250:251], 0, s[8:9]
	s_mov_b32 m0, s66
	s_addc_u32 s39, s43, 0
	global_load_lds_dwordx4 v[16:17], off
	v_lshl_add_u64 v[16:17], s[38:39], 0, v[128:129]
	s_mov_b32 m0, s40
	s_nop 0
	global_load_lds_dwordx4 v[16:17], off
	v_lshl_add_u64 v[16:17], s[38:39], 0, v[130:131]
	s_mov_b32 m0, s41
	s_nop 0
	global_load_lds_dwordx4 v[16:17], off
	v_lshl_add_u64 v[16:17], v[252:253], 0, s[8:9]
	s_mov_b32 m0, s54
	s_nop 0
	global_load_lds_dwordx4 v[16:17], off
	v_lshl_add_u64 v[16:17], v[132:133], 0, s[8:9]
	s_mov_b32 m0, s55
	s_nop 0
	global_load_lds_dwordx4 v[16:17], off
	s_waitcnt vmcnt(8)
	s_waitcnt lgkmcnt(0)
	s_barrier
	v_mfma_f32_16x16x32_bf16 v[16:19], v[12:15], v[36:39], v[142:145]
	v_mfma_f32_16x16x32_bf16 v[76:79], v[20:23], v[40:43], v[16:19]
	v_mfma_f32_16x16x32_bf16 v[16:19], v[170:173], v[36:39], v[146:149]
	v_mfma_f32_16x16x32_bf16 v[64:67], v[190:193], v[40:43], v[16:19]
	v_mfma_f32_16x16x32_bf16 v[16:19], v[12:15], v[174:177], v[150:153]
	v_mfma_f32_16x16x32_bf16 v[44:47], v[20:23], v[178:181], v[16:19]
	v_mfma_f32_16x16x32_bf16 v[16:19], v[170:173], v[174:177], v[154:157]
	v_mfma_f32_16x16x32_bf16 v[32:35], v[190:193], v[178:181], v[16:19]
	v_mfma_f32_16x16x32_bf16 v[16:19], v[12:15], v[208:211], v[158:161]
	v_mfma_f32_16x16x32_bf16 v[0:3], v[12:15], v[232:235], v[0:3]
	v_mfma_f32_16x16x32_bf16 v[28:31], v[20:23], v[212:215], v[16:19]
	v_mfma_f32_16x16x32_bf16 v[16:19], v[170:173], v[208:211], v[162:165]
	v_mfma_f32_16x16x32_bf16 v[12:15], v[20:23], v[236:239], v[0:3]
	v_mfma_f32_16x16x32_bf16 v[0:3], v[170:173], v[232:235], v[4:7]
	v_mfma_f32_16x16x32_bf16 v[16:19], v[190:193], v[212:215], v[16:19]
	v_mfma_f32_16x16x32_bf16 v[0:3], v[190:193], v[236:239], v[0:3]
	v_mfma_f32_16x16x32_bf16 v[4:7], v[194:197], v[36:39], v[8:11]
	v_mfma_f32_16x16x32_bf16 v[72:75], v[220:223], v[40:43], v[4:7]
	v_mfma_f32_16x16x32_bf16 v[4:7], v[224:227], v[36:39], v[198:201]
	v_mfma_f32_16x16x32_bf16 v[68:71], v[228:231], v[40:43], v[4:7]
	v_mfma_f32_16x16x32_bf16 v[4:7], v[194:197], v[174:177], v[24:27]
	v_mfma_f32_16x16x32_bf16 v[40:43], v[220:223], v[178:181], v[4:7]
	v_mfma_f32_16x16x32_bf16 v[4:7], v[224:227], v[174:177], v[202:205]
	v_mfma_f32_16x16x32_bf16 v[36:39], v[228:231], v[178:181], v[4:7]
	v_mfma_f32_16x16x32_bf16 v[4:7], v[194:197], v[208:211], v[216:219]
	v_mfma_f32_16x16x32_bf16 v[24:27], v[220:223], v[212:215], v[4:7]
	v_mfma_f32_16x16x32_bf16 v[4:7], v[224:227], v[208:211], v[182:185]
	v_mfma_f32_16x16x32_bf16 v[20:23], v[228:231], v[212:215], v[4:7]
	v_mfma_f32_16x16x32_bf16 v[4:7], v[194:197], v[232:235], v[186:189]
	v_mfma_f32_16x16x32_bf16 v[8:11], v[220:223], v[236:239], v[4:7]
	v_mfma_f32_16x16x32_bf16 v[4:7], v[224:227], v[232:235], v[166:169]
	v_mfma_f32_16x16x32_bf16 v[4:7], v[228:231], v[236:239], v[4:7]
	s_barrier
	s_andn2_b64 vcc, exec, s[10:11]
	s_cbranch_vccnz .LBB0_819
	s_barrier

.Lbal_first_17:
	s_add_u32 s38, s36, 0xfffc0080
	s_addc_u32 s39, s37, -1
	s_cmp_eq_u32 s61, 12
	s_cselect_b32 s41, s3, s39
	s_cselect_b32 s40, s29, s38
	s_cselect_b32 s39, s27, s60
	s_cselect_b32 s38, s58, s59
	s_add_i32 m0, s46, 0xc000
	s_nop 0
	global_load_lds_dwordx4 v134, s[36:37]
	s_add_i32 m0, s46, 0xe000
	s_nop 0
	global_load_lds_dwordx4 v132, s[36:37]
	ds_read_b128 v[140:143], v153
	ds_read_b128 v[144:147], v153 offset:1024
	ds_read_b128 v[158:161], v153 offset:2048
	ds_read_b128 v[162:165], v153 offset:3072
	ds_read_b128 v[166:169], v154
	ds_read_b128 v[170:173], v154 offset:1024
	ds_read_b128 v[174:177], v154 offset:2048
	ds_read_b128 v[178:181], v154 offset:3072
	ds_read_b128 v[182:185], v155
	ds_read_b128 v[186:189], v155 offset:1024
	ds_read_b128 v[190:193], v155 offset:2048
	ds_read_b128 v[194:197], v155 offset:3072
	ds_read_b128 v[198:201], v155 offset:4096
	ds_read_b128 v[202:205], v155 offset:5120
	ds_read_b128 v[208:211], v155 offset:6144
	ds_read_b128 v[212:215], v155 offset:7168
	s_waitcnt vmcnt(8)
	s_waitcnt lgkmcnt(0)
	s_barrier
	v_mfma_f32_16x16x32_bf16 v[124:127], v[140:143], v[182:185], v[124:127]
	v_mfma_f32_16x16x32_bf16 v[120:123], v[158:161], v[182:185], v[120:123]
	v_mfma_f32_16x16x32_bf16 v[108:111], v[140:143], v[190:193], v[108:111]
	v_mfma_f32_16x16x32_bf16 v[104:107], v[158:161], v[190:193], v[104:107]
	v_mfma_f32_16x16x32_bf16 v[92:95], v[140:143], v[198:201], v[92:95]
	v_mfma_f32_16x16x32_bf16 v[88:91], v[158:161], v[198:201], v[88:91]
	v_mfma_f32_16x16x32_bf16 v[76:79], v[140:143], v[208:211], v[76:79]
	v_mfma_f32_16x16x32_bf16 v[72:75], v[158:161], v[208:211], v[72:75]
	v_mfma_f32_16x16x32_bf16 v[124:127], v[144:147], v[186:189], v[124:127]
	v_mfma_f32_16x16x32_bf16 v[120:123], v[162:165], v[186:189], v[120:123]
	v_mfma_f32_16x16x32_bf16 v[108:111], v[144:147], v[194:197], v[108:111]
	v_mfma_f32_16x16x32_bf16 v[104:107], v[162:165], v[194:197], v[104:107]
	v_mfma_f32_16x16x32_bf16 v[92:95], v[144:147], v[202:205], v[92:95]
	v_mfma_f32_16x16x32_bf16 v[88:91], v[162:165], v[202:205], v[88:91]
	v_mfma_f32_16x16x32_bf16 v[76:79], v[144:147], v[212:215], v[76:79]
	v_mfma_f32_16x16x32_bf16 v[72:75], v[162:165], v[212:215], v[72:75]
	v_mfma_f32_16x16x32_bf16 v[116:119], v[166:169], v[182:185], v[116:119]
	v_mfma_f32_16x16x32_bf16 v[112:115], v[174:177], v[182:185], v[112:115]
	v_mfma_f32_16x16x32_bf16 v[100:103], v[166:169], v[190:193], v[100:103]
	v_mfma_f32_16x16x32_bf16 v[96:99], v[174:177], v[190:193], v[96:99]
	v_mfma_f32_16x16x32_bf16 v[84:87], v[166:169], v[198:201], v[84:87]
	v_mfma_f32_16x16x32_bf16 v[80:83], v[174:177], v[198:201], v[80:83]
	v_mfma_f32_16x16x32_bf16 v[68:71], v[166:169], v[208:211], v[68:71]
	v_mfma_f32_16x16x32_bf16 v[64:67], v[174:177], v[208:211], v[64:67]
	v_mfma_f32_16x16x32_bf16 v[116:119], v[170:173], v[186:189], v[116:119]
	v_mfma_f32_16x16x32_bf16 v[112:115], v[178:181], v[186:189], v[112:115]
	v_mfma_f32_16x16x32_bf16 v[100:103], v[170:173], v[194:197], v[100:103]
	v_mfma_f32_16x16x32_bf16 v[96:99], v[178:181], v[194:197], v[96:99]
	v_mfma_f32_16x16x32_bf16 v[84:87], v[170:173], v[202:205], v[84:87]
	v_mfma_f32_16x16x32_bf16 v[80:83], v[178:181], v[202:205], v[80:83]
	v_mfma_f32_16x16x32_bf16 v[68:71], v[170:173], v[212:215], v[68:71]
	v_mfma_f32_16x16x32_bf16 v[64:67], v[178:181], v[212:215], v[64:67]
	s_barrier
	s_add_i32 s62, s54, s45
	s_mov_b32 m0, s62
	s_nop 0
	global_load_lds_dwordx4 v128, s[38:39]
	s_add_i32 m0, s62, 0x2000
	s_add_u32 s62, s38, 0x40000
	s_mov_b64 s[98:99], s[38:39]
	s_addc_u32 s63, s39, 0
	s_add_i32 s64, s55, s45
	global_load_lds_dwordx4 v130, s[38:39]
	s_mov_b32 m0, s64
	s_mov_b64 s[100:101], s[40:41]
	global_load_lds_dwordx4 v128, s[62:63]
	s_add_i32 m0, s64, 0x2000
	s_nop 0
	global_load_lds_dwordx4 v130, s[62:63]
	ds_read_b128 v[182:185], v155 offset:16384
	ds_read_b128 v[186:189], v155 offset:17408
	ds_read_b128 v[190:193], v155 offset:18432
	ds_read_b128 v[194:197], v155 offset:19456
	ds_read_b128 v[198:201], v155 offset:20480
	ds_read_b128 v[202:205], v155 offset:21504
	ds_read_b128 v[208:211], v155 offset:22528
	ds_read_b128 v[212:215], v155 offset:23552
	s_waitcnt vmcnt(6)
	s_waitcnt lgkmcnt(0)
	s_barrier
	v_mfma_f32_16x16x32_bf16 v[60:63], v[140:143], v[182:185], v[60:63]
	v_mfma_f32_16x16x32_bf16 v[56:59], v[158:161], v[182:185], v[56:59]
	v_mfma_f32_16x16x32_bf16 v[44:47], v[140:143], v[190:193], v[44:47]
	v_mfma_f32_16x16x32_bf16 v[40:43], v[158:161], v[190:193], v[40:43]
	v_mfma_f32_16x16x32_bf16 v[28:31], v[140:143], v[198:201], v[28:31]
	v_mfma_f32_16x16x32_bf16 v[24:27], v[158:161], v[198:201], v[24:27]
	v_mfma_f32_16x16x32_bf16 v[12:15], v[140:143], v[208:211], v[12:15]
	v_mfma_f32_16x16x32_bf16 v[8:11], v[158:161], v[208:211], v[8:11]
	v_mfma_f32_16x16x32_bf16 v[60:63], v[144:147], v[186:189], v[60:63]
	v_mfma_f32_16x16x32_bf16 v[56:59], v[162:165], v[186:189], v[56:59]
	v_mfma_f32_16x16x32_bf16 v[44:47], v[144:147], v[194:197], v[44:47]
	v_mfma_f32_16x16x32_bf16 v[40:43], v[162:165], v[194:197], v[40:43]
	v_mfma_f32_16x16x32_bf16 v[28:31], v[144:147], v[202:205], v[28:31]
	v_mfma_f32_16x16x32_bf16 v[24:27], v[162:165], v[202:205], v[24:27]
	v_mfma_f32_16x16x32_bf16 v[12:15], v[144:147], v[212:215], v[12:15]
	v_mfma_f32_16x16x32_bf16 v[8:11], v[162:165], v[212:215], v[8:11]
	v_mfma_f32_16x16x32_bf16 v[52:55], v[166:169], v[182:185], v[52:55]
	v_mfma_f32_16x16x32_bf16 v[48:51], v[174:177], v[182:185], v[48:51]
	v_mfma_f32_16x16x32_bf16 v[36:39], v[166:169], v[190:193], v[36:39]
	v_mfma_f32_16x16x32_bf16 v[32:35], v[174:177], v[190:193], v[32:35]
	v_mfma_f32_16x16x32_bf16 v[20:23], v[166:169], v[198:201], v[20:23]
	v_mfma_f32_16x16x32_bf16 v[16:19], v[174:177], v[198:201], v[16:19]
	v_mfma_f32_16x16x32_bf16 v[4:7], v[166:169], v[208:211], v[4:7]
	v_mfma_f32_16x16x32_bf16 v[0:3], v[174:177], v[208:211], v[0:3]
	v_mfma_f32_16x16x32_bf16 v[52:55], v[170:173], v[186:189], v[52:55]
	v_mfma_f32_16x16x32_bf16 v[48:51], v[178:181], v[186:189], v[48:51]
	v_mfma_f32_16x16x32_bf16 v[36:39], v[170:173], v[194:197], v[36:39]
	v_mfma_f32_16x16x32_bf16 v[32:35], v[178:181], v[194:197], v[32:35]
	v_mfma_f32_16x16x32_bf16 v[20:23], v[170:173], v[202:205], v[20:23]
	v_mfma_f32_16x16x32_bf16 v[16:19], v[178:181], v[202:205], v[16:19]
	v_mfma_f32_16x16x32_bf16 v[4:7], v[170:173], v[212:215], v[4:7]
	v_mfma_f32_16x16x32_bf16 v[0:3], v[178:181], v[212:215], v[0:3]
	s_barrier
	s_mov_b32 m0, s46
	s_nop 0
	global_load_lds_dwordx4 v128, s[40:41]
	s_mov_b32 m0, s47
	s_nop 0
	global_load_lds_dwordx4 v130, s[40:41]
	s_add_i32 s62, 0, 0x18000
	s_add_i32 s63, 0, 0x1c000
	s_add_u32 s40, s40, 0x40000
	s_addc_u32 s41, s41, 0
	s_mov_b32 m0, s48
	s_nop 0
	global_load_lds_dwordx4 v128, s[40:41]
	s_mov_b32 m0, s49
	s_nop 0
	global_load_lds_dwordx4 v130, s[40:41]
	v_add_u32_e32 v157, s62, v151
	ds_read_b128 v[140:143], v157
	ds_read_b128 v[144:147], v157 offset:1024
	ds_read_b128 v[158:161], v157 offset:2048
	ds_read_b128 v[162:165], v157 offset:3072
	v_add_u32_e32 v157, s63, v151
	ds_read_b128 v[166:169], v157
	ds_read_b128 v[170:173], v157 offset:1024
	ds_read_b128 v[174:177], v157 offset:2048
	ds_read_b128 v[178:181], v157 offset:3072
	ds_read_b128 v[182:185], v155 offset:32768
	ds_read_b128 v[186:189], v155 offset:33792
	ds_read_b128 v[190:193], v155 offset:34816
	ds_read_b128 v[194:197], v155 offset:35840
	ds_read_b128 v[198:201], v155 offset:36864
	ds_read_b128 v[202:205], v155 offset:37888
	ds_read_b128 v[208:211], v155 offset:38912
	ds_read_b128 v[212:215], v155 offset:39936
	s_waitcnt vmcnt(8)
	s_waitcnt lgkmcnt(0)
	s_barrier
	v_mfma_f32_16x16x32_bf16 v[124:127], v[140:143], v[182:185], v[124:127]
	v_mfma_f32_16x16x32_bf16 v[120:123], v[158:161], v[182:185], v[120:123]
	v_mfma_f32_16x16x32_bf16 v[108:111], v[140:143], v[190:193], v[108:111]
	v_mfma_f32_16x16x32_bf16 v[104:107], v[158:161], v[190:193], v[104:107]
	v_mfma_f32_16x16x32_bf16 v[92:95], v[140:143], v[198:201], v[92:95]
	v_mfma_f32_16x16x32_bf16 v[88:91], v[158:161], v[198:201], v[88:91]
	v_mfma_f32_16x16x32_bf16 v[76:79], v[140:143], v[208:211], v[76:79]
	v_mfma_f32_16x16x32_bf16 v[72:75], v[158:161], v[208:211], v[72:75]
	v_mfma_f32_16x16x32_bf16 v[124:127], v[144:147], v[186:189], v[124:127]
	v_mfma_f32_16x16x32_bf16 v[120:123], v[162:165], v[186:189], v[120:123]
	v_mfma_f32_16x16x32_bf16 v[108:111], v[144:147], v[194:197], v[108:111]
	v_mfma_f32_16x16x32_bf16 v[104:107], v[162:165], v[194:197], v[104:107]
	v_mfma_f32_16x16x32_bf16 v[92:95], v[144:147], v[202:205], v[92:95]
	v_mfma_f32_16x16x32_bf16 v[88:91], v[162:165], v[202:205], v[88:91]
	v_mfma_f32_16x16x32_bf16 v[76:79], v[144:147], v[212:215], v[76:79]
	v_mfma_f32_16x16x32_bf16 v[72:75], v[162:165], v[212:215], v[72:75]
	v_mfma_f32_16x16x32_bf16 v[116:119], v[166:169], v[182:185], v[116:119]
	v_mfma_f32_16x16x32_bf16 v[112:115], v[174:177], v[182:185], v[112:115]
	v_mfma_f32_16x16x32_bf16 v[100:103], v[166:169], v[190:193], v[100:103]
	v_mfma_f32_16x16x32_bf16 v[96:99], v[174:177], v[190:193], v[96:99]
	v_mfma_f32_16x16x32_bf16 v[84:87], v[166:169], v[198:201], v[84:87]
	v_mfma_f32_16x16x32_bf16 v[80:83], v[174:177], v[198:201], v[80:83]
	v_mfma_f32_16x16x32_bf16 v[68:71], v[166:169], v[208:211], v[68:71]
	v_mfma_f32_16x16x32_bf16 v[64:67], v[174:177], v[208:211], v[64:67]
	v_mfma_f32_16x16x32_bf16 v[116:119], v[170:173], v[186:189], v[116:119]
	v_mfma_f32_16x16x32_bf16 v[112:115], v[178:181], v[186:189], v[112:115]
	v_mfma_f32_16x16x32_bf16 v[100:103], v[170:173], v[194:197], v[100:103]
	v_mfma_f32_16x16x32_bf16 v[96:99], v[178:181], v[194:197], v[96:99]
	v_mfma_f32_16x16x32_bf16 v[84:87], v[170:173], v[202:205], v[84:87]
	v_mfma_f32_16x16x32_bf16 v[80:83], v[178:181], v[202:205], v[80:83]
	v_mfma_f32_16x16x32_bf16 v[68:71], v[170:173], v[212:215], v[68:71]
	v_mfma_f32_16x16x32_bf16 v[64:67], v[178:181], v[212:215], v[64:67]
	s_barrier
	s_add_i32 s40, s62, s45
	s_mov_b32 m0, s40
	s_nop 0
	global_load_lds_dwordx4 v148, s[38:39]
	s_add_i32 m0, s40, 0x2000
	s_add_u32 s38, s38, 0x40080
	s_addc_u32 s39, s39, 0
	s_add_i32 s40, s63, s45
	global_load_lds_dwordx4 v149, s[98:99]
	s_mov_b32 m0, s40
	s_nop 0
	global_load_lds_dwordx4 v128, s[38:39]
	s_add_i32 m0, s40, 0x2000
	s_nop 0
	global_load_lds_dwordx4 v130, s[38:39]
	s_cmp_lg_u32 s61, 12
	s_cbranch_scc1 .Lbal_last_17
	s_mov_b32 m0, s51
	s_nop 0
	global_load_lds_dwordx4 v148, s[100:101]
	s_mov_b32 m0, s52
	s_nop 0
	global_load_lds_dwordx4 v149, s[100:101]
.Lbal_last_17:
	ds_read_b128 v[182:185], v155 offset:49152
	ds_read_b128 v[186:189], v155 offset:50176
	ds_read_b128 v[190:193], v155 offset:51200
	ds_read_b128 v[194:197], v155 offset:52224
	ds_read_b128 v[198:201], v155 offset:53248
	ds_read_b128 v[202:205], v155 offset:54272
	ds_read_b128 v[208:211], v155 offset:55296
	ds_read_b128 v[212:215], v155 offset:56320
	s_waitcnt vmcnt(6)
	s_waitcnt lgkmcnt(0)
	s_barrier
	v_mfma_f32_16x16x32_bf16 v[60:63], v[140:143], v[182:185], v[60:63]
	v_mfma_f32_16x16x32_bf16 v[56:59], v[158:161], v[182:185], v[56:59]
	v_mfma_f32_16x16x32_bf16 v[44:47], v[140:143], v[190:193], v[44:47]
	v_mfma_f32_16x16x32_bf16 v[40:43], v[158:161], v[190:193], v[40:43]
	s_add_i32 s61, s61, 2
	s_add_u32 s59, s59, 0x100
	s_addc_u32 s60, s60, 0
	s_add_u32 s36, s36, 0x100
	s_addc_u32 s37, s37, 0
	s_cmp_gt_u32 s61, 13
	v_mfma_f32_16x16x32_bf16 v[28:31], v[140:143], v[198:201], v[28:31]
	v_mfma_f32_16x16x32_bf16 v[24:27], v[158:161], v[198:201], v[24:27]
	v_mfma_f32_16x16x32_bf16 v[12:15], v[140:143], v[208:211], v[12:15]
	v_mfma_f32_16x16x32_bf16 v[8:11], v[158:161], v[208:211], v[8:11]
	v_mfma_f32_16x16x32_bf16 v[60:63], v[144:147], v[186:189], v[60:63]
	v_mfma_f32_16x16x32_bf16 v[56:59], v[162:165], v[186:189], v[56:59]
	v_mfma_f32_16x16x32_bf16 v[44:47], v[144:147], v[194:197], v[44:47]
	v_mfma_f32_16x16x32_bf16 v[40:43], v[162:165], v[194:197], v[40:43]
	v_mfma_f32_16x16x32_bf16 v[28:31], v[144:147], v[202:205], v[28:31]
	v_mfma_f32_16x16x32_bf16 v[24:27], v[162:165], v[202:205], v[24:27]
	v_mfma_f32_16x16x32_bf16 v[12:15], v[144:147], v[212:215], v[12:15]
	v_mfma_f32_16x16x32_bf16 v[8:11], v[162:165], v[212:215], v[8:11]
	v_mfma_f32_16x16x32_bf16 v[52:55], v[166:169], v[182:185], v[52:55]
	v_mfma_f32_16x16x32_bf16 v[48:51], v[174:177], v[182:185], v[48:51]
	v_mfma_f32_16x16x32_bf16 v[36:39], v[166:169], v[190:193], v[36:39]
	v_mfma_f32_16x16x32_bf16 v[32:35], v[174:177], v[190:193], v[32:35]
	v_mfma_f32_16x16x32_bf16 v[20:23], v[166:169], v[198:201], v[20:23]
	v_mfma_f32_16x16x32_bf16 v[16:19], v[174:177], v[198:201], v[16:19]
	v_mfma_f32_16x16x32_bf16 v[4:7], v[166:169], v[208:211], v[4:7]
	v_mfma_f32_16x16x32_bf16 v[0:3], v[174:177], v[208:211], v[0:3]
	v_mfma_f32_16x16x32_bf16 v[52:55], v[170:173], v[186:189], v[52:55]
	v_mfma_f32_16x16x32_bf16 v[48:51], v[178:181], v[186:189], v[48:51]
	v_mfma_f32_16x16x32_bf16 v[36:39], v[170:173], v[194:197], v[36:39]
	v_mfma_f32_16x16x32_bf16 v[32:35], v[178:181], v[194:197], v[32:35]
	v_mfma_f32_16x16x32_bf16 v[20:23], v[170:173], v[202:205], v[20:23]
	v_mfma_f32_16x16x32_bf16 v[16:19], v[178:181], v[202:205], v[16:19]
	v_mfma_f32_16x16x32_bf16 v[4:7], v[170:173], v[212:215], v[4:7]
	v_mfma_f32_16x16x32_bf16 v[0:3], v[178:181], v[212:215], v[0:3]
	s_barrier
	s_cbranch_scc0 .LBB0_895
	s_setprio 0
	s_and_b64 vcc, exec, s[24:25]
	s_cbranch_vccz .LBB0_898
	s_barrier

.Lbal_first_16:
	s_add_u32 s26, s6, 0xfffc0080
	s_addc_u32 s27, s7, -1
	s_cmp_eq_u32 s53, 12
	s_cselect_b32 s29, s19, s27
	s_cselect_b32 s28, s49, s26
	s_cselect_b32 s27, s17, s52
	s_cselect_b32 s26, s50, s51
	s_add_i32 m0, s25, 0xc000
	s_nop 0
	global_load_lds_dwordx4 v138, s[6:7]
	s_add_i32 m0, s25, 0xe000
	s_nop 0
	global_load_lds_dwordx4 v136, s[6:7]
	ds_read_b128 v[144:147], v151
	ds_read_b128 v[156:159], v151 offset:1024
	ds_read_b128 v[160:163], v151 offset:2048
	ds_read_b128 v[164:167], v151 offset:3072
	ds_read_b128 v[168:171], v152
	ds_read_b128 v[172:175], v152 offset:1024
	ds_read_b128 v[176:179], v152 offset:2048
	ds_read_b128 v[180:183], v152 offset:3072
	ds_read_b128 v[184:187], v153
	ds_read_b128 v[188:191], v153 offset:1024
	ds_read_b128 v[192:195], v153 offset:2048
	ds_read_b128 v[196:199], v153 offset:3072
	ds_read_b128 v[200:203], v153 offset:4096
	ds_read_b128 v[208:211], v153 offset:5120
	ds_read_b128 v[212:215], v153 offset:6144
	ds_read_b128 v[216:219], v153 offset:7168
	s_waitcnt vmcnt(8)
	s_waitcnt lgkmcnt(0)
	s_barrier
	v_mfma_f32_16x16x32_bf16 v[124:127], v[144:147], v[184:187], v[124:127]
	v_mfma_f32_16x16x32_bf16 v[120:123], v[160:163], v[184:187], v[120:123]
	v_mfma_f32_16x16x32_bf16 v[108:111], v[144:147], v[192:195], v[108:111]
	v_mfma_f32_16x16x32_bf16 v[104:107], v[160:163], v[192:195], v[104:107]
	v_mfma_f32_16x16x32_bf16 v[92:95], v[144:147], v[200:203], v[92:95]
	v_mfma_f32_16x16x32_bf16 v[88:91], v[160:163], v[200:203], v[88:91]
	v_mfma_f32_16x16x32_bf16 v[76:79], v[144:147], v[212:215], v[76:79]
	v_mfma_f32_16x16x32_bf16 v[72:75], v[160:163], v[212:215], v[72:75]
	v_mfma_f32_16x16x32_bf16 v[124:127], v[156:159], v[188:191], v[124:127]
	v_mfma_f32_16x16x32_bf16 v[120:123], v[164:167], v[188:191], v[120:123]
	v_mfma_f32_16x16x32_bf16 v[108:111], v[156:159], v[196:199], v[108:111]
	v_mfma_f32_16x16x32_bf16 v[104:107], v[164:167], v[196:199], v[104:107]
	v_mfma_f32_16x16x32_bf16 v[92:95], v[156:159], v[208:211], v[92:95]
	v_mfma_f32_16x16x32_bf16 v[88:91], v[164:167], v[208:211], v[88:91]
	v_mfma_f32_16x16x32_bf16 v[76:79], v[156:159], v[216:219], v[76:79]
	v_mfma_f32_16x16x32_bf16 v[72:75], v[164:167], v[216:219], v[72:75]
	v_mfma_f32_16x16x32_bf16 v[116:119], v[168:171], v[184:187], v[116:119]
	v_mfma_f32_16x16x32_bf16 v[112:115], v[176:179], v[184:187], v[112:115]
	v_mfma_f32_16x16x32_bf16 v[100:103], v[168:171], v[192:195], v[100:103]
	v_mfma_f32_16x16x32_bf16 v[96:99], v[176:179], v[192:195], v[96:99]
	v_mfma_f32_16x16x32_bf16 v[84:87], v[168:171], v[200:203], v[84:87]
	v_mfma_f32_16x16x32_bf16 v[80:83], v[176:179], v[200:203], v[80:83]
	v_mfma_f32_16x16x32_bf16 v[68:71], v[168:171], v[212:215], v[68:71]
	v_mfma_f32_16x16x32_bf16 v[64:67], v[176:179], v[212:215], v[64:67]
	v_mfma_f32_16x16x32_bf16 v[116:119], v[172:175], v[188:191], v[116:119]
	v_mfma_f32_16x16x32_bf16 v[112:115], v[180:183], v[188:191], v[112:115]
	v_mfma_f32_16x16x32_bf16 v[100:103], v[172:175], v[196:199], v[100:103]
	v_mfma_f32_16x16x32_bf16 v[96:99], v[180:183], v[196:199], v[96:99]
	v_mfma_f32_16x16x32_bf16 v[84:87], v[172:175], v[208:211], v[84:87]
	v_mfma_f32_16x16x32_bf16 v[80:83], v[180:183], v[208:211], v[80:83]
	v_mfma_f32_16x16x32_bf16 v[68:71], v[172:175], v[216:219], v[68:71]
	v_mfma_f32_16x16x32_bf16 v[64:67], v[180:183], v[216:219], v[64:67]
	s_barrier
	s_add_i32 s54, s45, s38
	s_mov_b32 m0, s54
	s_nop 0
	global_load_lds_dwordx4 v130, s[26:27]
	s_add_i32 m0, s54, 0x2000
	s_add_u32 s54, s26, 0x40000
	s_mov_b64 s[98:99], s[26:27]
	s_addc_u32 s55, s27, 0
	s_add_i32 s56, s46, s38
	global_load_lds_dwordx4 v134, s[26:27]
	s_mov_b32 m0, s56
	s_mov_b64 s[100:101], s[28:29]
	global_load_lds_dwordx4 v130, s[54:55]
	s_add_i32 m0, s56, 0x2000
	s_nop 0
	global_load_lds_dwordx4 v134, s[54:55]
	ds_read_b128 v[184:187], v153 offset:16384
	ds_read_b128 v[188:191], v153 offset:17408
	ds_read_b128 v[192:195], v153 offset:18432
	ds_read_b128 v[196:199], v153 offset:19456
	ds_read_b128 v[200:203], v153 offset:20480
	ds_read_b128 v[208:211], v153 offset:21504
	ds_read_b128 v[212:215], v153 offset:22528
	ds_read_b128 v[216:219], v153 offset:23552
	s_waitcnt vmcnt(6)
	s_waitcnt lgkmcnt(0)
	s_barrier
	v_mfma_f32_16x16x32_bf16 v[60:63], v[144:147], v[184:187], v[60:63]
	v_mfma_f32_16x16x32_bf16 v[56:59], v[160:163], v[184:187], v[56:59]
	v_mfma_f32_16x16x32_bf16 v[44:47], v[144:147], v[192:195], v[44:47]
	v_mfma_f32_16x16x32_bf16 v[40:43], v[160:163], v[192:195], v[40:43]
	v_mfma_f32_16x16x32_bf16 v[28:31], v[144:147], v[200:203], v[28:31]
	v_mfma_f32_16x16x32_bf16 v[24:27], v[160:163], v[200:203], v[24:27]
	v_mfma_f32_16x16x32_bf16 v[12:15], v[144:147], v[212:215], v[12:15]
	v_mfma_f32_16x16x32_bf16 v[8:11], v[160:163], v[212:215], v[8:11]
	v_mfma_f32_16x16x32_bf16 v[60:63], v[156:159], v[188:191], v[60:63]
	v_mfma_f32_16x16x32_bf16 v[56:59], v[164:167], v[188:191], v[56:59]
	v_mfma_f32_16x16x32_bf16 v[44:47], v[156:159], v[196:199], v[44:47]
	v_mfma_f32_16x16x32_bf16 v[40:43], v[164:167], v[196:199], v[40:43]
	v_mfma_f32_16x16x32_bf16 v[28:31], v[156:159], v[208:211], v[28:31]
	v_mfma_f32_16x16x32_bf16 v[24:27], v[164:167], v[208:211], v[24:27]
	v_mfma_f32_16x16x32_bf16 v[12:15], v[156:159], v[216:219], v[12:15]
	v_mfma_f32_16x16x32_bf16 v[8:11], v[164:167], v[216:219], v[8:11]
	v_mfma_f32_16x16x32_bf16 v[52:55], v[168:171], v[184:187], v[52:55]
	v_mfma_f32_16x16x32_bf16 v[48:51], v[176:179], v[184:187], v[48:51]
	v_mfma_f32_16x16x32_bf16 v[36:39], v[168:171], v[192:195], v[36:39]
	v_mfma_f32_16x16x32_bf16 v[32:35], v[176:179], v[192:195], v[32:35]
	v_mfma_f32_16x16x32_bf16 v[20:23], v[168:171], v[200:203], v[20:23]
	v_mfma_f32_16x16x32_bf16 v[16:19], v[176:179], v[200:203], v[16:19]
	v_mfma_f32_16x16x32_bf16 v[4:7], v[168:171], v[212:215], v[4:7]
	v_mfma_f32_16x16x32_bf16 v[0:3], v[176:179], v[212:215], v[0:3]
	v_mfma_f32_16x16x32_bf16 v[52:55], v[172:175], v[188:191], v[52:55]
	v_mfma_f32_16x16x32_bf16 v[48:51], v[180:183], v[188:191], v[48:51]
	v_mfma_f32_16x16x32_bf16 v[36:39], v[172:175], v[196:199], v[36:39]
	v_mfma_f32_16x16x32_bf16 v[32:35], v[180:183], v[196:199], v[32:35]
	v_mfma_f32_16x16x32_bf16 v[20:23], v[172:175], v[208:211], v[20:23]
	v_mfma_f32_16x16x32_bf16 v[16:19], v[180:183], v[208:211], v[16:19]
	v_mfma_f32_16x16x32_bf16 v[4:7], v[172:175], v[216:219], v[4:7]
	v_mfma_f32_16x16x32_bf16 v[0:3], v[180:183], v[216:219], v[0:3]
	s_barrier
	s_mov_b32 m0, s25
	s_nop 0
	global_load_lds_dwordx4 v128, s[28:29]
	s_mov_b32 m0, s39
	s_nop 0
	global_load_lds_dwordx4 v132, s[28:29]
	s_add_i32 s54, 0, 0x18000
	s_add_i32 s55, 0, 0x1c000
	s_add_u32 s28, s28, 0x40000
	s_addc_u32 s29, s29, 0
	s_mov_b32 m0, s40
	s_nop 0
	global_load_lds_dwordx4 v128, s[28:29]
	s_mov_b32 m0, s41
	s_nop 0
	global_load_lds_dwordx4 v132, s[28:29]
	v_add_u32_e32 v155, s54, v149
	ds_read_b128 v[144:147], v155
	ds_read_b128 v[156:159], v155 offset:1024
	ds_read_b128 v[160:163], v155 offset:2048
	ds_read_b128 v[164:167], v155 offset:3072
	v_add_u32_e32 v155, s55, v149
	ds_read_b128 v[168:171], v155
	ds_read_b128 v[172:175], v155 offset:1024
	ds_read_b128 v[176:179], v155 offset:2048
	ds_read_b128 v[180:183], v155 offset:3072
	ds_read_b128 v[184:187], v153 offset:32768
	ds_read_b128 v[188:191], v153 offset:33792
	ds_read_b128 v[192:195], v153 offset:34816
	ds_read_b128 v[196:199], v153 offset:35840
	ds_read_b128 v[200:203], v153 offset:36864
	ds_read_b128 v[208:211], v153 offset:37888
	ds_read_b128 v[212:215], v153 offset:38912
	ds_read_b128 v[216:219], v153 offset:39936
	s_waitcnt vmcnt(8)
	s_waitcnt lgkmcnt(0)
	s_barrier
	v_mfma_f32_16x16x32_bf16 v[124:127], v[144:147], v[184:187], v[124:127]
	v_mfma_f32_16x16x32_bf16 v[120:123], v[160:163], v[184:187], v[120:123]
	v_mfma_f32_16x16x32_bf16 v[108:111], v[144:147], v[192:195], v[108:111]
	v_mfma_f32_16x16x32_bf16 v[104:107], v[160:163], v[192:195], v[104:107]
	v_mfma_f32_16x16x32_bf16 v[92:95], v[144:147], v[200:203], v[92:95]
	v_mfma_f32_16x16x32_bf16 v[88:91], v[160:163], v[200:203], v[88:91]
	v_mfma_f32_16x16x32_bf16 v[76:79], v[144:147], v[212:215], v[76:79]
	v_mfma_f32_16x16x32_bf16 v[72:75], v[160:163], v[212:215], v[72:75]
	v_mfma_f32_16x16x32_bf16 v[124:127], v[156:159], v[188:191], v[124:127]
	v_mfma_f32_16x16x32_bf16 v[120:123], v[164:167], v[188:191], v[120:123]
	v_mfma_f32_16x16x32_bf16 v[108:111], v[156:159], v[196:199], v[108:111]
	v_mfma_f32_16x16x32_bf16 v[104:107], v[164:167], v[196:199], v[104:107]
	v_mfma_f32_16x16x32_bf16 v[92:95], v[156:159], v[208:211], v[92:95]
	v_mfma_f32_16x16x32_bf16 v[88:91], v[164:167], v[208:211], v[88:91]
	v_mfma_f32_16x16x32_bf16 v[76:79], v[156:159], v[216:219], v[76:79]
	v_mfma_f32_16x16x32_bf16 v[72:75], v[164:167], v[216:219], v[72:75]
	v_mfma_f32_16x16x32_bf16 v[116:119], v[168:171], v[184:187], v[116:119]
	v_mfma_f32_16x16x32_bf16 v[112:115], v[176:179], v[184:187], v[112:115]
	v_mfma_f32_16x16x32_bf16 v[100:103], v[168:171], v[192:195], v[100:103]
	v_mfma_f32_16x16x32_bf16 v[96:99], v[176:179], v[192:195], v[96:99]
	v_mfma_f32_16x16x32_bf16 v[84:87], v[168:171], v[200:203], v[84:87]
	v_mfma_f32_16x16x32_bf16 v[80:83], v[176:179], v[200:203], v[80:83]
	v_mfma_f32_16x16x32_bf16 v[68:71], v[168:171], v[212:215], v[68:71]
	v_mfma_f32_16x16x32_bf16 v[64:67], v[176:179], v[212:215], v[64:67]
	v_mfma_f32_16x16x32_bf16 v[116:119], v[172:175], v[188:191], v[116:119]
	v_mfma_f32_16x16x32_bf16 v[112:115], v[180:183], v[188:191], v[112:115]
	v_mfma_f32_16x16x32_bf16 v[100:103], v[172:175], v[196:199], v[100:103]
	v_mfma_f32_16x16x32_bf16 v[96:99], v[180:183], v[196:199], v[96:99]
	v_mfma_f32_16x16x32_bf16 v[84:87], v[172:175], v[208:211], v[84:87]
	v_mfma_f32_16x16x32_bf16 v[80:83], v[180:183], v[208:211], v[80:83]
	v_mfma_f32_16x16x32_bf16 v[68:71], v[172:175], v[216:219], v[68:71]
	v_mfma_f32_16x16x32_bf16 v[64:67], v[180:183], v[216:219], v[64:67]
	s_barrier
	s_add_i32 s28, s54, s38
	s_mov_b32 m0, s28
	s_nop 0
	global_load_lds_dwordx4 v205, s[26:27]
	s_add_i32 m0, s28, 0x2000
	s_add_u32 s26, s26, 0x40080
	s_addc_u32 s27, s27, 0
	s_add_i32 s28, s55, s38
	global_load_lds_dwordx4 v221, s[98:99]
	s_mov_b32 m0, s28
	s_nop 0
	global_load_lds_dwordx4 v130, s[26:27]
	s_add_i32 m0, s28, 0x2000
	s_nop 0
	global_load_lds_dwordx4 v134, s[26:27]
	s_cmp_lg_u32 s53, 12
	s_cbranch_scc1 .Lbal_last_16
	s_mov_b32 m0, s43
	s_nop 0
	global_load_lds_dwordx4 v204, s[100:101]
	s_mov_b32 m0, s44
	s_nop 0
	global_load_lds_dwordx4 v220, s[100:101]
.Lbal_last_16:
	ds_read_b128 v[184:187], v153 offset:49152
	ds_read_b128 v[188:191], v153 offset:50176
	ds_read_b128 v[192:195], v153 offset:51200
	ds_read_b128 v[196:199], v153 offset:52224
	ds_read_b128 v[200:203], v153 offset:53248
	ds_read_b128 v[208:211], v153 offset:54272
	ds_read_b128 v[212:215], v153 offset:55296
	ds_read_b128 v[216:219], v153 offset:56320
	s_waitcnt vmcnt(6)
	s_waitcnt lgkmcnt(0)
	s_barrier
	v_mfma_f32_16x16x32_bf16 v[60:63], v[144:147], v[184:187], v[60:63]
	v_mfma_f32_16x16x32_bf16 v[56:59], v[160:163], v[184:187], v[56:59]
	v_mfma_f32_16x16x32_bf16 v[44:47], v[144:147], v[192:195], v[44:47]
	v_mfma_f32_16x16x32_bf16 v[40:43], v[160:163], v[192:195], v[40:43]
	s_add_i32 s53, s53, 2
	s_add_u32 s51, s51, 0x100
	s_addc_u32 s52, s52, 0
	s_add_u32 s6, s6, 0x100
	s_addc_u32 s7, s7, 0
	s_cmp_gt_u32 s53, 13
	v_mfma_f32_16x16x32_bf16 v[28:31], v[144:147], v[200:203], v[28:31]
	v_mfma_f32_16x16x32_bf16 v[24:27], v[160:163], v[200:203], v[24:27]
	v_mfma_f32_16x16x32_bf16 v[12:15], v[144:147], v[212:215], v[12:15]
	v_mfma_f32_16x16x32_bf16 v[8:11], v[160:163], v[212:215], v[8:11]
	v_mfma_f32_16x16x32_bf16 v[60:63], v[156:159], v[188:191], v[60:63]
	v_mfma_f32_16x16x32_bf16 v[56:59], v[164:167], v[188:191], v[56:59]
	v_mfma_f32_16x16x32_bf16 v[44:47], v[156:159], v[196:199], v[44:47]
	v_mfma_f32_16x16x32_bf16 v[40:43], v[164:167], v[196:199], v[40:43]
	v_mfma_f32_16x16x32_bf16 v[28:31], v[156:159], v[208:211], v[28:31]
	v_mfma_f32_16x16x32_bf16 v[24:27], v[164:167], v[208:211], v[24:27]
	v_mfma_f32_16x16x32_bf16 v[12:15], v[156:159], v[216:219], v[12:15]
	v_mfma_f32_16x16x32_bf16 v[8:11], v[164:167], v[216:219], v[8:11]
	v_mfma_f32_16x16x32_bf16 v[52:55], v[168:171], v[184:187], v[52:55]
	v_mfma_f32_16x16x32_bf16 v[48:51], v[176:179], v[184:187], v[48:51]
	v_mfma_f32_16x16x32_bf16 v[36:39], v[168:171], v[192:195], v[36:39]
	v_mfma_f32_16x16x32_bf16 v[32:35], v[176:179], v[192:195], v[32:35]
	v_mfma_f32_16x16x32_bf16 v[20:23], v[168:171], v[200:203], v[20:23]
	v_mfma_f32_16x16x32_bf16 v[16:19], v[176:179], v[200:203], v[16:19]
	v_mfma_f32_16x16x32_bf16 v[4:7], v[168:171], v[212:215], v[4:7]
	v_mfma_f32_16x16x32_bf16 v[0:3], v[176:179], v[212:215], v[0:3]
	v_mfma_f32_16x16x32_bf16 v[52:55], v[172:175], v[188:191], v[52:55]
	v_mfma_f32_16x16x32_bf16 v[48:51], v[180:183], v[188:191], v[48:51]
	v_mfma_f32_16x16x32_bf16 v[36:39], v[172:175], v[196:199], v[36:39]
	v_mfma_f32_16x16x32_bf16 v[32:35], v[180:183], v[196:199], v[32:35]
	v_mfma_f32_16x16x32_bf16 v[20:23], v[172:175], v[208:211], v[20:23]
	v_mfma_f32_16x16x32_bf16 v[16:19], v[180:183], v[208:211], v[16:19]
	v_mfma_f32_16x16x32_bf16 v[4:7], v[172:175], v[216:219], v[4:7]
	v_mfma_f32_16x16x32_bf16 v[0:3], v[180:183], v[216:219], v[0:3]
	s_barrier
	s_cbranch_scc0 .LBB0_988
	s_setprio 0
	s_and_b64 vcc, exec, s[14:15]
	s_cbranch_vccz .LBB0_991
	s_barrier

.Lbal_first_15:
	s_add_u32 s26, s24, 0xfffe0080
	s_addc_u32 s27, s25, -1
	s_cmp_eq_u32 s50, 4
	s_cselect_b32 s29, s17, s27
	s_cselect_b32 s28, s46, s26
	s_cselect_b32 s27, s15, s49
	s_cselect_b32 s26, s47, s48
	s_add_i32 m0, s23, 0xc000
	s_nop 0
	global_load_lds_dwordx4 v138, s[24:25]
	s_add_i32 m0, s23, 0xe000
	s_nop 0
	global_load_lds_dwordx4 v136, s[24:25]
	ds_read_b128 v[144:147], v151
	ds_read_b128 v[154:157], v151 offset:1024
	ds_read_b128 v[158:161], v151 offset:2048
	ds_read_b128 v[162:165], v151 offset:3072
	ds_read_b128 v[166:169], v152
	ds_read_b128 v[170:173], v152 offset:1024
	ds_read_b128 v[174:177], v152 offset:2048
	ds_read_b128 v[178:181], v152 offset:3072
	ds_read_b128 v[182:185], v153
	ds_read_b128 v[186:189], v153 offset:1024
	ds_read_b128 v[190:193], v153 offset:2048
	ds_read_b128 v[194:197], v153 offset:3072
	ds_read_b128 v[198:201], v153 offset:4096
	ds_read_b128 v[202:205], v153 offset:5120
	ds_read_b128 v[208:211], v153 offset:6144
	ds_read_b128 v[212:215], v153 offset:7168
	s_waitcnt vmcnt(8)
	s_waitcnt lgkmcnt(0)
	s_barrier
	v_mfma_f32_16x16x32_bf16 v[124:127], v[144:147], v[182:185], v[124:127]
	v_mfma_f32_16x16x32_bf16 v[120:123], v[158:161], v[182:185], v[120:123]
	v_mfma_f32_16x16x32_bf16 v[108:111], v[144:147], v[190:193], v[108:111]
	v_mfma_f32_16x16x32_bf16 v[104:107], v[158:161], v[190:193], v[104:107]
	v_mfma_f32_16x16x32_bf16 v[92:95], v[144:147], v[198:201], v[92:95]
	v_mfma_f32_16x16x32_bf16 v[88:91], v[158:161], v[198:201], v[88:91]
	v_mfma_f32_16x16x32_bf16 v[76:79], v[144:147], v[208:211], v[76:79]
	v_mfma_f32_16x16x32_bf16 v[72:75], v[158:161], v[208:211], v[72:75]
	v_mfma_f32_16x16x32_bf16 v[124:127], v[154:157], v[186:189], v[124:127]
	v_mfma_f32_16x16x32_bf16 v[120:123], v[162:165], v[186:189], v[120:123]
	v_mfma_f32_16x16x32_bf16 v[108:111], v[154:157], v[194:197], v[108:111]
	v_mfma_f32_16x16x32_bf16 v[104:107], v[162:165], v[194:197], v[104:107]
	v_mfma_f32_16x16x32_bf16 v[92:95], v[154:157], v[202:205], v[92:95]
	v_mfma_f32_16x16x32_bf16 v[88:91], v[162:165], v[202:205], v[88:91]
	v_mfma_f32_16x16x32_bf16 v[76:79], v[154:157], v[212:215], v[76:79]
	v_mfma_f32_16x16x32_bf16 v[72:75], v[162:165], v[212:215], v[72:75]
	v_mfma_f32_16x16x32_bf16 v[116:119], v[166:169], v[182:185], v[116:119]
	v_mfma_f32_16x16x32_bf16 v[112:115], v[174:177], v[182:185], v[112:115]
	v_mfma_f32_16x16x32_bf16 v[100:103], v[166:169], v[190:193], v[100:103]
	v_mfma_f32_16x16x32_bf16 v[96:99], v[174:177], v[190:193], v[96:99]
	v_mfma_f32_16x16x32_bf16 v[84:87], v[166:169], v[198:201], v[84:87]
	v_mfma_f32_16x16x32_bf16 v[80:83], v[174:177], v[198:201], v[80:83]
	v_mfma_f32_16x16x32_bf16 v[68:71], v[166:169], v[208:211], v[68:71]
	v_mfma_f32_16x16x32_bf16 v[64:67], v[174:177], v[208:211], v[64:67]
	v_mfma_f32_16x16x32_bf16 v[116:119], v[170:173], v[186:189], v[116:119]
	v_mfma_f32_16x16x32_bf16 v[112:115], v[178:181], v[186:189], v[112:115]
	v_mfma_f32_16x16x32_bf16 v[100:103], v[170:173], v[194:197], v[100:103]
	v_mfma_f32_16x16x32_bf16 v[96:99], v[178:181], v[194:197], v[96:99]
	v_mfma_f32_16x16x32_bf16 v[84:87], v[170:173], v[202:205], v[84:87]
	v_mfma_f32_16x16x32_bf16 v[80:83], v[178:181], v[202:205], v[80:83]
	v_mfma_f32_16x16x32_bf16 v[68:71], v[170:173], v[212:215], v[68:71]
	v_mfma_f32_16x16x32_bf16 v[64:67], v[178:181], v[212:215], v[64:67]
	s_barrier
	s_add_i32 s51, s43, s36
	s_mov_b32 m0, s51
	s_nop 0
	global_load_lds_dwordx4 v130, s[26:27]
	s_add_i32 m0, s51, 0x2000
	s_add_u32 s52, s26, 0x20000
	s_mov_b64 s[98:99], s[26:27]
	s_addc_u32 s53, s27, 0
	s_add_i32 s51, s44, s36
	global_load_lds_dwordx4 v134, s[26:27]
	s_mov_b32 m0, s51
	s_mov_b64 s[100:101], s[28:29]
	global_load_lds_dwordx4 v130, s[52:53]
	s_add_i32 m0, s51, 0x2000
	s_nop 0
	global_load_lds_dwordx4 v134, s[52:53]
	ds_read_b128 v[182:185], v153 offset:16384
	ds_read_b128 v[186:189], v153 offset:17408
	ds_read_b128 v[190:193], v153 offset:18432
	ds_read_b128 v[194:197], v153 offset:19456
	ds_read_b128 v[198:201], v153 offset:20480
	ds_read_b128 v[202:205], v153 offset:21504
	ds_read_b128 v[208:211], v153 offset:22528
	ds_read_b128 v[212:215], v153 offset:23552
	s_waitcnt vmcnt(6)
	s_waitcnt lgkmcnt(0)
	s_barrier
	v_mfma_f32_16x16x32_bf16 v[60:63], v[144:147], v[182:185], v[60:63]
	v_mfma_f32_16x16x32_bf16 v[56:59], v[158:161], v[182:185], v[56:59]
	v_mfma_f32_16x16x32_bf16 v[44:47], v[144:147], v[190:193], v[44:47]
	v_mfma_f32_16x16x32_bf16 v[40:43], v[158:161], v[190:193], v[40:43]
	v_mfma_f32_16x16x32_bf16 v[28:31], v[144:147], v[198:201], v[28:31]
	v_mfma_f32_16x16x32_bf16 v[24:27], v[158:161], v[198:201], v[24:27]
	v_mfma_f32_16x16x32_bf16 v[12:15], v[144:147], v[208:211], v[12:15]
	v_mfma_f32_16x16x32_bf16 v[8:11], v[158:161], v[208:211], v[8:11]
	v_mfma_f32_16x16x32_bf16 v[60:63], v[154:157], v[186:189], v[60:63]
	v_mfma_f32_16x16x32_bf16 v[56:59], v[162:165], v[186:189], v[56:59]
	v_mfma_f32_16x16x32_bf16 v[44:47], v[154:157], v[194:197], v[44:47]
	v_mfma_f32_16x16x32_bf16 v[40:43], v[162:165], v[194:197], v[40:43]
	v_mfma_f32_16x16x32_bf16 v[28:31], v[154:157], v[202:205], v[28:31]
	v_mfma_f32_16x16x32_bf16 v[24:27], v[162:165], v[202:205], v[24:27]
	v_mfma_f32_16x16x32_bf16 v[12:15], v[154:157], v[212:215], v[12:15]
	v_mfma_f32_16x16x32_bf16 v[8:11], v[162:165], v[212:215], v[8:11]
	v_mfma_f32_16x16x32_bf16 v[52:55], v[166:169], v[182:185], v[52:55]
	v_mfma_f32_16x16x32_bf16 v[48:51], v[174:177], v[182:185], v[48:51]
	v_mfma_f32_16x16x32_bf16 v[36:39], v[166:169], v[190:193], v[36:39]
	v_mfma_f32_16x16x32_bf16 v[32:35], v[174:177], v[190:193], v[32:35]
	v_mfma_f32_16x16x32_bf16 v[20:23], v[166:169], v[198:201], v[20:23]
	v_mfma_f32_16x16x32_bf16 v[16:19], v[174:177], v[198:201], v[16:19]
	v_mfma_f32_16x16x32_bf16 v[4:7], v[166:169], v[208:211], v[4:7]
	v_mfma_f32_16x16x32_bf16 v[0:3], v[174:177], v[208:211], v[0:3]
	v_mfma_f32_16x16x32_bf16 v[52:55], v[170:173], v[186:189], v[52:55]
	v_mfma_f32_16x16x32_bf16 v[48:51], v[178:181], v[186:189], v[48:51]
	v_mfma_f32_16x16x32_bf16 v[36:39], v[170:173], v[194:197], v[36:39]
	v_mfma_f32_16x16x32_bf16 v[32:35], v[178:181], v[194:197], v[32:35]
	v_mfma_f32_16x16x32_bf16 v[20:23], v[170:173], v[202:205], v[20:23]
	v_mfma_f32_16x16x32_bf16 v[16:19], v[178:181], v[202:205], v[16:19]
	v_mfma_f32_16x16x32_bf16 v[4:7], v[170:173], v[212:215], v[4:7]
	v_mfma_f32_16x16x32_bf16 v[0:3], v[178:181], v[212:215], v[0:3]
	s_barrier
	s_mov_b32 m0, s23
	s_nop 0
	global_load_lds_dwordx4 v128, s[28:29]
	s_mov_b32 m0, s37
	s_nop 0
	global_load_lds_dwordx4 v132, s[28:29]
	s_add_i32 s51, 0, 0x18000
	s_add_i32 s52, 0, 0x1c000
	s_add_u32 s28, s28, 0x20000
	s_addc_u32 s29, s29, 0
	s_mov_b32 m0, s38
	s_nop 0
	global_load_lds_dwordx4 v128, s[28:29]
	s_mov_b32 m0, s39
	s_nop 0
	global_load_lds_dwordx4 v132, s[28:29]
	v_add_u32_e32 v162, s51, v149
	v_add_u32_e32 v178, s52, v149
	ds_read_b128 v[144:147], v162
	ds_read_b128 v[154:157], v162 offset:1024
	ds_read_b128 v[158:161], v162 offset:2048
	ds_read_b128 v[162:165], v162 offset:3072
	ds_read_b128 v[166:169], v178
	ds_read_b128 v[170:173], v178 offset:1024
	ds_read_b128 v[174:177], v178 offset:2048
	ds_read_b128 v[178:181], v178 offset:3072
	ds_read_b128 v[182:185], v153 offset:32768
	ds_read_b128 v[186:189], v153 offset:33792
	ds_read_b128 v[190:193], v153 offset:34816
	ds_read_b128 v[194:197], v153 offset:35840
	ds_read_b128 v[198:201], v153 offset:36864
	ds_read_b128 v[202:205], v153 offset:37888
	ds_read_b128 v[208:211], v153 offset:38912
	ds_read_b128 v[212:215], v153 offset:39936
	s_waitcnt vmcnt(8)
	s_waitcnt lgkmcnt(0)
	s_barrier
	v_mfma_f32_16x16x32_bf16 v[124:127], v[144:147], v[182:185], v[124:127]
	v_mfma_f32_16x16x32_bf16 v[120:123], v[158:161], v[182:185], v[120:123]
	v_mfma_f32_16x16x32_bf16 v[108:111], v[144:147], v[190:193], v[108:111]
	v_mfma_f32_16x16x32_bf16 v[104:107], v[158:161], v[190:193], v[104:107]
	v_mfma_f32_16x16x32_bf16 v[92:95], v[144:147], v[198:201], v[92:95]
	v_mfma_f32_16x16x32_bf16 v[88:91], v[158:161], v[198:201], v[88:91]
	v_mfma_f32_16x16x32_bf16 v[76:79], v[144:147], v[208:211], v[76:79]
	v_mfma_f32_16x16x32_bf16 v[72:75], v[158:161], v[208:211], v[72:75]
	v_mfma_f32_16x16x32_bf16 v[124:127], v[154:157], v[186:189], v[124:127]
	v_mfma_f32_16x16x32_bf16 v[120:123], v[162:165], v[186:189], v[120:123]
	v_mfma_f32_16x16x32_bf16 v[108:111], v[154:157], v[194:197], v[108:111]
	v_mfma_f32_16x16x32_bf16 v[104:107], v[162:165], v[194:197], v[104:107]
	v_mfma_f32_16x16x32_bf16 v[92:95], v[154:157], v[202:205], v[92:95]
	v_mfma_f32_16x16x32_bf16 v[88:91], v[162:165], v[202:205], v[88:91]
	v_mfma_f32_16x16x32_bf16 v[76:79], v[154:157], v[212:215], v[76:79]
	v_mfma_f32_16x16x32_bf16 v[72:75], v[162:165], v[212:215], v[72:75]
	v_mfma_f32_16x16x32_bf16 v[116:119], v[166:169], v[182:185], v[116:119]
	v_mfma_f32_16x16x32_bf16 v[112:115], v[174:177], v[182:185], v[112:115]
	v_mfma_f32_16x16x32_bf16 v[100:103], v[166:169], v[190:193], v[100:103]
	v_mfma_f32_16x16x32_bf16 v[96:99], v[174:177], v[190:193], v[96:99]
	v_mfma_f32_16x16x32_bf16 v[84:87], v[166:169], v[198:201], v[84:87]
	v_mfma_f32_16x16x32_bf16 v[80:83], v[174:177], v[198:201], v[80:83]
	v_mfma_f32_16x16x32_bf16 v[68:71], v[166:169], v[208:211], v[68:71]
	v_mfma_f32_16x16x32_bf16 v[64:67], v[174:177], v[208:211], v[64:67]
	v_mfma_f32_16x16x32_bf16 v[116:119], v[170:173], v[186:189], v[116:119]
	v_mfma_f32_16x16x32_bf16 v[112:115], v[178:181], v[186:189], v[112:115]
	v_mfma_f32_16x16x32_bf16 v[100:103], v[170:173], v[194:197], v[100:103]
	v_mfma_f32_16x16x32_bf16 v[96:99], v[178:181], v[194:197], v[96:99]
	v_mfma_f32_16x16x32_bf16 v[84:87], v[170:173], v[202:205], v[84:87]
	v_mfma_f32_16x16x32_bf16 v[80:83], v[178:181], v[202:205], v[80:83]
	v_mfma_f32_16x16x32_bf16 v[68:71], v[170:173], v[212:215], v[68:71]
	v_mfma_f32_16x16x32_bf16 v[64:67], v[178:181], v[212:215], v[64:67]
	s_barrier
	s_add_i32 s28, s51, s36
	s_mov_b32 m0, s28
	s_nop 0
	global_load_lds_dwordx4 v217, s[26:27]
	s_add_i32 m0, s28, 0x2000
	s_add_u32 s26, s26, 0x20080
	s_addc_u32 s27, s27, 0
	s_add_i32 s28, s52, s36
	global_load_lds_dwordx4 v219, s[98:99]
	s_mov_b32 m0, s28
	s_nop 0
	global_load_lds_dwordx4 v130, s[26:27]
	s_add_i32 m0, s28, 0x2000
	s_nop 0
	global_load_lds_dwordx4 v134, s[26:27]
	s_cmp_lg_u32 s50, 4
	s_cbranch_scc1 .Lbal_last_15
	s_mov_b32 m0, s41
	s_nop 0
	global_load_lds_dwordx4 v216, s[100:101]
	s_mov_b32 m0, s42
	s_nop 0
	global_load_lds_dwordx4 v218, s[100:101]
.Lbal_last_15:
	ds_read_b128 v[182:185], v153 offset:49152
	ds_read_b128 v[186:189], v153 offset:50176
	ds_read_b128 v[190:193], v153 offset:51200
	ds_read_b128 v[194:197], v153 offset:52224
	ds_read_b128 v[198:201], v153 offset:53248
	ds_read_b128 v[202:205], v153 offset:54272
	ds_read_b128 v[208:211], v153 offset:55296
	ds_read_b128 v[212:215], v153 offset:56320
	s_waitcnt vmcnt(6)
	s_waitcnt lgkmcnt(0)
	s_barrier
	v_mfma_f32_16x16x32_bf16 v[60:63], v[144:147], v[182:185], v[60:63]
	v_mfma_f32_16x16x32_bf16 v[56:59], v[158:161], v[182:185], v[56:59]
	v_mfma_f32_16x16x32_bf16 v[44:47], v[144:147], v[190:193], v[44:47]
	v_mfma_f32_16x16x32_bf16 v[40:43], v[158:161], v[190:193], v[40:43]
	s_add_i32 s50, s50, 2
	s_add_u32 s48, s48, 0x100
	s_addc_u32 s49, s49, 0
	s_add_u32 s24, s24, 0x100
	s_addc_u32 s25, s25, 0
	s_cmp_gt_u32 s50, 5
	v_mfma_f32_16x16x32_bf16 v[28:31], v[144:147], v[198:201], v[28:31]
	v_mfma_f32_16x16x32_bf16 v[24:27], v[158:161], v[198:201], v[24:27]
	v_mfma_f32_16x16x32_bf16 v[12:15], v[144:147], v[208:211], v[12:15]
	v_mfma_f32_16x16x32_bf16 v[8:11], v[158:161], v[208:211], v[8:11]
	v_mfma_f32_16x16x32_bf16 v[60:63], v[154:157], v[186:189], v[60:63]
	v_mfma_f32_16x16x32_bf16 v[56:59], v[162:165], v[186:189], v[56:59]
	v_mfma_f32_16x16x32_bf16 v[44:47], v[154:157], v[194:197], v[44:47]
	v_mfma_f32_16x16x32_bf16 v[40:43], v[162:165], v[194:197], v[40:43]
	v_mfma_f32_16x16x32_bf16 v[28:31], v[154:157], v[202:205], v[28:31]
	v_mfma_f32_16x16x32_bf16 v[24:27], v[162:165], v[202:205], v[24:27]
	v_mfma_f32_16x16x32_bf16 v[12:15], v[154:157], v[212:215], v[12:15]
	v_mfma_f32_16x16x32_bf16 v[8:11], v[162:165], v[212:215], v[8:11]
	v_mfma_f32_16x16x32_bf16 v[52:55], v[166:169], v[182:185], v[52:55]
	v_mfma_f32_16x16x32_bf16 v[48:51], v[174:177], v[182:185], v[48:51]
	v_mfma_f32_16x16x32_bf16 v[36:39], v[166:169], v[190:193], v[36:39]
	v_mfma_f32_16x16x32_bf16 v[32:35], v[174:177], v[190:193], v[32:35]
	v_mfma_f32_16x16x32_bf16 v[20:23], v[166:169], v[198:201], v[20:23]
	v_mfma_f32_16x16x32_bf16 v[16:19], v[174:177], v[198:201], v[16:19]
	v_mfma_f32_16x16x32_bf16 v[4:7], v[166:169], v[208:211], v[4:7]
	v_mfma_f32_16x16x32_bf16 v[0:3], v[174:177], v[208:211], v[0:3]
	v_mfma_f32_16x16x32_bf16 v[52:55], v[170:173], v[186:189], v[52:55]
	v_mfma_f32_16x16x32_bf16 v[48:51], v[178:181], v[186:189], v[48:51]
	v_mfma_f32_16x16x32_bf16 v[36:39], v[170:173], v[194:197], v[36:39]
	v_mfma_f32_16x16x32_bf16 v[32:35], v[178:181], v[194:197], v[32:35]
	v_mfma_f32_16x16x32_bf16 v[20:23], v[170:173], v[202:205], v[20:23]
	v_mfma_f32_16x16x32_bf16 v[16:19], v[178:181], v[202:205], v[16:19]
	v_mfma_f32_16x16x32_bf16 v[4:7], v[170:173], v[212:215], v[4:7]
	v_mfma_f32_16x16x32_bf16 v[0:3], v[178:181], v[212:215], v[0:3]
	s_barrier
	s_cbranch_scc0 .LBB0_1193
	s_setprio 0
	s_and_b64 vcc, exec, s[12:13]
	s_cbranch_vccz .LBB0_1196
	s_barrier

.Lbal_first_13:
	s_add_u32 s26, s24, 0xfffc0080
	s_addc_u32 s27, s25, -1
	s_cmp_eq_u32 s53, 12
	s_cselect_b32 s29, s19, s27
	s_cselect_b32 s28, s49, s26
	s_cselect_b32 s27, s17, s52
	s_cselect_b32 s26, s50, s51
	s_add_i32 m0, s39, 0xc000
	s_nop 0
	global_load_lds_dwordx4 v138, s[24:25]
	s_add_i32 m0, s39, 0xe000
	s_nop 0
	global_load_lds_dwordx4 v136, s[24:25]
	ds_read_b128 v[144:147], v151
	ds_read_b128 v[156:159], v151 offset:1024
	ds_read_b128 v[160:163], v151 offset:2048
	ds_read_b128 v[164:167], v151 offset:3072
	ds_read_b128 v[168:171], v152
	ds_read_b128 v[172:175], v152 offset:1024
	ds_read_b128 v[176:179], v152 offset:2048
	ds_read_b128 v[180:183], v152 offset:3072
	ds_read_b128 v[184:187], v153
	ds_read_b128 v[188:191], v153 offset:1024
	ds_read_b128 v[192:195], v153 offset:2048
	ds_read_b128 v[196:199], v153 offset:3072
	ds_read_b128 v[200:203], v153 offset:4096
	ds_read_b128 v[208:211], v153 offset:5120
	ds_read_b128 v[212:215], v153 offset:6144
	ds_read_b128 v[216:219], v153 offset:7168
	s_waitcnt vmcnt(8)
	s_waitcnt lgkmcnt(0)
	s_barrier
	v_mfma_f32_16x16x32_bf16 v[124:127], v[144:147], v[184:187], v[124:127]
	v_mfma_f32_16x16x32_bf16 v[120:123], v[160:163], v[184:187], v[120:123]
	v_mfma_f32_16x16x32_bf16 v[108:111], v[144:147], v[192:195], v[108:111]
	v_mfma_f32_16x16x32_bf16 v[104:107], v[160:163], v[192:195], v[104:107]
	v_mfma_f32_16x16x32_bf16 v[92:95], v[144:147], v[200:203], v[92:95]
	v_mfma_f32_16x16x32_bf16 v[88:91], v[160:163], v[200:203], v[88:91]
	v_mfma_f32_16x16x32_bf16 v[76:79], v[144:147], v[212:215], v[76:79]
	v_mfma_f32_16x16x32_bf16 v[72:75], v[160:163], v[212:215], v[72:75]
	v_mfma_f32_16x16x32_bf16 v[124:127], v[156:159], v[188:191], v[124:127]
	v_mfma_f32_16x16x32_bf16 v[120:123], v[164:167], v[188:191], v[120:123]
	v_mfma_f32_16x16x32_bf16 v[108:111], v[156:159], v[196:199], v[108:111]
	v_mfma_f32_16x16x32_bf16 v[104:107], v[164:167], v[196:199], v[104:107]
	v_mfma_f32_16x16x32_bf16 v[92:95], v[156:159], v[208:211], v[92:95]
	v_mfma_f32_16x16x32_bf16 v[88:91], v[164:167], v[208:211], v[88:91]
	v_mfma_f32_16x16x32_bf16 v[76:79], v[156:159], v[216:219], v[76:79]
	v_mfma_f32_16x16x32_bf16 v[72:75], v[164:167], v[216:219], v[72:75]
	v_mfma_f32_16x16x32_bf16 v[116:119], v[168:171], v[184:187], v[116:119]
	v_mfma_f32_16x16x32_bf16 v[112:115], v[176:179], v[184:187], v[112:115]
	v_mfma_f32_16x16x32_bf16 v[100:103], v[168:171], v[192:195], v[100:103]
	v_mfma_f32_16x16x32_bf16 v[96:99], v[176:179], v[192:195], v[96:99]
	v_mfma_f32_16x16x32_bf16 v[84:87], v[168:171], v[200:203], v[84:87]
	v_mfma_f32_16x16x32_bf16 v[80:83], v[176:179], v[200:203], v[80:83]
	v_mfma_f32_16x16x32_bf16 v[68:71], v[168:171], v[212:215], v[68:71]
	v_mfma_f32_16x16x32_bf16 v[64:67], v[176:179], v[212:215], v[64:67]
	v_mfma_f32_16x16x32_bf16 v[116:119], v[172:175], v[188:191], v[116:119]
	v_mfma_f32_16x16x32_bf16 v[112:115], v[180:183], v[188:191], v[112:115]
	v_mfma_f32_16x16x32_bf16 v[100:103], v[172:175], v[196:199], v[100:103]
	v_mfma_f32_16x16x32_bf16 v[96:99], v[180:183], v[196:199], v[96:99]
	v_mfma_f32_16x16x32_bf16 v[84:87], v[172:175], v[208:211], v[84:87]
	v_mfma_f32_16x16x32_bf16 v[80:83], v[180:183], v[208:211], v[80:83]
	v_mfma_f32_16x16x32_bf16 v[68:71], v[172:175], v[216:219], v[68:71]
	v_mfma_f32_16x16x32_bf16 v[64:67], v[180:183], v[216:219], v[64:67]
	s_barrier
	s_add_i32 s54, s46, s38
	s_mov_b32 m0, s54
	s_nop 0
	global_load_lds_dwordx4 v130, s[26:27]
	s_add_i32 m0, s54, 0x2000
	s_add_u32 s54, s26, 0x40000
	s_mov_b64 s[98:99], s[26:27]
	s_addc_u32 s55, s27, 0
	s_add_i32 s56, s47, s38
	global_load_lds_dwordx4 v134, s[26:27]
	s_mov_b32 m0, s56
	s_mov_b64 s[100:101], s[28:29]
	global_load_lds_dwordx4 v130, s[54:55]
	s_add_i32 m0, s56, 0x2000
	s_nop 0
	global_load_lds_dwordx4 v134, s[54:55]
	ds_read_b128 v[184:187], v153 offset:16384
	ds_read_b128 v[188:191], v153 offset:17408
	ds_read_b128 v[192:195], v153 offset:18432
	ds_read_b128 v[196:199], v153 offset:19456
	ds_read_b128 v[200:203], v153 offset:20480
	ds_read_b128 v[208:211], v153 offset:21504
	ds_read_b128 v[212:215], v153 offset:22528
	ds_read_b128 v[216:219], v153 offset:23552
	s_waitcnt vmcnt(6)
	s_waitcnt lgkmcnt(0)
	s_barrier
	v_mfma_f32_16x16x32_bf16 v[60:63], v[144:147], v[184:187], v[60:63]
	v_mfma_f32_16x16x32_bf16 v[56:59], v[160:163], v[184:187], v[56:59]
	v_mfma_f32_16x16x32_bf16 v[44:47], v[144:147], v[192:195], v[44:47]
	v_mfma_f32_16x16x32_bf16 v[40:43], v[160:163], v[192:195], v[40:43]
	v_mfma_f32_16x16x32_bf16 v[28:31], v[144:147], v[200:203], v[28:31]
	v_mfma_f32_16x16x32_bf16 v[24:27], v[160:163], v[200:203], v[24:27]
	v_mfma_f32_16x16x32_bf16 v[12:15], v[144:147], v[212:215], v[12:15]
	v_mfma_f32_16x16x32_bf16 v[8:11], v[160:163], v[212:215], v[8:11]
	v_mfma_f32_16x16x32_bf16 v[60:63], v[156:159], v[188:191], v[60:63]
	v_mfma_f32_16x16x32_bf16 v[56:59], v[164:167], v[188:191], v[56:59]
	v_mfma_f32_16x16x32_bf16 v[44:47], v[156:159], v[196:199], v[44:47]
	v_mfma_f32_16x16x32_bf16 v[40:43], v[164:167], v[196:199], v[40:43]
	v_mfma_f32_16x16x32_bf16 v[28:31], v[156:159], v[208:211], v[28:31]
	v_mfma_f32_16x16x32_bf16 v[24:27], v[164:167], v[208:211], v[24:27]
	v_mfma_f32_16x16x32_bf16 v[12:15], v[156:159], v[216:219], v[12:15]
	v_mfma_f32_16x16x32_bf16 v[8:11], v[164:167], v[216:219], v[8:11]
	v_mfma_f32_16x16x32_bf16 v[52:55], v[168:171], v[184:187], v[52:55]
	v_mfma_f32_16x16x32_bf16 v[48:51], v[176:179], v[184:187], v[48:51]
	v_mfma_f32_16x16x32_bf16 v[36:39], v[168:171], v[192:195], v[36:39]
	v_mfma_f32_16x16x32_bf16 v[32:35], v[176:179], v[192:195], v[32:35]
	v_mfma_f32_16x16x32_bf16 v[20:23], v[168:171], v[200:203], v[20:23]
	v_mfma_f32_16x16x32_bf16 v[16:19], v[176:179], v[200:203], v[16:19]
	v_mfma_f32_16x16x32_bf16 v[4:7], v[168:171], v[212:215], v[4:7]
	v_mfma_f32_16x16x32_bf16 v[0:3], v[176:179], v[212:215], v[0:3]
	v_mfma_f32_16x16x32_bf16 v[52:55], v[172:175], v[188:191], v[52:55]
	v_mfma_f32_16x16x32_bf16 v[48:51], v[180:183], v[188:191], v[48:51]
	v_mfma_f32_16x16x32_bf16 v[36:39], v[172:175], v[196:199], v[36:39]
	v_mfma_f32_16x16x32_bf16 v[32:35], v[180:183], v[196:199], v[32:35]
	v_mfma_f32_16x16x32_bf16 v[20:23], v[172:175], v[208:211], v[20:23]
	v_mfma_f32_16x16x32_bf16 v[16:19], v[180:183], v[208:211], v[16:19]
	v_mfma_f32_16x16x32_bf16 v[4:7], v[172:175], v[216:219], v[4:7]
	v_mfma_f32_16x16x32_bf16 v[0:3], v[180:183], v[216:219], v[0:3]
	s_barrier
	s_mov_b32 m0, s39
	s_nop 0
	global_load_lds_dwordx4 v128, s[28:29]
	s_mov_b32 m0, s40
	s_nop 0
	global_load_lds_dwordx4 v132, s[28:29]
	s_add_i32 s54, 0, 0x18000
	s_add_i32 s55, 0, 0x1c000
	s_add_u32 s28, s28, 0x40000
	s_addc_u32 s29, s29, 0
	s_mov_b32 m0, s41
	s_nop 0
	global_load_lds_dwordx4 v128, s[28:29]
	s_mov_b32 m0, s42
	s_nop 0
	global_load_lds_dwordx4 v132, s[28:29]
	v_add_u32_e32 v155, s54, v149
	ds_read_b128 v[144:147], v155
	ds_read_b128 v[156:159], v155 offset:1024
	ds_read_b128 v[160:163], v155 offset:2048
	ds_read_b128 v[164:167], v155 offset:3072
	v_add_u32_e32 v155, s55, v149
	ds_read_b128 v[168:171], v155
	ds_read_b128 v[172:175], v155 offset:1024
	ds_read_b128 v[176:179], v155 offset:2048
	ds_read_b128 v[180:183], v155 offset:3072
	ds_read_b128 v[184:187], v153 offset:32768
	ds_read_b128 v[188:191], v153 offset:33792
	ds_read_b128 v[192:195], v153 offset:34816
	ds_read_b128 v[196:199], v153 offset:35840
	ds_read_b128 v[200:203], v153 offset:36864
	ds_read_b128 v[208:211], v153 offset:37888
	ds_read_b128 v[212:215], v153 offset:38912
	ds_read_b128 v[216:219], v153 offset:39936
	s_waitcnt vmcnt(8)
	s_waitcnt lgkmcnt(0)
	s_barrier
	v_mfma_f32_16x16x32_bf16 v[124:127], v[144:147], v[184:187], v[124:127]
	v_mfma_f32_16x16x32_bf16 v[120:123], v[160:163], v[184:187], v[120:123]
	v_mfma_f32_16x16x32_bf16 v[108:111], v[144:147], v[192:195], v[108:111]
	v_mfma_f32_16x16x32_bf16 v[104:107], v[160:163], v[192:195], v[104:107]
	v_mfma_f32_16x16x32_bf16 v[92:95], v[144:147], v[200:203], v[92:95]
	v_mfma_f32_16x16x32_bf16 v[88:91], v[160:163], v[200:203], v[88:91]
	v_mfma_f32_16x16x32_bf16 v[76:79], v[144:147], v[212:215], v[76:79]
	v_mfma_f32_16x16x32_bf16 v[72:75], v[160:163], v[212:215], v[72:75]
	v_mfma_f32_16x16x32_bf16 v[124:127], v[156:159], v[188:191], v[124:127]
	v_mfma_f32_16x16x32_bf16 v[120:123], v[164:167], v[188:191], v[120:123]
	v_mfma_f32_16x16x32_bf16 v[108:111], v[156:159], v[196:199], v[108:111]
	v_mfma_f32_16x16x32_bf16 v[104:107], v[164:167], v[196:199], v[104:107]
	v_mfma_f32_16x16x32_bf16 v[92:95], v[156:159], v[208:211], v[92:95]
	v_mfma_f32_16x16x32_bf16 v[88:91], v[164:167], v[208:211], v[88:91]
	v_mfma_f32_16x16x32_bf16 v[76:79], v[156:159], v[216:219], v[76:79]
	v_mfma_f32_16x16x32_bf16 v[72:75], v[164:167], v[216:219], v[72:75]
	v_mfma_f32_16x16x32_bf16 v[116:119], v[168:171], v[184:187], v[116:119]
	v_mfma_f32_16x16x32_bf16 v[112:115], v[176:179], v[184:187], v[112:115]
	v_mfma_f32_16x16x32_bf16 v[100:103], v[168:171], v[192:195], v[100:103]
	v_mfma_f32_16x16x32_bf16 v[96:99], v[176:179], v[192:195], v[96:99]
	v_mfma_f32_16x16x32_bf16 v[84:87], v[168:171], v[200:203], v[84:87]
	v_mfma_f32_16x16x32_bf16 v[80:83], v[176:179], v[200:203], v[80:83]
	v_mfma_f32_16x16x32_bf16 v[68:71], v[168:171], v[212:215], v[68:71]
	v_mfma_f32_16x16x32_bf16 v[64:67], v[176:179], v[212:215], v[64:67]
	v_mfma_f32_16x16x32_bf16 v[116:119], v[172:175], v[188:191], v[116:119]
	v_mfma_f32_16x16x32_bf16 v[112:115], v[180:183], v[188:191], v[112:115]
	v_mfma_f32_16x16x32_bf16 v[100:103], v[172:175], v[196:199], v[100:103]
	v_mfma_f32_16x16x32_bf16 v[96:99], v[180:183], v[196:199], v[96:99]
	v_mfma_f32_16x16x32_bf16 v[84:87], v[172:175], v[208:211], v[84:87]
	v_mfma_f32_16x16x32_bf16 v[80:83], v[180:183], v[208:211], v[80:83]
	v_mfma_f32_16x16x32_bf16 v[68:71], v[172:175], v[216:219], v[68:71]
	v_mfma_f32_16x16x32_bf16 v[64:67], v[180:183], v[216:219], v[64:67]
	s_barrier
	s_add_i32 s28, s54, s38
	s_mov_b32 m0, s28
	s_nop 0
	global_load_lds_dwordx4 v205, s[26:27]
	s_add_i32 m0, s28, 0x2000
	s_add_u32 s26, s26, 0x40080
	s_addc_u32 s27, s27, 0
	s_add_i32 s28, s55, s38
	global_load_lds_dwordx4 v221, s[98:99]
	s_mov_b32 m0, s28
	s_nop 0
	global_load_lds_dwordx4 v130, s[26:27]
	s_add_i32 m0, s28, 0x2000
	s_nop 0
	global_load_lds_dwordx4 v134, s[26:27]
	s_cmp_lg_u32 s53, 12
	s_cbranch_scc1 .Lbal_last_13
	s_mov_b32 m0, s44
	s_nop 0
	global_load_lds_dwordx4 v204, s[100:101]
	s_mov_b32 m0, s45
	s_nop 0
	global_load_lds_dwordx4 v220, s[100:101]
.Lbal_last_13:
	ds_read_b128 v[184:187], v153 offset:49152
	ds_read_b128 v[188:191], v153 offset:50176
	ds_read_b128 v[192:195], v153 offset:51200
	ds_read_b128 v[196:199], v153 offset:52224
	ds_read_b128 v[200:203], v153 offset:53248
	ds_read_b128 v[208:211], v153 offset:54272
	ds_read_b128 v[212:215], v153 offset:55296
	ds_read_b128 v[216:219], v153 offset:56320
	s_waitcnt vmcnt(6)
	s_waitcnt lgkmcnt(0)
	s_barrier
	v_mfma_f32_16x16x32_bf16 v[60:63], v[144:147], v[184:187], v[60:63]
	v_mfma_f32_16x16x32_bf16 v[56:59], v[160:163], v[184:187], v[56:59]
	v_mfma_f32_16x16x32_bf16 v[44:47], v[144:147], v[192:195], v[44:47]
	v_mfma_f32_16x16x32_bf16 v[40:43], v[160:163], v[192:195], v[40:43]
	s_add_i32 s53, s53, 2
	s_add_u32 s51, s51, 0x100
	s_addc_u32 s52, s52, 0
	s_add_u32 s24, s24, 0x100
	s_addc_u32 s25, s25, 0
	s_cmp_gt_u32 s53, 13
	v_mfma_f32_16x16x32_bf16 v[28:31], v[144:147], v[200:203], v[28:31]
	v_mfma_f32_16x16x32_bf16 v[24:27], v[160:163], v[200:203], v[24:27]
	v_mfma_f32_16x16x32_bf16 v[12:15], v[144:147], v[212:215], v[12:15]
	v_mfma_f32_16x16x32_bf16 v[8:11], v[160:163], v[212:215], v[8:11]
	v_mfma_f32_16x16x32_bf16 v[60:63], v[156:159], v[188:191], v[60:63]
	v_mfma_f32_16x16x32_bf16 v[56:59], v[164:167], v[188:191], v[56:59]
	v_mfma_f32_16x16x32_bf16 v[44:47], v[156:159], v[196:199], v[44:47]
	v_mfma_f32_16x16x32_bf16 v[40:43], v[164:167], v[196:199], v[40:43]
	v_mfma_f32_16x16x32_bf16 v[28:31], v[156:159], v[208:211], v[28:31]
	v_mfma_f32_16x16x32_bf16 v[24:27], v[164:167], v[208:211], v[24:27]
	v_mfma_f32_16x16x32_bf16 v[12:15], v[156:159], v[216:219], v[12:15]
	v_mfma_f32_16x16x32_bf16 v[8:11], v[164:167], v[216:219], v[8:11]
	v_mfma_f32_16x16x32_bf16 v[52:55], v[168:171], v[184:187], v[52:55]
	v_mfma_f32_16x16x32_bf16 v[48:51], v[176:179], v[184:187], v[48:51]
	v_mfma_f32_16x16x32_bf16 v[36:39], v[168:171], v[192:195], v[36:39]
	v_mfma_f32_16x16x32_bf16 v[32:35], v[176:179], v[192:195], v[32:35]
	v_mfma_f32_16x16x32_bf16 v[20:23], v[168:171], v[200:203], v[20:23]
	v_mfma_f32_16x16x32_bf16 v[16:19], v[176:179], v[200:203], v[16:19]
	v_mfma_f32_16x16x32_bf16 v[4:7], v[168:171], v[212:215], v[4:7]
	v_mfma_f32_16x16x32_bf16 v[0:3], v[176:179], v[212:215], v[0:3]
	v_mfma_f32_16x16x32_bf16 v[52:55], v[172:175], v[188:191], v[52:55]
	v_mfma_f32_16x16x32_bf16 v[48:51], v[180:183], v[188:191], v[48:51]
	v_mfma_f32_16x16x32_bf16 v[36:39], v[172:175], v[196:199], v[36:39]
	v_mfma_f32_16x16x32_bf16 v[32:35], v[180:183], v[196:199], v[32:35]
	v_mfma_f32_16x16x32_bf16 v[20:23], v[172:175], v[208:211], v[20:23]
	v_mfma_f32_16x16x32_bf16 v[16:19], v[180:183], v[208:211], v[16:19]
	v_mfma_f32_16x16x32_bf16 v[4:7], v[172:175], v[216:219], v[4:7]
	v_mfma_f32_16x16x32_bf16 v[0:3], v[180:183], v[216:219], v[0:3]
	s_barrier
	s_cbranch_scc0 .LBB0_1365
	s_setprio 0
	s_and_b64 vcc, exec, s[14:15]
	s_cbranch_vccz .LBB0_1368
	s_barrier

.LBB0_1483:
	ds_read_b128 v[0:3], v139
	ds_read_b128 v[4:7], v139 offset:1024
	ds_read_b128 v[8:11], v139 offset:2048
	ds_read_b128 v[12:15], v139 offset:3072
	ds_read_b128 v[16:19], v140
	ds_read_b128 v[20:23], v140 offset:1024
	ds_read_b128 v[24:27], v140 offset:2048
	ds_read_b128 v[28:31], v140 offset:3072
	s_ashr_i32 s29, s28, 31
	s_lshl_b64 s[30:31], s[28:29], 17
	s_add_u32 s30, s46, s30
	s_addc_u32 s31, s47, s31
	s_and_b64 s[34:35], s[4:5], exec
	s_cselect_b32 s45, s31, s39
	s_cselect_b32 s44, s30, s38
	s_ashr_i32 s27, s26, 31
	s_lshl_b64 s[34:35], s[26:27], 17
	s_add_u32 s34, s48, s34
	s_addc_u32 s35, s49, s35
	s_and_b64 s[42:43], s[4:5], exec
	s_cselect_b32 s43, s35, s41
	s_cselect_b32 s42, s34, s40
	s_add_u32 s64, s38, 0x10080
	s_addc_u32 s65, s39, 0
	s_add_i32 s67, s37, 0xc000
	v_lshl_add_u64 v[64:65], s[64:65], 0, v[128:129]
	s_mov_b32 m0, s67
	s_add_i32 s27, s37, 0xe000
	ds_read_b128 v[32:35], v141
	ds_read_b128 v[36:39], v141 offset:1024
	ds_read_b128 v[40:43], v141 offset:2048
	ds_read_b128 v[44:47], v141 offset:3072
	ds_read_b128 v[48:51], v141 offset:4096
	ds_read_b128 v[52:55], v141 offset:5120
	ds_read_b128 v[56:59], v141 offset:6144
	ds_read_b128 v[60:63], v141 offset:7168
	global_load_lds_dwordx4 v[64:65], off
	v_lshl_add_u64 v[64:65], s[64:65], 0, v[130:131]
	s_mov_b32 m0, s27
	s_nop 0
	global_load_lds_dwordx4 v[64:65], off
	s_waitcnt vmcnt(8)
	s_waitcnt lgkmcnt(0)
	s_barrier
	v_mfma_f32_16x16x32_bf16 v[64:67], v[0:3], v[32:35], 0
	v_mfma_f32_16x16x32_bf16 v[68:71], v[8:11], v[32:35], 0
	v_mfma_f32_16x16x32_bf16 v[72:75], v[0:3], v[40:43], 0
	v_mfma_f32_16x16x32_bf16 v[76:79], v[8:11], v[40:43], 0
	v_mfma_f32_16x16x32_bf16 v[80:83], v[0:3], v[48:51], 0
	v_mfma_f32_16x16x32_bf16 v[84:87], v[8:11], v[48:51], 0
	v_mfma_f32_16x16x32_bf16 v[88:91], v[0:3], v[56:59], 0
	v_mfma_f32_16x16x32_bf16 v[92:95], v[8:11], v[56:59], 0
	v_mfma_f32_16x16x32_bf16 v[64:67], v[4:7], v[36:39], v[64:67]
	v_mfma_f32_16x16x32_bf16 v[68:71], v[12:15], v[36:39], v[68:71]
	v_mfma_f32_16x16x32_bf16 v[72:75], v[4:7], v[44:47], v[72:75]
	v_mfma_f32_16x16x32_bf16 v[76:79], v[12:15], v[44:47], v[76:79]
	v_mfma_f32_16x16x32_bf16 v[80:83], v[4:7], v[52:55], v[80:83]
	v_mfma_f32_16x16x32_bf16 v[84:87], v[12:15], v[52:55], v[84:87]
	v_mfma_f32_16x16x32_bf16 v[88:91], v[4:7], v[60:63], v[88:91]
	v_mfma_f32_16x16x32_bf16 v[92:95], v[12:15], v[60:63], v[92:95]
	v_mfma_f32_16x16x32_bf16 v[96:99], v[16:19], v[32:35], 0
	v_mfma_f32_16x16x32_bf16 v[32:35], v[24:27], v[32:35], 0
	v_mfma_f32_16x16x32_bf16 v[96:99], v[20:23], v[36:39], v[96:99]
	v_mfma_f32_16x16x32_bf16 v[32:35], v[28:31], v[36:39], v[32:35]
	v_mfma_f32_16x16x32_bf16 v[36:39], v[16:19], v[40:43], 0
	v_mfma_f32_16x16x32_bf16 v[40:43], v[24:27], v[40:43], 0
	v_mfma_f32_16x16x32_bf16 v[36:39], v[20:23], v[44:47], v[36:39]
	v_mfma_f32_16x16x32_bf16 v[40:43], v[28:31], v[44:47], v[40:43]
	v_mfma_f32_16x16x32_bf16 v[44:47], v[16:19], v[48:51], 0
	v_mfma_f32_16x16x32_bf16 v[48:51], v[24:27], v[48:51], 0
	v_mfma_f32_16x16x32_bf16 v[44:47], v[20:23], v[52:55], v[44:47]
	v_mfma_f32_16x16x32_bf16 v[48:51], v[28:31], v[52:55], v[48:51]
	v_mfma_f32_16x16x32_bf16 v[52:55], v[16:19], v[56:59], 0
	v_mfma_f32_16x16x32_bf16 v[56:59], v[24:27], v[56:59], 0
	v_mfma_f32_16x16x32_bf16 v[52:55], v[20:23], v[60:63], v[52:55]
	v_mfma_f32_16x16x32_bf16 v[56:59], v[28:31], v[60:63], v[56:59]
	s_barrier
	s_add_i32 s65, s56, s50
	v_lshl_add_u64 v[208:209], s[40:41], 0, v[128:129]
	s_add_i32 s29, s65, 0x2000
	v_lshl_add_u64 v[142:143], v[208:209], 0, s[14:15]
	s_mov_b32 m0, s65
	v_lshl_add_u64 v[210:211], s[40:41], 0, v[130:131]
	s_add_u32 s68, s40, 0x10100
	ds_read_b128 v[60:63], v141 offset:16384
	ds_read_b128 v[100:103], v141 offset:17408
	ds_read_b128 v[104:107], v141 offset:18432
	ds_read_b128 v[108:111], v141 offset:19456
	ds_read_b128 v[112:115], v141 offset:20480
	ds_read_b128 v[116:119], v141 offset:21504
	ds_read_b128 v[120:123], v141 offset:22528
	ds_read_b128 v[124:127], v141 offset:23552
	global_load_lds_dwordx4 v[142:143], off
	v_lshl_add_u64 v[142:143], v[210:211], 0, s[14:15]
	s_mov_b32 m0, s29
	s_addc_u32 s69, s41, 0
	s_add_i32 s63, s57, s50
	global_load_lds_dwordx4 v[142:143], off
	v_lshl_add_u64 v[142:143], s[68:69], 0, v[128:129]
	s_mov_b32 m0, s63
	s_add_i32 s64, s63, 0x2000
	global_load_lds_dwordx4 v[142:143], off
	v_lshl_add_u64 v[142:143], s[68:69], 0, v[130:131]
	s_mov_b32 m0, s64
	v_lshl_add_u64 v[212:213], s[38:39], 0, v[128:129]
	global_load_lds_dwordx4 v[142:143], off
	v_lshl_add_u64 v[142:143], v[212:213], 0, s[14:15]
	s_mov_b32 m0, s37
	v_lshl_add_u64 v[214:215], s[38:39], 0, v[130:131]
	global_load_lds_dwordx4 v[142:143], off
	v_lshl_add_u64 v[142:143], v[214:215], 0, s[14:15]
	s_mov_b32 m0, s51
	s_nop 0
	global_load_lds_dwordx4 v[142:143], off
	s_waitcnt vmcnt(8)
	s_waitcnt lgkmcnt(0)
	s_barrier
	v_mfma_f32_16x16x32_bf16 v[142:145], v[0:3], v[60:63], 0
	v_mfma_f32_16x16x32_bf16 v[150:153], v[0:3], v[104:107], 0
	v_mfma_f32_16x16x32_bf16 v[158:161], v[0:3], v[112:115], 0
	v_mfma_f32_16x16x32_bf16 v[0:3], v[0:3], v[120:123], 0
	v_mfma_f32_16x16x32_bf16 v[142:145], v[4:7], v[100:103], v[142:145]
	v_mfma_f32_16x16x32_bf16 v[150:153], v[4:7], v[108:111], v[150:153]
	v_mfma_f32_16x16x32_bf16 v[158:161], v[4:7], v[116:119], v[158:161]
	v_mfma_f32_16x16x32_bf16 v[0:3], v[4:7], v[124:127], v[0:3]
	v_mfma_f32_16x16x32_bf16 v[4:7], v[8:11], v[120:123], 0
	v_mfma_f32_16x16x32_bf16 v[146:149], v[8:11], v[60:63], 0
	v_mfma_f32_16x16x32_bf16 v[154:157], v[8:11], v[104:107], 0
	v_mfma_f32_16x16x32_bf16 v[162:165], v[8:11], v[112:115], 0
	v_mfma_f32_16x16x32_bf16 v[4:7], v[12:15], v[124:127], v[4:7]
	v_mfma_f32_16x16x32_bf16 v[146:149], v[12:15], v[100:103], v[146:149]
	v_mfma_f32_16x16x32_bf16 v[154:157], v[12:15], v[108:111], v[154:157]
	v_mfma_f32_16x16x32_bf16 v[162:165], v[12:15], v[116:119], v[162:165]
	v_mfma_f32_16x16x32_bf16 v[8:11], v[16:19], v[60:63], 0
	v_mfma_f32_16x16x32_bf16 v[12:15], v[24:27], v[60:63], 0
	v_mfma_f32_16x16x32_bf16 v[8:11], v[20:23], v[100:103], v[8:11]
	v_mfma_f32_16x16x32_bf16 v[12:15], v[28:31], v[100:103], v[12:15]
	v_mfma_f32_16x16x32_bf16 v[60:63], v[16:19], v[104:107], 0
	v_mfma_f32_16x16x32_bf16 v[100:103], v[24:27], v[104:107], 0
	v_mfma_f32_16x16x32_bf16 v[104:107], v[16:19], v[112:115], 0
	v_mfma_f32_16x16x32_bf16 v[16:19], v[16:19], v[120:123], 0
	v_mfma_f32_16x16x32_bf16 v[60:63], v[20:23], v[108:111], v[60:63]
	v_mfma_f32_16x16x32_bf16 v[100:103], v[28:31], v[108:111], v[100:103]
	v_mfma_f32_16x16x32_bf16 v[104:107], v[20:23], v[116:119], v[104:107]
	v_mfma_f32_16x16x32_bf16 v[108:111], v[24:27], v[112:115], 0
	v_mfma_f32_16x16x32_bf16 v[16:19], v[20:23], v[124:127], v[16:19]
	v_mfma_f32_16x16x32_bf16 v[20:23], v[24:27], v[120:123], 0
	v_mfma_f32_16x16x32_bf16 v[108:111], v[28:31], v[116:119], v[108:111]
	v_mfma_f32_16x16x32_bf16 v[20:23], v[28:31], v[124:127], v[20:23]
	s_barrier
	s_add_i32 s66, 0, 0x18000
	s_add_i32 s72, 0, 0x1c000
	v_add_u32_e32 v220, s66, v137
	v_add_u32_e32 v228, s72, v137
	ds_read_b128 v[24:27], v220
	ds_read_b128 v[28:31], v220 offset:1024
	ds_read_b128 v[112:115], v220 offset:2048
	ds_read_b128 v[116:119], v220 offset:3072
	ds_read_b128 v[120:123], v228
	ds_read_b128 v[124:127], v228 offset:1024
	ds_read_b128 v[166:169], v228 offset:2048
	ds_read_b128 v[170:173], v228 offset:3072
	s_add_u32 s68, s38, 0x10100
	s_addc_u32 s69, s39, 0
	s_mov_b32 m0, s52
	v_lshl_add_u64 v[216:217], s[68:69], 0, v[128:129]
	ds_read_b128 v[174:177], v141 offset:32768
	ds_read_b128 v[178:181], v141 offset:33792
	ds_read_b128 v[182:185], v141 offset:34816
	ds_read_b128 v[186:189], v141 offset:35840
	ds_read_b128 v[190:193], v141 offset:36864
	ds_read_b128 v[194:197], v141 offset:37888
	ds_read_b128 v[198:201], v141 offset:38912
	ds_read_b128 v[202:205], v141 offset:39936
	global_load_lds_dwordx4 v[216:217], off
	v_lshl_add_u64 v[216:217], s[68:69], 0, v[130:131]
	s_mov_b32 m0, s53
	s_nop 0
	global_load_lds_dwordx4 v[216:217], off
	s_waitcnt vmcnt(8)
	s_waitcnt lgkmcnt(0)
	s_barrier
	v_mfma_f32_16x16x32_bf16 v[64:67], v[24:27], v[174:177], v[64:67]
	v_mfma_f32_16x16x32_bf16 v[68:71], v[112:115], v[174:177], v[68:71]
	v_mfma_f32_16x16x32_bf16 v[72:75], v[24:27], v[182:185], v[72:75]
	v_mfma_f32_16x16x32_bf16 v[76:79], v[112:115], v[182:185], v[76:79]
	v_mfma_f32_16x16x32_bf16 v[80:83], v[24:27], v[190:193], v[80:83]
	v_mfma_f32_16x16x32_bf16 v[84:87], v[112:115], v[190:193], v[84:87]
	v_mfma_f32_16x16x32_bf16 v[88:91], v[24:27], v[198:201], v[88:91]
	v_mfma_f32_16x16x32_bf16 v[92:95], v[112:115], v[198:201], v[92:95]
	v_mfma_f32_16x16x32_bf16 v[64:67], v[28:31], v[178:181], v[64:67]
	v_mfma_f32_16x16x32_bf16 v[68:71], v[116:119], v[178:181], v[68:71]
	v_mfma_f32_16x16x32_bf16 v[72:75], v[28:31], v[186:189], v[72:75]
	v_mfma_f32_16x16x32_bf16 v[76:79], v[116:119], v[186:189], v[76:79]
	v_mfma_f32_16x16x32_bf16 v[80:83], v[28:31], v[194:197], v[80:83]
	v_mfma_f32_16x16x32_bf16 v[84:87], v[116:119], v[194:197], v[84:87]
	v_mfma_f32_16x16x32_bf16 v[88:91], v[28:31], v[202:205], v[88:91]
	v_mfma_f32_16x16x32_bf16 v[92:95], v[116:119], v[202:205], v[92:95]
	v_mfma_f32_16x16x32_bf16 v[96:99], v[120:123], v[174:177], v[96:99]
	v_mfma_f32_16x16x32_bf16 v[32:35], v[166:169], v[174:177], v[32:35]
	v_mfma_f32_16x16x32_bf16 v[36:39], v[120:123], v[182:185], v[36:39]
	v_mfma_f32_16x16x32_bf16 v[40:43], v[166:169], v[182:185], v[40:43]
	v_mfma_f32_16x16x32_bf16 v[44:47], v[120:123], v[190:193], v[44:47]
	v_mfma_f32_16x16x32_bf16 v[48:51], v[166:169], v[190:193], v[48:51]
	v_mfma_f32_16x16x32_bf16 v[52:55], v[120:123], v[198:201], v[52:55]
	v_mfma_f32_16x16x32_bf16 v[56:59], v[166:169], v[198:201], v[56:59]
	v_mfma_f32_16x16x32_bf16 v[96:99], v[124:127], v[178:181], v[96:99]
	v_mfma_f32_16x16x32_bf16 v[32:35], v[170:173], v[178:181], v[32:35]
	v_mfma_f32_16x16x32_bf16 v[36:39], v[124:127], v[186:189], v[36:39]
	v_mfma_f32_16x16x32_bf16 v[40:43], v[170:173], v[186:189], v[40:43]
	v_mfma_f32_16x16x32_bf16 v[44:47], v[124:127], v[194:197], v[44:47]
	v_mfma_f32_16x16x32_bf16 v[48:51], v[170:173], v[194:197], v[48:51]
	v_mfma_f32_16x16x32_bf16 v[52:55], v[124:127], v[202:205], v[52:55]
	v_mfma_f32_16x16x32_bf16 v[56:59], v[170:173], v[202:205], v[56:59]
	s_barrier
	s_add_i32 s68, s66, s50
	s_add_i32 s66, s68, 0x2000
	v_lshl_add_u64 v[208:209], v[208:209], 0, s[16:17]
	s_mov_b32 m0, s68
	s_add_u32 s70, s40, 0x10180
	ds_read_b128 v[174:177], v141 offset:49152
	ds_read_b128 v[178:181], v141 offset:50176
	ds_read_b128 v[182:185], v141 offset:51200
	ds_read_b128 v[186:189], v141 offset:52224
	ds_read_b128 v[190:193], v141 offset:53248
	ds_read_b128 v[194:197], v141 offset:54272
	ds_read_b128 v[198:201], v141 offset:55296
	ds_read_b128 v[202:205], v141 offset:56320
	global_load_lds_dwordx4 v[208:209], off
	v_lshl_add_u64 v[208:209], v[210:211], 0, s[16:17]
	s_mov_b32 m0, s66
	s_addc_u32 s71, s41, 0
	s_add_i32 s40, s72, s50
	global_load_lds_dwordx4 v[208:209], off
	v_lshl_add_u64 v[208:209], s[70:71], 0, v[128:129]
	s_mov_b32 m0, s40
	s_add_i32 s41, s40, 0x2000
	global_load_lds_dwordx4 v[208:209], off
	v_lshl_add_u64 v[208:209], s[70:71], 0, v[130:131]
	s_mov_b32 m0, s41
	s_nop 0
	global_load_lds_dwordx4 v[208:209], off
	v_lshl_add_u64 v[208:209], v[212:213], 0, s[16:17]
	s_mov_b32 m0, s54
	s_nop 0
	global_load_lds_dwordx4 v[208:209], off
	v_lshl_add_u64 v[208:209], v[214:215], 0, s[16:17]
	s_mov_b32 m0, s55
	s_nop 0
	global_load_lds_dwordx4 v[208:209], off
	s_waitcnt vmcnt(8)
	s_waitcnt lgkmcnt(0)
	s_barrier
	v_mfma_f32_16x16x32_bf16 v[0:3], v[24:27], v[198:201], v[0:3]
	v_mfma_f32_16x16x32_bf16 v[4:7], v[112:115], v[198:201], v[4:7]
	v_mfma_f32_16x16x32_bf16 v[142:145], v[24:27], v[174:177], v[142:145]
	v_mfma_f32_16x16x32_bf16 v[146:149], v[112:115], v[174:177], v[146:149]
	v_mfma_f32_16x16x32_bf16 v[150:153], v[24:27], v[182:185], v[150:153]
	v_mfma_f32_16x16x32_bf16 v[154:157], v[112:115], v[182:185], v[154:157]
	v_mfma_f32_16x16x32_bf16 v[158:161], v[24:27], v[190:193], v[158:161]
	v_mfma_f32_16x16x32_bf16 v[162:165], v[112:115], v[190:193], v[162:165]
	v_mfma_f32_16x16x32_bf16 v[0:3], v[28:31], v[202:205], v[0:3]
	v_mfma_f32_16x16x32_bf16 v[4:7], v[116:119], v[202:205], v[4:7]
	v_mfma_f32_16x16x32_bf16 v[142:145], v[28:31], v[178:181], v[142:145]
	v_mfma_f32_16x16x32_bf16 v[146:149], v[116:119], v[178:181], v[146:149]
	v_mfma_f32_16x16x32_bf16 v[150:153], v[28:31], v[186:189], v[150:153]
	v_mfma_f32_16x16x32_bf16 v[154:157], v[116:119], v[186:189], v[154:157]
	v_mfma_f32_16x16x32_bf16 v[158:161], v[28:31], v[194:197], v[158:161]
	v_mfma_f32_16x16x32_bf16 v[162:165], v[116:119], v[194:197], v[162:165]
	v_mfma_f32_16x16x32_bf16 v[8:11], v[120:123], v[174:177], v[8:11]
	v_mfma_f32_16x16x32_bf16 v[12:15], v[166:169], v[174:177], v[12:15]
	v_mfma_f32_16x16x32_bf16 v[24:27], v[120:123], v[182:185], v[60:63]
	v_mfma_f32_16x16x32_bf16 v[28:31], v[166:169], v[182:185], v[100:103]
	v_mfma_f32_16x16x32_bf16 v[60:63], v[120:123], v[190:193], v[104:107]
	v_mfma_f32_16x16x32_bf16 v[100:103], v[166:169], v[190:193], v[108:111]
	v_mfma_f32_16x16x32_bf16 v[16:19], v[120:123], v[198:201], v[16:19]
	v_mfma_f32_16x16x32_bf16 v[20:23], v[166:169], v[198:201], v[20:23]
	v_mfma_f32_16x16x32_bf16 v[8:11], v[124:127], v[178:181], v[8:11]
	v_mfma_f32_16x16x32_bf16 v[12:15], v[170:173], v[178:181], v[12:15]
	v_mfma_f32_16x16x32_bf16 v[24:27], v[124:127], v[186:189], v[24:27]
	v_mfma_f32_16x16x32_bf16 v[28:31], v[170:173], v[186:189], v[28:31]
	v_mfma_f32_16x16x32_bf16 v[60:63], v[124:127], v[194:197], v[60:63]
	v_mfma_f32_16x16x32_bf16 v[100:103], v[170:173], v[194:197], v[100:103]
	v_mfma_f32_16x16x32_bf16 v[16:19], v[124:127], v[202:205], v[16:19]
	v_mfma_f32_16x16x32_bf16 v[20:23], v[170:173], v[202:205], v[20:23]
	s_barrier
	ds_read_b128 v[104:107], v139
	ds_read_b128 v[108:111], v139 offset:1024
	ds_read_b128 v[112:115], v139 offset:2048
	ds_read_b128 v[116:119], v139 offset:3072
	ds_read_b128 v[120:123], v140
	ds_read_b128 v[124:127], v140 offset:1024
	ds_read_b128 v[166:169], v140 offset:2048
	ds_read_b128 v[170:173], v140 offset:3072
	s_add_u32 s38, s38, 0x10180
	s_addc_u32 s39, s39, 0
	s_mov_b32 m0, s67
	v_lshl_add_u64 v[208:209], s[38:39], 0, v[128:129]
	ds_read_b128 v[174:177], v141
	ds_read_b128 v[178:181], v141 offset:1024
	ds_read_b128 v[182:185], v141 offset:2048
	ds_read_b128 v[186:189], v141 offset:3072
	ds_read_b128 v[190:193], v141 offset:4096
	ds_read_b128 v[194:197], v141 offset:5120
	ds_read_b128 v[198:201], v141 offset:6144
	ds_read_b128 v[202:205], v141 offset:7168
	global_load_lds_dwordx4 v[208:209], off
	v_lshl_add_u64 v[208:209], s[38:39], 0, v[130:131]
	s_mov_b32 m0, s27
	s_nop 0
	global_load_lds_dwordx4 v[208:209], off
	s_waitcnt vmcnt(8)
	s_waitcnt lgkmcnt(0)
	s_barrier
	v_mfma_f32_16x16x32_bf16 v[64:67], v[104:107], v[174:177], v[64:67]
	v_mfma_f32_16x16x32_bf16 v[68:71], v[112:115], v[174:177], v[68:71]
	v_mfma_f32_16x16x32_bf16 v[72:75], v[104:107], v[182:185], v[72:75]
	v_mfma_f32_16x16x32_bf16 v[76:79], v[112:115], v[182:185], v[76:79]
	v_mfma_f32_16x16x32_bf16 v[80:83], v[104:107], v[190:193], v[80:83]
	v_mfma_f32_16x16x32_bf16 v[84:87], v[112:115], v[190:193], v[84:87]
	v_mfma_f32_16x16x32_bf16 v[88:91], v[104:107], v[198:201], v[88:91]
	v_mfma_f32_16x16x32_bf16 v[64:67], v[108:111], v[178:181], v[64:67]
	v_mfma_f32_16x16x32_bf16 v[68:71], v[116:119], v[178:181], v[68:71]
	v_mfma_f32_16x16x32_bf16 v[72:75], v[108:111], v[186:189], v[72:75]
	v_mfma_f32_16x16x32_bf16 v[76:79], v[116:119], v[186:189], v[76:79]
	v_mfma_f32_16x16x32_bf16 v[80:83], v[108:111], v[194:197], v[80:83]
	v_mfma_f32_16x16x32_bf16 v[84:87], v[116:119], v[194:197], v[84:87]
	v_mfma_f32_16x16x32_bf16 v[88:91], v[108:111], v[202:205], v[88:91]
	v_mfma_f32_16x16x32_bf16 v[92:95], v[112:115], v[198:201], v[92:95]
	v_mfma_f32_16x16x32_bf16 v[208:211], v[116:119], v[202:205], v[92:95]
	v_mfma_f32_16x16x32_bf16 v[48:51], v[166:169], v[190:193], v[48:51]
	v_mfma_f32_16x16x32_bf16 v[92:95], v[120:123], v[174:177], v[96:99]
	v_mfma_f32_16x16x32_bf16 v[32:35], v[166:169], v[174:177], v[32:35]
	v_mfma_f32_16x16x32_bf16 v[36:39], v[120:123], v[182:185], v[36:39]
	v_mfma_f32_16x16x32_bf16 v[40:43], v[166:169], v[182:185], v[40:43]
	v_mfma_f32_16x16x32_bf16 v[44:47], v[120:123], v[190:193], v[44:47]
	v_mfma_f32_16x16x32_bf16 v[174:177], v[170:173], v[194:197], v[48:51]
	v_mfma_f32_16x16x32_bf16 v[48:51], v[120:123], v[198:201], v[52:55]
	v_mfma_f32_16x16x32_bf16 v[32:35], v[170:173], v[178:181], v[32:35]
	v_mfma_f32_16x16x32_bf16 v[36:39], v[124:127], v[186:189], v[36:39]
	v_mfma_f32_16x16x32_bf16 v[40:43], v[170:173], v[186:189], v[40:43]
	v_mfma_f32_16x16x32_bf16 v[44:47], v[124:127], v[194:197], v[44:47]
	v_mfma_f32_16x16x32_bf16 v[52:55], v[124:127], v[202:205], v[48:51]
	v_mfma_f32_16x16x32_bf16 v[48:51], v[166:169], v[198:201], v[56:59]
	v_mfma_f32_16x16x32_bf16 v[212:215], v[124:127], v[178:181], v[92:95]
	v_mfma_f32_16x16x32_bf16 v[178:181], v[170:173], v[202:205], v[48:51]
	s_barrier
	s_mov_b32 m0, s65
	v_lshl_add_u64 v[248:249], s[42:43], 0, v[128:129]
	s_add_u32 s38, s42, 0x10000
	s_nop 0
	ds_read_b128 v[48:51], v141 offset:16384
	ds_read_b128 v[56:59], v141 offset:17408
	ds_read_b128 v[92:95], v141 offset:18432
	ds_read_b128 v[96:99], v141 offset:19456
	ds_read_b128 v[182:185], v141 offset:20480
	ds_read_b128 v[186:189], v141 offset:21504
	ds_read_b128 v[190:193], v141 offset:22528
	ds_read_b128 v[194:197], v141 offset:23552
	global_load_lds_dwordx4 v[248:249], off
	v_lshl_add_u64 v[250:251], s[42:43], 0, v[130:131]
	s_mov_b32 m0, s29
	s_addc_u32 s39, s43, 0
	global_load_lds_dwordx4 v[250:251], off
	v_lshl_add_u64 v[198:199], s[38:39], 0, v[128:129]
	s_mov_b32 m0, s63
	v_lshl_add_u64 v[252:253], s[44:45], 0, v[128:129]
	global_load_lds_dwordx4 v[198:199], off
	v_lshl_add_u64 v[198:199], s[38:39], 0, v[130:131]
	s_mov_b32 m0, s64
	v_lshl_add_u64 v[132:133], s[44:45], 0, v[130:131]
	global_load_lds_dwordx4 v[198:199], off
	s_mov_b32 m0, s37
	s_nop 0
	global_load_lds_dwordx4 v[252:253], off
	s_mov_b32 m0, s51
	s_nop 0
	global_load_lds_dwordx4 v[132:133], off
	s_waitcnt vmcnt(8)
	s_waitcnt lgkmcnt(0)
	s_barrier
	v_mfma_f32_16x16x32_bf16 v[0:3], v[104:107], v[190:193], v[0:3]
	v_mfma_f32_16x16x32_bf16 v[4:7], v[112:115], v[190:193], v[4:7]
	v_mfma_f32_16x16x32_bf16 v[142:145], v[104:107], v[48:51], v[142:145]
	v_mfma_f32_16x16x32_bf16 v[146:149], v[112:115], v[48:51], v[146:149]
	v_mfma_f32_16x16x32_bf16 v[150:153], v[104:107], v[92:95], v[150:153]
	v_mfma_f32_16x16x32_bf16 v[154:157], v[112:115], v[92:95], v[154:157]
	v_mfma_f32_16x16x32_bf16 v[158:161], v[104:107], v[182:185], v[158:161]
	v_mfma_f32_16x16x32_bf16 v[162:165], v[112:115], v[182:185], v[162:165]
	v_mfma_f32_16x16x32_bf16 v[0:3], v[108:111], v[194:197], v[0:3]
	v_mfma_f32_16x16x32_bf16 v[4:7], v[116:119], v[194:197], v[4:7]
	v_mfma_f32_16x16x32_bf16 v[142:145], v[108:111], v[56:59], v[142:145]
	v_mfma_f32_16x16x32_bf16 v[146:149], v[116:119], v[56:59], v[146:149]
	v_mfma_f32_16x16x32_bf16 v[150:153], v[108:111], v[96:99], v[150:153]
	v_mfma_f32_16x16x32_bf16 v[154:157], v[116:119], v[96:99], v[154:157]
	v_mfma_f32_16x16x32_bf16 v[158:161], v[108:111], v[186:189], v[158:161]
	v_mfma_f32_16x16x32_bf16 v[162:165], v[116:119], v[186:189], v[162:165]
	v_mfma_f32_16x16x32_bf16 v[12:15], v[166:169], v[48:51], v[12:15]
	v_mfma_f32_16x16x32_bf16 v[198:201], v[170:173], v[56:59], v[12:15]
	v_mfma_f32_16x16x32_bf16 v[12:15], v[120:123], v[92:95], v[24:27]
	v_mfma_f32_16x16x32_bf16 v[24:27], v[124:127], v[96:99], v[12:15]
	v_mfma_f32_16x16x32_bf16 v[12:15], v[166:169], v[92:95], v[28:31]
	v_mfma_f32_16x16x32_bf16 v[202:205], v[170:173], v[96:99], v[12:15]
	v_mfma_f32_16x16x32_bf16 v[12:15], v[120:123], v[182:185], v[60:63]
	v_mfma_f32_16x16x32_bf16 v[216:219], v[124:127], v[186:189], v[12:15]
	v_mfma_f32_16x16x32_bf16 v[12:15], v[166:169], v[182:185], v[100:103]
	v_mfma_f32_16x16x32_bf16 v[8:11], v[120:123], v[48:51], v[8:11]
	v_mfma_f32_16x16x32_bf16 v[182:185], v[170:173], v[186:189], v[12:15]
	v_mfma_f32_16x16x32_bf16 v[12:15], v[120:123], v[190:193], v[16:19]
	v_mfma_f32_16x16x32_bf16 v[8:11], v[124:127], v[56:59], v[8:11]
	v_mfma_f32_16x16x32_bf16 v[186:189], v[124:127], v[194:197], v[12:15]
	v_mfma_f32_16x16x32_bf16 v[12:15], v[166:169], v[190:193], v[20:23]
	v_mfma_f32_16x16x32_bf16 v[166:169], v[170:173], v[194:197], v[12:15]
	s_barrier
	s_nop 4
	ds_read_b128 v[12:15], v220
	ds_read_b128 v[20:23], v220 offset:1024
	ds_read_b128 v[170:173], v220 offset:2048
	ds_read_b128 v[190:193], v220 offset:3072
	ds_read_b128 v[194:197], v228
	ds_read_b128 v[220:223], v228 offset:1024
	ds_read_b128 v[224:227], v228 offset:2048
	ds_read_b128 v[228:231], v228 offset:3072
	s_add_u32 s38, s44, 0x10000
	s_addc_u32 s39, s45, 0
	s_mov_b32 m0, s52
	v_lshl_add_u64 v[48:49], s[38:39], 0, v[128:129]
	ds_read_b128 v[16:19], v141 offset:32768
	ds_read_b128 v[28:31], v141 offset:33792
	ds_read_b128 v[56:59], v141 offset:34816
	ds_read_b128 v[100:103], v141 offset:35840
	ds_read_b128 v[232:235], v141 offset:36864
	ds_read_b128 v[236:239], v141 offset:37888
	ds_read_b128 v[240:243], v141 offset:38912
	ds_read_b128 v[244:247], v141 offset:39936
	global_load_lds_dwordx4 v[48:49], off
	v_lshl_add_u64 v[48:49], s[38:39], 0, v[130:131]
	s_mov_b32 m0, s53
	s_nop 0
	global_load_lds_dwordx4 v[48:49], off
	s_waitcnt vmcnt(8)
	s_waitcnt lgkmcnt(0)
	s_barrier
	v_mfma_f32_16x16x32_bf16 v[48:51], v[12:15], v[16:19], v[64:67]
	v_mfma_f32_16x16x32_bf16 v[124:127], v[20:23], v[28:31], v[48:51]
	v_mfma_f32_16x16x32_bf16 v[48:51], v[170:173], v[16:19], v[68:71]
	v_mfma_f32_16x16x32_bf16 v[112:115], v[190:193], v[28:31], v[48:51]
	v_mfma_f32_16x16x32_bf16 v[48:51], v[12:15], v[56:59], v[72:75]
	v_mfma_f32_16x16x32_bf16 v[108:111], v[20:23], v[100:103], v[48:51]
	v_mfma_f32_16x16x32_bf16 v[48:51], v[170:173], v[56:59], v[76:79]
	v_mfma_f32_16x16x32_bf16 v[96:99], v[190:193], v[100:103], v[48:51]
	v_mfma_f32_16x16x32_bf16 v[48:51], v[12:15], v[232:235], v[80:83]
	v_mfma_f32_16x16x32_bf16 v[92:95], v[20:23], v[236:239], v[48:51]
	v_mfma_f32_16x16x32_bf16 v[48:51], v[170:173], v[232:235], v[84:87]
	v_mfma_f32_16x16x32_bf16 v[80:83], v[190:193], v[236:239], v[48:51]
	v_mfma_f32_16x16x32_bf16 v[48:51], v[12:15], v[240:243], v[88:91]
	v_mfma_f32_16x16x32_bf16 v[60:63], v[20:23], v[244:247], v[48:51]
	v_mfma_f32_16x16x32_bf16 v[48:51], v[170:173], v[240:243], v[208:211]
	v_mfma_f32_16x16x32_bf16 v[48:51], v[190:193], v[244:247], v[48:51]
	v_mfma_f32_16x16x32_bf16 v[64:67], v[194:197], v[16:19], v[212:215]
	v_mfma_f32_16x16x32_bf16 v[16:19], v[224:227], v[16:19], v[32:35]
	v_mfma_f32_16x16x32_bf16 v[116:119], v[228:231], v[28:31], v[16:19]
	v_mfma_f32_16x16x32_bf16 v[16:19], v[194:197], v[56:59], v[36:39]
	v_mfma_f32_16x16x32_bf16 v[104:107], v[220:223], v[100:103], v[16:19]
	v_mfma_f32_16x16x32_bf16 v[16:19], v[224:227], v[56:59], v[40:43]
	v_mfma_f32_16x16x32_bf16 v[100:103], v[228:231], v[100:103], v[16:19]
	v_mfma_f32_16x16x32_bf16 v[16:19], v[194:197], v[232:235], v[44:47]
	v_mfma_f32_16x16x32_bf16 v[88:91], v[220:223], v[236:239], v[16:19]
	v_mfma_f32_16x16x32_bf16 v[16:19], v[224:227], v[232:235], v[174:177]
	v_mfma_f32_16x16x32_bf16 v[84:87], v[228:231], v[236:239], v[16:19]
	v_mfma_f32_16x16x32_bf16 v[16:19], v[194:197], v[240:243], v[52:55]
	v_mfma_f32_16x16x32_bf16 v[56:59], v[220:223], v[244:247], v[16:19]
	v_mfma_f32_16x16x32_bf16 v[16:19], v[224:227], v[240:243], v[178:181]
	v_mfma_f32_16x16x32_bf16 v[120:123], v[220:223], v[28:31], v[64:67]
	v_mfma_f32_16x16x32_bf16 v[52:55], v[228:231], v[244:247], v[16:19]
	s_barrier
	s_mov_b32 m0, s68
	s_nop 2
	v_lshl_add_u64 v[16:17], v[248:249], 0, s[8:9]
	s_add_u32 s38, s42, 0x10080
	ds_read_b128 v[36:39], v141 offset:49152
	ds_read_b128 v[40:43], v141 offset:50176
	ds_read_b128 v[174:177], v141 offset:51200
	ds_read_b128 v[178:181], v141 offset:52224
	ds_read_b128 v[208:211], v141 offset:53248
	ds_read_b128 v[212:215], v141 offset:54272
	ds_read_b128 v[232:235], v141 offset:55296
	ds_read_b128 v[236:239], v141 offset:56320
	global_load_lds_dwordx4 v[16:17], off
	v_lshl_add_u64 v[16:17], v[250:251], 0, s[8:9]
	s_mov_b32 m0, s66
	s_addc_u32 s39, s43, 0
	global_load_lds_dwordx4 v[16:17], off
	v_lshl_add_u64 v[16:17], s[38:39], 0, v[128:129]
	s_mov_b32 m0, s40
	s_nop 0
	global_load_lds_dwordx4 v[16:17], off
	v_lshl_add_u64 v[16:17], s[38:39], 0, v[130:131]
	s_mov_b32 m0, s41
	s_nop 0
	global_load_lds_dwordx4 v[16:17], off
	v_lshl_add_u64 v[16:17], v[252:253], 0, s[8:9]
	s_mov_b32 m0, s54
	s_nop 0
	global_load_lds_dwordx4 v[16:17], off
	v_lshl_add_u64 v[16:17], v[132:133], 0, s[8:9]
	s_mov_b32 m0, s55
	s_nop 0
	global_load_lds_dwordx4 v[16:17], off
	s_waitcnt vmcnt(8)
	s_waitcnt lgkmcnt(0)
	s_barrier
	v_mfma_f32_16x16x32_bf16 v[16:19], v[12:15], v[36:39], v[142:145]
	v_mfma_f32_16x16x32_bf16 v[76:79], v[20:23], v[40:43], v[16:19]
	v_mfma_f32_16x16x32_bf16 v[16:19], v[170:173], v[36:39], v[146:149]
	v_mfma_f32_16x16x32_bf16 v[64:67], v[190:193], v[40:43], v[16:19]
	v_mfma_f32_16x16x32_bf16 v[16:19], v[12:15], v[174:177], v[150:153]
	v_mfma_f32_16x16x32_bf16 v[44:47], v[20:23], v[178:181], v[16:19]
	v_mfma_f32_16x16x32_bf16 v[16:19], v[170:173], v[174:177], v[154:157]
	v_mfma_f32_16x16x32_bf16 v[32:35], v[190:193], v[178:181], v[16:19]
	v_mfma_f32_16x16x32_bf16 v[16:19], v[12:15], v[208:211], v[158:161]
	v_mfma_f32_16x16x32_bf16 v[0:3], v[12:15], v[232:235], v[0:3]
	v_mfma_f32_16x16x32_bf16 v[28:31], v[20:23], v[212:215], v[16:19]
	v_mfma_f32_16x16x32_bf16 v[16:19], v[170:173], v[208:211], v[162:165]
	v_mfma_f32_16x16x32_bf16 v[12:15], v[20:23], v[236:239], v[0:3]
	v_mfma_f32_16x16x32_bf16 v[0:3], v[170:173], v[232:235], v[4:7]
	v_mfma_f32_16x16x32_bf16 v[16:19], v[190:193], v[212:215], v[16:19]
	v_mfma_f32_16x16x32_bf16 v[0:3], v[190:193], v[236:239], v[0:3]
	v_mfma_f32_16x16x32_bf16 v[4:7], v[194:197], v[36:39], v[8:11]
	v_mfma_f32_16x16x32_bf16 v[72:75], v[220:223], v[40:43], v[4:7]
	v_mfma_f32_16x16x32_bf16 v[4:7], v[224:227], v[36:39], v[198:201]
	v_mfma_f32_16x16x32_bf16 v[68:71], v[228:231], v[40:43], v[4:7]
	v_mfma_f32_16x16x32_bf16 v[4:7], v[194:197], v[174:177], v[24:27]
	v_mfma_f32_16x16x32_bf16 v[40:43], v[220:223], v[178:181], v[4:7]
	v_mfma_f32_16x16x32_bf16 v[4:7], v[224:227], v[174:177], v[202:205]
	v_mfma_f32_16x16x32_bf16 v[36:39], v[228:231], v[178:181], v[4:7]
	v_mfma_f32_16x16x32_bf16 v[4:7], v[194:197], v[208:211], v[216:219]
	v_mfma_f32_16x16x32_bf16 v[24:27], v[220:223], v[212:215], v[4:7]
	v_mfma_f32_16x16x32_bf16 v[4:7], v[224:227], v[208:211], v[182:185]
	v_mfma_f32_16x16x32_bf16 v[20:23], v[228:231], v[212:215], v[4:7]
	v_mfma_f32_16x16x32_bf16 v[4:7], v[194:197], v[232:235], v[186:189]
	v_mfma_f32_16x16x32_bf16 v[8:11], v[220:223], v[236:239], v[4:7]
	v_mfma_f32_16x16x32_bf16 v[4:7], v[224:227], v[232:235], v[166:169]
	v_mfma_f32_16x16x32_bf16 v[4:7], v[228:231], v[236:239], v[4:7]
	s_barrier
	s_andn2_b64 vcc, exec, s[10:11]
	s_cbranch_vccnz .LBB0_1485
	s_barrier

.Lbal_first_11:
	s_add_u32 s38, s36, 0xfffc0080
	s_addc_u32 s39, s37, -1
	s_cmp_eq_u32 s61, 12
	s_cselect_b32 s41, s3, s39
	s_cselect_b32 s40, s29, s38
	s_cselect_b32 s39, s27, s60
	s_cselect_b32 s38, s58, s59
	s_add_i32 m0, s46, 0xc000
	s_nop 0
	global_load_lds_dwordx4 v134, s[36:37]
	s_add_i32 m0, s46, 0xe000
	s_nop 0
	global_load_lds_dwordx4 v132, s[36:37]
	ds_read_b128 v[140:143], v151
	ds_read_b128 v[144:147], v151 offset:1024
	ds_read_b128 v[156:159], v151 offset:2048
	ds_read_b128 v[160:163], v151 offset:3072
	ds_read_b128 v[164:167], v152
	ds_read_b128 v[168:171], v152 offset:1024
	ds_read_b128 v[172:175], v152 offset:2048
	ds_read_b128 v[176:179], v152 offset:3072
	ds_read_b128 v[180:183], v153
	ds_read_b128 v[184:187], v153 offset:1024
	ds_read_b128 v[188:191], v153 offset:2048
	ds_read_b128 v[192:195], v153 offset:3072
	ds_read_b128 v[196:199], v153 offset:4096
	ds_read_b128 v[200:203], v153 offset:5120
	ds_read_b128 v[208:211], v153 offset:6144
	ds_read_b128 v[212:215], v153 offset:7168
	s_waitcnt vmcnt(8)
	s_waitcnt lgkmcnt(0)
	s_barrier
	v_mfma_f32_16x16x32_bf16 v[124:127], v[140:143], v[180:183], v[124:127]
	v_mfma_f32_16x16x32_bf16 v[120:123], v[156:159], v[180:183], v[120:123]
	v_mfma_f32_16x16x32_bf16 v[108:111], v[140:143], v[188:191], v[108:111]
	v_mfma_f32_16x16x32_bf16 v[104:107], v[156:159], v[188:191], v[104:107]
	v_mfma_f32_16x16x32_bf16 v[92:95], v[140:143], v[196:199], v[92:95]
	v_mfma_f32_16x16x32_bf16 v[88:91], v[156:159], v[196:199], v[88:91]
	v_mfma_f32_16x16x32_bf16 v[76:79], v[140:143], v[208:211], v[76:79]
	v_mfma_f32_16x16x32_bf16 v[72:75], v[156:159], v[208:211], v[72:75]
	v_mfma_f32_16x16x32_bf16 v[124:127], v[144:147], v[184:187], v[124:127]
	v_mfma_f32_16x16x32_bf16 v[120:123], v[160:163], v[184:187], v[120:123]
	v_mfma_f32_16x16x32_bf16 v[108:111], v[144:147], v[192:195], v[108:111]
	v_mfma_f32_16x16x32_bf16 v[104:107], v[160:163], v[192:195], v[104:107]
	v_mfma_f32_16x16x32_bf16 v[92:95], v[144:147], v[200:203], v[92:95]
	v_mfma_f32_16x16x32_bf16 v[88:91], v[160:163], v[200:203], v[88:91]
	v_mfma_f32_16x16x32_bf16 v[76:79], v[144:147], v[212:215], v[76:79]
	v_mfma_f32_16x16x32_bf16 v[72:75], v[160:163], v[212:215], v[72:75]
	v_mfma_f32_16x16x32_bf16 v[116:119], v[164:167], v[180:183], v[116:119]
	v_mfma_f32_16x16x32_bf16 v[112:115], v[172:175], v[180:183], v[112:115]
	v_mfma_f32_16x16x32_bf16 v[100:103], v[164:167], v[188:191], v[100:103]
	v_mfma_f32_16x16x32_bf16 v[96:99], v[172:175], v[188:191], v[96:99]
	v_mfma_f32_16x16x32_bf16 v[84:87], v[164:167], v[196:199], v[84:87]
	v_mfma_f32_16x16x32_bf16 v[80:83], v[172:175], v[196:199], v[80:83]
	v_mfma_f32_16x16x32_bf16 v[68:71], v[164:167], v[208:211], v[68:71]
	v_mfma_f32_16x16x32_bf16 v[64:67], v[172:175], v[208:211], v[64:67]
	v_mfma_f32_16x16x32_bf16 v[116:119], v[168:171], v[184:187], v[116:119]
	v_mfma_f32_16x16x32_bf16 v[112:115], v[176:179], v[184:187], v[112:115]
	v_mfma_f32_16x16x32_bf16 v[100:103], v[168:171], v[192:195], v[100:103]
	v_mfma_f32_16x16x32_bf16 v[96:99], v[176:179], v[192:195], v[96:99]
	v_mfma_f32_16x16x32_bf16 v[84:87], v[168:171], v[200:203], v[84:87]
	v_mfma_f32_16x16x32_bf16 v[80:83], v[176:179], v[200:203], v[80:83]
	v_mfma_f32_16x16x32_bf16 v[68:71], v[168:171], v[212:215], v[68:71]
	v_mfma_f32_16x16x32_bf16 v[64:67], v[176:179], v[212:215], v[64:67]
	s_barrier
	s_add_i32 s62, s54, s45
	s_mov_b32 m0, s62
	s_nop 0
	global_load_lds_dwordx4 v128, s[38:39]
	s_add_i32 m0, s62, 0x2000
	s_add_u32 s62, s38, 0x40000
	s_mov_b64 s[98:99], s[38:39]
	s_addc_u32 s63, s39, 0
	s_add_i32 s64, s55, s45
	global_load_lds_dwordx4 v130, s[38:39]
	s_mov_b32 m0, s64
	s_mov_b64 s[100:101], s[40:41]
	global_load_lds_dwordx4 v128, s[62:63]
	s_add_i32 m0, s64, 0x2000
	s_nop 0
	global_load_lds_dwordx4 v130, s[62:63]
	ds_read_b128 v[180:183], v153 offset:16384
	ds_read_b128 v[184:187], v153 offset:17408
	ds_read_b128 v[188:191], v153 offset:18432
	ds_read_b128 v[192:195], v153 offset:19456
	ds_read_b128 v[196:199], v153 offset:20480
	ds_read_b128 v[200:203], v153 offset:21504
	ds_read_b128 v[208:211], v153 offset:22528
	ds_read_b128 v[212:215], v153 offset:23552
	s_waitcnt vmcnt(6)
	s_waitcnt lgkmcnt(0)
	s_barrier
	v_mfma_f32_16x16x32_bf16 v[60:63], v[140:143], v[180:183], v[60:63]
	v_mfma_f32_16x16x32_bf16 v[56:59], v[156:159], v[180:183], v[56:59]
	v_mfma_f32_16x16x32_bf16 v[44:47], v[140:143], v[188:191], v[44:47]
	v_mfma_f32_16x16x32_bf16 v[40:43], v[156:159], v[188:191], v[40:43]
	v_mfma_f32_16x16x32_bf16 v[28:31], v[140:143], v[196:199], v[28:31]
	v_mfma_f32_16x16x32_bf16 v[24:27], v[156:159], v[196:199], v[24:27]
	v_mfma_f32_16x16x32_bf16 v[12:15], v[140:143], v[208:211], v[12:15]
	v_mfma_f32_16x16x32_bf16 v[8:11], v[156:159], v[208:211], v[8:11]
	v_mfma_f32_16x16x32_bf16 v[60:63], v[144:147], v[184:187], v[60:63]
	v_mfma_f32_16x16x32_bf16 v[56:59], v[160:163], v[184:187], v[56:59]
	v_mfma_f32_16x16x32_bf16 v[44:47], v[144:147], v[192:195], v[44:47]
	v_mfma_f32_16x16x32_bf16 v[40:43], v[160:163], v[192:195], v[40:43]
	v_mfma_f32_16x16x32_bf16 v[28:31], v[144:147], v[200:203], v[28:31]
	v_mfma_f32_16x16x32_bf16 v[24:27], v[160:163], v[200:203], v[24:27]
	v_mfma_f32_16x16x32_bf16 v[12:15], v[144:147], v[212:215], v[12:15]
	v_mfma_f32_16x16x32_bf16 v[8:11], v[160:163], v[212:215], v[8:11]
	v_mfma_f32_16x16x32_bf16 v[52:55], v[164:167], v[180:183], v[52:55]
	v_mfma_f32_16x16x32_bf16 v[48:51], v[172:175], v[180:183], v[48:51]
	v_mfma_f32_16x16x32_bf16 v[36:39], v[164:167], v[188:191], v[36:39]
	v_mfma_f32_16x16x32_bf16 v[32:35], v[172:175], v[188:191], v[32:35]
	v_mfma_f32_16x16x32_bf16 v[20:23], v[164:167], v[196:199], v[20:23]
	v_mfma_f32_16x16x32_bf16 v[16:19], v[172:175], v[196:199], v[16:19]
	v_mfma_f32_16x16x32_bf16 v[4:7], v[164:167], v[208:211], v[4:7]
	v_mfma_f32_16x16x32_bf16 v[0:3], v[172:175], v[208:211], v[0:3]
	v_mfma_f32_16x16x32_bf16 v[52:55], v[168:171], v[184:187], v[52:55]
	v_mfma_f32_16x16x32_bf16 v[48:51], v[176:179], v[184:187], v[48:51]
	v_mfma_f32_16x16x32_bf16 v[36:39], v[168:171], v[192:195], v[36:39]
	v_mfma_f32_16x16x32_bf16 v[32:35], v[176:179], v[192:195], v[32:35]
	v_mfma_f32_16x16x32_bf16 v[20:23], v[168:171], v[200:203], v[20:23]
	v_mfma_f32_16x16x32_bf16 v[16:19], v[176:179], v[200:203], v[16:19]
	v_mfma_f32_16x16x32_bf16 v[4:7], v[168:171], v[212:215], v[4:7]
	v_mfma_f32_16x16x32_bf16 v[0:3], v[176:179], v[212:215], v[0:3]
	s_barrier
	s_mov_b32 m0, s46
	s_nop 0
	global_load_lds_dwordx4 v128, s[40:41]
	s_mov_b32 m0, s47
	s_nop 0
	global_load_lds_dwordx4 v130, s[40:41]
	s_add_i32 s62, 0, 0x18000
	s_add_i32 s63, 0, 0x1c000
	s_add_u32 s40, s40, 0x40000
	s_addc_u32 s41, s41, 0
	s_mov_b32 m0, s48
	s_nop 0
	global_load_lds_dwordx4 v128, s[40:41]
	s_mov_b32 m0, s49
	s_nop 0
	global_load_lds_dwordx4 v130, s[40:41]
	v_add_u32_e32 v155, s62, v149
	ds_read_b128 v[140:143], v155
	ds_read_b128 v[144:147], v155 offset:1024
	ds_read_b128 v[156:159], v155 offset:2048
	ds_read_b128 v[160:163], v155 offset:3072
	v_add_u32_e32 v155, s63, v149
	ds_read_b128 v[164:167], v155
	ds_read_b128 v[168:171], v155 offset:1024
	ds_read_b128 v[172:175], v155 offset:2048
	ds_read_b128 v[176:179], v155 offset:3072
	ds_read_b128 v[180:183], v153 offset:32768
	ds_read_b128 v[184:187], v153 offset:33792
	ds_read_b128 v[188:191], v153 offset:34816
	ds_read_b128 v[192:195], v153 offset:35840
	ds_read_b128 v[196:199], v153 offset:36864
	ds_read_b128 v[200:203], v153 offset:37888
	ds_read_b128 v[208:211], v153 offset:38912
	ds_read_b128 v[212:215], v153 offset:39936
	s_waitcnt vmcnt(8)
	s_waitcnt lgkmcnt(0)
	s_barrier
	v_mfma_f32_16x16x32_bf16 v[124:127], v[140:143], v[180:183], v[124:127]
	v_mfma_f32_16x16x32_bf16 v[120:123], v[156:159], v[180:183], v[120:123]
	v_mfma_f32_16x16x32_bf16 v[108:111], v[140:143], v[188:191], v[108:111]
	v_mfma_f32_16x16x32_bf16 v[104:107], v[156:159], v[188:191], v[104:107]
	v_mfma_f32_16x16x32_bf16 v[92:95], v[140:143], v[196:199], v[92:95]
	v_mfma_f32_16x16x32_bf16 v[88:91], v[156:159], v[196:199], v[88:91]
	v_mfma_f32_16x16x32_bf16 v[76:79], v[140:143], v[208:211], v[76:79]
	v_mfma_f32_16x16x32_bf16 v[72:75], v[156:159], v[208:211], v[72:75]
	v_mfma_f32_16x16x32_bf16 v[124:127], v[144:147], v[184:187], v[124:127]
	v_mfma_f32_16x16x32_bf16 v[120:123], v[160:163], v[184:187], v[120:123]
	v_mfma_f32_16x16x32_bf16 v[108:111], v[144:147], v[192:195], v[108:111]
	v_mfma_f32_16x16x32_bf16 v[104:107], v[160:163], v[192:195], v[104:107]
	v_mfma_f32_16x16x32_bf16 v[92:95], v[144:147], v[200:203], v[92:95]
	v_mfma_f32_16x16x32_bf16 v[88:91], v[160:163], v[200:203], v[88:91]
	v_mfma_f32_16x16x32_bf16 v[76:79], v[144:147], v[212:215], v[76:79]
	v_mfma_f32_16x16x32_bf16 v[72:75], v[160:163], v[212:215], v[72:75]
	v_mfma_f32_16x16x32_bf16 v[116:119], v[164:167], v[180:183], v[116:119]
	v_mfma_f32_16x16x32_bf16 v[112:115], v[172:175], v[180:183], v[112:115]
	v_mfma_f32_16x16x32_bf16 v[100:103], v[164:167], v[188:191], v[100:103]
	v_mfma_f32_16x16x32_bf16 v[96:99], v[172:175], v[188:191], v[96:99]
	v_mfma_f32_16x16x32_bf16 v[84:87], v[164:167], v[196:199], v[84:87]
	v_mfma_f32_16x16x32_bf16 v[80:83], v[172:175], v[196:199], v[80:83]
	v_mfma_f32_16x16x32_bf16 v[68:71], v[164:167], v[208:211], v[68:71]
	v_mfma_f32_16x16x32_bf16 v[64:67], v[172:175], v[208:211], v[64:67]
	v_mfma_f32_16x16x32_bf16 v[116:119], v[168:171], v[184:187], v[116:119]
	v_mfma_f32_16x16x32_bf16 v[112:115], v[176:179], v[184:187], v[112:115]
	v_mfma_f32_16x16x32_bf16 v[100:103], v[168:171], v[192:195], v[100:103]
	v_mfma_f32_16x16x32_bf16 v[96:99], v[176:179], v[192:195], v[96:99]
	v_mfma_f32_16x16x32_bf16 v[84:87], v[168:171], v[200:203], v[84:87]
	v_mfma_f32_16x16x32_bf16 v[80:83], v[176:179], v[200:203], v[80:83]
	v_mfma_f32_16x16x32_bf16 v[68:71], v[168:171], v[212:215], v[68:71]
	v_mfma_f32_16x16x32_bf16 v[64:67], v[176:179], v[212:215], v[64:67]
	s_barrier
	s_add_i32 s40, s62, s45
	s_mov_b32 m0, s40
	s_nop 0
	global_load_lds_dwordx4 v204, s[38:39]
	s_add_i32 m0, s40, 0x2000
	s_add_u32 s38, s38, 0x40080
	s_addc_u32 s39, s39, 0
	s_add_i32 s40, s63, s45
	global_load_lds_dwordx4 v205, s[98:99]
	s_mov_b32 m0, s40
	s_nop 0
	global_load_lds_dwordx4 v128, s[38:39]
	s_add_i32 m0, s40, 0x2000
	s_nop 0
	global_load_lds_dwordx4 v130, s[38:39]
	s_cmp_lg_u32 s61, 12
	s_cbranch_scc1 .Lbal_last_11
	s_mov_b32 m0, s51
	s_nop 0
	global_load_lds_dwordx4 v204, s[100:101]
	s_mov_b32 m0, s52
	s_nop 0
	global_load_lds_dwordx4 v205, s[100:101]
.Lbal_last_11:
	ds_read_b128 v[180:183], v153 offset:49152
	ds_read_b128 v[184:187], v153 offset:50176
	ds_read_b128 v[188:191], v153 offset:51200
	ds_read_b128 v[192:195], v153 offset:52224
	ds_read_b128 v[196:199], v153 offset:53248
	ds_read_b128 v[200:203], v153 offset:54272
	ds_read_b128 v[208:211], v153 offset:55296
	ds_read_b128 v[212:215], v153 offset:56320
	s_waitcnt vmcnt(6)
	s_waitcnt lgkmcnt(0)
	s_barrier
	v_mfma_f32_16x16x32_bf16 v[60:63], v[140:143], v[180:183], v[60:63]
	v_mfma_f32_16x16x32_bf16 v[56:59], v[156:159], v[180:183], v[56:59]
	v_mfma_f32_16x16x32_bf16 v[44:47], v[140:143], v[188:191], v[44:47]
	v_mfma_f32_16x16x32_bf16 v[40:43], v[156:159], v[188:191], v[40:43]
	s_add_i32 s61, s61, 2
	s_add_u32 s59, s59, 0x100
	s_addc_u32 s60, s60, 0
	s_add_u32 s36, s36, 0x100
	s_addc_u32 s37, s37, 0
	s_cmp_gt_u32 s61, 13
	v_mfma_f32_16x16x32_bf16 v[28:31], v[140:143], v[196:199], v[28:31]
	v_mfma_f32_16x16x32_bf16 v[24:27], v[156:159], v[196:199], v[24:27]
	v_mfma_f32_16x16x32_bf16 v[12:15], v[140:143], v[208:211], v[12:15]
	v_mfma_f32_16x16x32_bf16 v[8:11], v[156:159], v[208:211], v[8:11]
	v_mfma_f32_16x16x32_bf16 v[60:63], v[144:147], v[184:187], v[60:63]
	v_mfma_f32_16x16x32_bf16 v[56:59], v[160:163], v[184:187], v[56:59]
	v_mfma_f32_16x16x32_bf16 v[44:47], v[144:147], v[192:195], v[44:47]
	v_mfma_f32_16x16x32_bf16 v[40:43], v[160:163], v[192:195], v[40:43]
	v_mfma_f32_16x16x32_bf16 v[28:31], v[144:147], v[200:203], v[28:31]
	v_mfma_f32_16x16x32_bf16 v[24:27], v[160:163], v[200:203], v[24:27]
	v_mfma_f32_16x16x32_bf16 v[12:15], v[144:147], v[212:215], v[12:15]
	v_mfma_f32_16x16x32_bf16 v[8:11], v[160:163], v[212:215], v[8:11]
	v_mfma_f32_16x16x32_bf16 v[52:55], v[164:167], v[180:183], v[52:55]
	v_mfma_f32_16x16x32_bf16 v[48:51], v[172:175], v[180:183], v[48:51]
	v_mfma_f32_16x16x32_bf16 v[36:39], v[164:167], v[188:191], v[36:39]
	v_mfma_f32_16x16x32_bf16 v[32:35], v[172:175], v[188:191], v[32:35]
	v_mfma_f32_16x16x32_bf16 v[20:23], v[164:167], v[196:199], v[20:23]
	v_mfma_f32_16x16x32_bf16 v[16:19], v[172:175], v[196:199], v[16:19]
	v_mfma_f32_16x16x32_bf16 v[4:7], v[164:167], v[208:211], v[4:7]
	v_mfma_f32_16x16x32_bf16 v[0:3], v[172:175], v[208:211], v[0:3]
	v_mfma_f32_16x16x32_bf16 v[52:55], v[168:171], v[184:187], v[52:55]
	v_mfma_f32_16x16x32_bf16 v[48:51], v[176:179], v[184:187], v[48:51]
	v_mfma_f32_16x16x32_bf16 v[36:39], v[168:171], v[192:195], v[36:39]
	v_mfma_f32_16x16x32_bf16 v[32:35], v[176:179], v[192:195], v[32:35]
	v_mfma_f32_16x16x32_bf16 v[20:23], v[168:171], v[200:203], v[20:23]
	v_mfma_f32_16x16x32_bf16 v[16:19], v[176:179], v[200:203], v[16:19]
	v_mfma_f32_16x16x32_bf16 v[4:7], v[168:171], v[212:215], v[4:7]
	v_mfma_f32_16x16x32_bf16 v[0:3], v[176:179], v[212:215], v[0:3]
	s_barrier
	s_cbranch_scc0 .LBB0_1561
	s_setprio 0
	s_and_b64 vcc, exec, s[24:25]
	s_cbranch_vccz .LBB0_1564
	s_barrier

.Lbal_first_10:
	s_add_u32 s26, s24, 0xfffc0080
	s_addc_u32 s27, s25, -1
	s_cmp_eq_u32 s54, 12
	s_cselect_b32 s29, s19, s27
	s_cselect_b32 s28, s50, s26
	s_cselect_b32 s27, s17, s53
	s_cselect_b32 s26, s51, s52
	s_add_i32 m0, s38, 0xc000
	s_nop 0
	global_load_lds_dwordx4 v138, s[24:25]
	s_add_i32 m0, s38, 0xe000
	s_nop 0
	global_load_lds_dwordx4 v136, s[24:25]
	ds_read_b128 v[144:147], v151
	ds_read_b128 v[156:159], v151 offset:1024
	ds_read_b128 v[160:163], v151 offset:2048
	ds_read_b128 v[164:167], v151 offset:3072
	ds_read_b128 v[168:171], v152
	ds_read_b128 v[172:175], v152 offset:1024
	ds_read_b128 v[176:179], v152 offset:2048
	ds_read_b128 v[180:183], v152 offset:3072
	ds_read_b128 v[184:187], v153
	ds_read_b128 v[188:191], v153 offset:1024
	ds_read_b128 v[192:195], v153 offset:2048
	ds_read_b128 v[196:199], v153 offset:3072
	ds_read_b128 v[200:203], v153 offset:4096
	ds_read_b128 v[208:211], v153 offset:5120
	ds_read_b128 v[212:215], v153 offset:6144
	ds_read_b128 v[216:219], v153 offset:7168
	s_waitcnt vmcnt(8)
	s_waitcnt lgkmcnt(0)
	s_barrier
	v_mfma_f32_16x16x32_bf16 v[124:127], v[144:147], v[184:187], v[124:127]
	v_mfma_f32_16x16x32_bf16 v[120:123], v[160:163], v[184:187], v[120:123]
	v_mfma_f32_16x16x32_bf16 v[108:111], v[144:147], v[192:195], v[108:111]
	v_mfma_f32_16x16x32_bf16 v[104:107], v[160:163], v[192:195], v[104:107]
	v_mfma_f32_16x16x32_bf16 v[92:95], v[144:147], v[200:203], v[92:95]
	v_mfma_f32_16x16x32_bf16 v[88:91], v[160:163], v[200:203], v[88:91]
	v_mfma_f32_16x16x32_bf16 v[76:79], v[144:147], v[212:215], v[76:79]
	v_mfma_f32_16x16x32_bf16 v[72:75], v[160:163], v[212:215], v[72:75]
	v_mfma_f32_16x16x32_bf16 v[124:127], v[156:159], v[188:191], v[124:127]
	v_mfma_f32_16x16x32_bf16 v[120:123], v[164:167], v[188:191], v[120:123]
	v_mfma_f32_16x16x32_bf16 v[108:111], v[156:159], v[196:199], v[108:111]
	v_mfma_f32_16x16x32_bf16 v[104:107], v[164:167], v[196:199], v[104:107]
	v_mfma_f32_16x16x32_bf16 v[92:95], v[156:159], v[208:211], v[92:95]
	v_mfma_f32_16x16x32_bf16 v[88:91], v[164:167], v[208:211], v[88:91]
	v_mfma_f32_16x16x32_bf16 v[76:79], v[156:159], v[216:219], v[76:79]
	v_mfma_f32_16x16x32_bf16 v[72:75], v[164:167], v[216:219], v[72:75]
	v_mfma_f32_16x16x32_bf16 v[116:119], v[168:171], v[184:187], v[116:119]
	v_mfma_f32_16x16x32_bf16 v[112:115], v[176:179], v[184:187], v[112:115]
	v_mfma_f32_16x16x32_bf16 v[100:103], v[168:171], v[192:195], v[100:103]
	v_mfma_f32_16x16x32_bf16 v[96:99], v[176:179], v[192:195], v[96:99]
	v_mfma_f32_16x16x32_bf16 v[84:87], v[168:171], v[200:203], v[84:87]
	v_mfma_f32_16x16x32_bf16 v[80:83], v[176:179], v[200:203], v[80:83]
	v_mfma_f32_16x16x32_bf16 v[68:71], v[168:171], v[212:215], v[68:71]
	v_mfma_f32_16x16x32_bf16 v[64:67], v[176:179], v[212:215], v[64:67]
	v_mfma_f32_16x16x32_bf16 v[116:119], v[172:175], v[188:191], v[116:119]
	v_mfma_f32_16x16x32_bf16 v[112:115], v[180:183], v[188:191], v[112:115]
	v_mfma_f32_16x16x32_bf16 v[100:103], v[172:175], v[196:199], v[100:103]
	v_mfma_f32_16x16x32_bf16 v[96:99], v[180:183], v[196:199], v[96:99]
	v_mfma_f32_16x16x32_bf16 v[84:87], v[172:175], v[208:211], v[84:87]
	v_mfma_f32_16x16x32_bf16 v[80:83], v[180:183], v[208:211], v[80:83]
	v_mfma_f32_16x16x32_bf16 v[68:71], v[172:175], v[216:219], v[68:71]
	v_mfma_f32_16x16x32_bf16 v[64:67], v[180:183], v[216:219], v[64:67]
	s_barrier
	s_add_i32 s55, s47, s35
	s_mov_b32 m0, s55
	s_nop 0
	global_load_lds_dwordx4 v132, s[26:27]
	s_add_i32 m0, s55, 0x2000
	s_add_u32 s56, s26, 0x40000
	s_mov_b64 s[98:99], s[26:27]
	s_addc_u32 s57, s27, 0
	s_add_i32 s55, s48, s35
	global_load_lds_dwordx4 v128, s[26:27]
	s_mov_b32 m0, s55
	s_mov_b64 s[100:101], s[28:29]
	global_load_lds_dwordx4 v132, s[56:57]
	s_add_i32 m0, s55, 0x2000
	s_nop 0
	global_load_lds_dwordx4 v128, s[56:57]
	ds_read_b128 v[184:187], v153 offset:16384
	ds_read_b128 v[188:191], v153 offset:17408
	ds_read_b128 v[192:195], v153 offset:18432
	ds_read_b128 v[196:199], v153 offset:19456
	ds_read_b128 v[200:203], v153 offset:20480
	ds_read_b128 v[208:211], v153 offset:21504
	ds_read_b128 v[212:215], v153 offset:22528
	ds_read_b128 v[216:219], v153 offset:23552
	s_waitcnt vmcnt(6)
	s_waitcnt lgkmcnt(0)
	s_barrier
	v_mfma_f32_16x16x32_bf16 v[60:63], v[144:147], v[184:187], v[60:63]
	v_mfma_f32_16x16x32_bf16 v[56:59], v[160:163], v[184:187], v[56:59]
	v_mfma_f32_16x16x32_bf16 v[44:47], v[144:147], v[192:195], v[44:47]
	v_mfma_f32_16x16x32_bf16 v[40:43], v[160:163], v[192:195], v[40:43]
	v_mfma_f32_16x16x32_bf16 v[28:31], v[144:147], v[200:203], v[28:31]
	v_mfma_f32_16x16x32_bf16 v[24:27], v[160:163], v[200:203], v[24:27]
	v_mfma_f32_16x16x32_bf16 v[12:15], v[144:147], v[212:215], v[12:15]
	v_mfma_f32_16x16x32_bf16 v[8:11], v[160:163], v[212:215], v[8:11]
	v_mfma_f32_16x16x32_bf16 v[60:63], v[156:159], v[188:191], v[60:63]
	v_mfma_f32_16x16x32_bf16 v[56:59], v[164:167], v[188:191], v[56:59]
	v_mfma_f32_16x16x32_bf16 v[44:47], v[156:159], v[196:199], v[44:47]
	v_mfma_f32_16x16x32_bf16 v[40:43], v[164:167], v[196:199], v[40:43]
	v_mfma_f32_16x16x32_bf16 v[28:31], v[156:159], v[208:211], v[28:31]
	v_mfma_f32_16x16x32_bf16 v[24:27], v[164:167], v[208:211], v[24:27]
	v_mfma_f32_16x16x32_bf16 v[12:15], v[156:159], v[216:219], v[12:15]
	v_mfma_f32_16x16x32_bf16 v[8:11], v[164:167], v[216:219], v[8:11]
	v_mfma_f32_16x16x32_bf16 v[52:55], v[168:171], v[184:187], v[52:55]
	v_mfma_f32_16x16x32_bf16 v[48:51], v[176:179], v[184:187], v[48:51]
	v_mfma_f32_16x16x32_bf16 v[36:39], v[168:171], v[192:195], v[36:39]
	v_mfma_f32_16x16x32_bf16 v[32:35], v[176:179], v[192:195], v[32:35]
	v_mfma_f32_16x16x32_bf16 v[20:23], v[168:171], v[200:203], v[20:23]
	v_mfma_f32_16x16x32_bf16 v[16:19], v[176:179], v[200:203], v[16:19]
	v_mfma_f32_16x16x32_bf16 v[4:7], v[168:171], v[212:215], v[4:7]
	v_mfma_f32_16x16x32_bf16 v[0:3], v[176:179], v[212:215], v[0:3]
	v_mfma_f32_16x16x32_bf16 v[52:55], v[172:175], v[188:191], v[52:55]
	v_mfma_f32_16x16x32_bf16 v[48:51], v[180:183], v[188:191], v[48:51]
	v_mfma_f32_16x16x32_bf16 v[36:39], v[172:175], v[196:199], v[36:39]
	v_mfma_f32_16x16x32_bf16 v[32:35], v[180:183], v[196:199], v[32:35]
	v_mfma_f32_16x16x32_bf16 v[20:23], v[172:175], v[208:211], v[20:23]
	v_mfma_f32_16x16x32_bf16 v[16:19], v[180:183], v[208:211], v[16:19]
	v_mfma_f32_16x16x32_bf16 v[4:7], v[172:175], v[216:219], v[4:7]
	v_mfma_f32_16x16x32_bf16 v[0:3], v[180:183], v[216:219], v[0:3]
	s_barrier
	s_mov_b32 m0, s38
	s_nop 0
	global_load_lds_dwordx4 v134, s[28:29]
	s_mov_b32 m0, s39
	s_nop 0
	global_load_lds_dwordx4 v130, s[28:29]
	s_add_i32 s55, 0, 0x18000
	s_add_i32 s56, 0, 0x1c000
	s_add_u32 s28, s28, 0x40000
	s_addc_u32 s29, s29, 0
	s_mov_b32 m0, s40
	s_nop 0
	global_load_lds_dwordx4 v134, s[28:29]
	s_mov_b32 m0, s41
	s_nop 0
	global_load_lds_dwordx4 v130, s[28:29]
	v_add_u32_e32 v164, s55, v149
	v_add_u32_e32 v180, s56, v149
	ds_read_b128 v[144:147], v164
	ds_read_b128 v[156:159], v164 offset:1024
	ds_read_b128 v[160:163], v164 offset:2048
	ds_read_b128 v[164:167], v164 offset:3072
	ds_read_b128 v[168:171], v180
	ds_read_b128 v[172:175], v180 offset:1024
	ds_read_b128 v[176:179], v180 offset:2048
	ds_read_b128 v[180:183], v180 offset:3072
	ds_read_b128 v[184:187], v153 offset:32768
	ds_read_b128 v[188:191], v153 offset:33792
	ds_read_b128 v[192:195], v153 offset:34816
	ds_read_b128 v[196:199], v153 offset:35840
	ds_read_b128 v[200:203], v153 offset:36864
	ds_read_b128 v[208:211], v153 offset:37888
	ds_read_b128 v[212:215], v153 offset:38912
	ds_read_b128 v[216:219], v153 offset:39936
	s_waitcnt vmcnt(8)
	s_waitcnt lgkmcnt(0)
	s_barrier
	v_mfma_f32_16x16x32_bf16 v[124:127], v[144:147], v[184:187], v[124:127]
	v_mfma_f32_16x16x32_bf16 v[120:123], v[160:163], v[184:187], v[120:123]
	v_mfma_f32_16x16x32_bf16 v[108:111], v[144:147], v[192:195], v[108:111]
	v_mfma_f32_16x16x32_bf16 v[104:107], v[160:163], v[192:195], v[104:107]
	v_mfma_f32_16x16x32_bf16 v[92:95], v[144:147], v[200:203], v[92:95]
	v_mfma_f32_16x16x32_bf16 v[88:91], v[160:163], v[200:203], v[88:91]
	v_mfma_f32_16x16x32_bf16 v[76:79], v[144:147], v[212:215], v[76:79]
	v_mfma_f32_16x16x32_bf16 v[72:75], v[160:163], v[212:215], v[72:75]
	v_mfma_f32_16x16x32_bf16 v[124:127], v[156:159], v[188:191], v[124:127]
	v_mfma_f32_16x16x32_bf16 v[120:123], v[164:167], v[188:191], v[120:123]
	v_mfma_f32_16x16x32_bf16 v[108:111], v[156:159], v[196:199], v[108:111]
	v_mfma_f32_16x16x32_bf16 v[104:107], v[164:167], v[196:199], v[104:107]
	v_mfma_f32_16x16x32_bf16 v[92:95], v[156:159], v[208:211], v[92:95]
	v_mfma_f32_16x16x32_bf16 v[88:91], v[164:167], v[208:211], v[88:91]
	v_mfma_f32_16x16x32_bf16 v[76:79], v[156:159], v[216:219], v[76:79]
	v_mfma_f32_16x16x32_bf16 v[72:75], v[164:167], v[216:219], v[72:75]
	v_mfma_f32_16x16x32_bf16 v[116:119], v[168:171], v[184:187], v[116:119]
	v_mfma_f32_16x16x32_bf16 v[112:115], v[176:179], v[184:187], v[112:115]
	v_mfma_f32_16x16x32_bf16 v[100:103], v[168:171], v[192:195], v[100:103]
	v_mfma_f32_16x16x32_bf16 v[96:99], v[176:179], v[192:195], v[96:99]
	v_mfma_f32_16x16x32_bf16 v[84:87], v[168:171], v[200:203], v[84:87]
	v_mfma_f32_16x16x32_bf16 v[80:83], v[176:179], v[200:203], v[80:83]
	v_mfma_f32_16x16x32_bf16 v[68:71], v[168:171], v[212:215], v[68:71]
	v_mfma_f32_16x16x32_bf16 v[64:67], v[176:179], v[212:215], v[64:67]
	v_mfma_f32_16x16x32_bf16 v[116:119], v[172:175], v[188:191], v[116:119]
	v_mfma_f32_16x16x32_bf16 v[112:115], v[180:183], v[188:191], v[112:115]
	v_mfma_f32_16x16x32_bf16 v[100:103], v[172:175], v[196:199], v[100:103]
	v_mfma_f32_16x16x32_bf16 v[96:99], v[180:183], v[196:199], v[96:99]
	v_mfma_f32_16x16x32_bf16 v[84:87], v[172:175], v[208:211], v[84:87]
	v_mfma_f32_16x16x32_bf16 v[80:83], v[180:183], v[208:211], v[80:83]
	v_mfma_f32_16x16x32_bf16 v[68:71], v[172:175], v[216:219], v[68:71]
	v_mfma_f32_16x16x32_bf16 v[64:67], v[180:183], v[216:219], v[64:67]
	s_barrier
	s_add_i32 s28, s55, s35
	s_mov_b32 m0, s28
	s_nop 0
	global_load_lds_dwordx4 v220, s[26:27]
	s_add_i32 m0, s28, 0x2000
	s_add_u32 s26, s26, 0x40080
	s_addc_u32 s27, s27, 0
	s_add_i32 s28, s56, s35
	global_load_lds_dwordx4 v204, s[98:99]
	s_mov_b32 m0, s28
	s_nop 0
	global_load_lds_dwordx4 v132, s[26:27]
	s_add_i32 m0, s28, 0x2000
	s_nop 0
	global_load_lds_dwordx4 v128, s[26:27]
	s_cmp_lg_u32 s54, 12
	s_cbranch_scc1 .Lbal_last_10
	s_mov_b32 m0, s45
	s_nop 0
	global_load_lds_dwordx4 v221, s[100:101]
	s_mov_b32 m0, s46
	s_nop 0
	global_load_lds_dwordx4 v205, s[100:101]
.Lbal_last_10:
	ds_read_b128 v[184:187], v153 offset:49152
	ds_read_b128 v[188:191], v153 offset:50176
	ds_read_b128 v[192:195], v153 offset:51200
	ds_read_b128 v[196:199], v153 offset:52224
	ds_read_b128 v[200:203], v153 offset:53248
	ds_read_b128 v[208:211], v153 offset:54272
	ds_read_b128 v[212:215], v153 offset:55296
	ds_read_b128 v[216:219], v153 offset:56320
	s_waitcnt vmcnt(6)
	s_waitcnt lgkmcnt(0)
	s_barrier
	v_mfma_f32_16x16x32_bf16 v[60:63], v[144:147], v[184:187], v[60:63]
	v_mfma_f32_16x16x32_bf16 v[56:59], v[160:163], v[184:187], v[56:59]
	v_mfma_f32_16x16x32_bf16 v[44:47], v[144:147], v[192:195], v[44:47]
	v_mfma_f32_16x16x32_bf16 v[40:43], v[160:163], v[192:195], v[40:43]
	s_add_i32 s54, s54, 2
	s_add_u32 s52, s52, 0x100
	s_addc_u32 s53, s53, 0
	s_add_u32 s24, s24, 0x100
	s_addc_u32 s25, s25, 0
	s_cmp_gt_u32 s54, 13
	v_mfma_f32_16x16x32_bf16 v[28:31], v[144:147], v[200:203], v[28:31]
	v_mfma_f32_16x16x32_bf16 v[24:27], v[160:163], v[200:203], v[24:27]
	v_mfma_f32_16x16x32_bf16 v[12:15], v[144:147], v[212:215], v[12:15]
	v_mfma_f32_16x16x32_bf16 v[8:11], v[160:163], v[212:215], v[8:11]
	v_mfma_f32_16x16x32_bf16 v[60:63], v[156:159], v[188:191], v[60:63]
	v_mfma_f32_16x16x32_bf16 v[56:59], v[164:167], v[188:191], v[56:59]
	v_mfma_f32_16x16x32_bf16 v[44:47], v[156:159], v[196:199], v[44:47]
	v_mfma_f32_16x16x32_bf16 v[40:43], v[164:167], v[196:199], v[40:43]
	v_mfma_f32_16x16x32_bf16 v[28:31], v[156:159], v[208:211], v[28:31]
	v_mfma_f32_16x16x32_bf16 v[24:27], v[164:167], v[208:211], v[24:27]
	v_mfma_f32_16x16x32_bf16 v[12:15], v[156:159], v[216:219], v[12:15]
	v_mfma_f32_16x16x32_bf16 v[8:11], v[164:167], v[216:219], v[8:11]
	v_mfma_f32_16x16x32_bf16 v[52:55], v[168:171], v[184:187], v[52:55]
	v_mfma_f32_16x16x32_bf16 v[48:51], v[176:179], v[184:187], v[48:51]
	v_mfma_f32_16x16x32_bf16 v[36:39], v[168:171], v[192:195], v[36:39]
	v_mfma_f32_16x16x32_bf16 v[32:35], v[176:179], v[192:195], v[32:35]
	v_mfma_f32_16x16x32_bf16 v[20:23], v[168:171], v[200:203], v[20:23]
	v_mfma_f32_16x16x32_bf16 v[16:19], v[176:179], v[200:203], v[16:19]
	v_mfma_f32_16x16x32_bf16 v[4:7], v[168:171], v[212:215], v[4:7]
	v_mfma_f32_16x16x32_bf16 v[0:3], v[176:179], v[212:215], v[0:3]
	v_mfma_f32_16x16x32_bf16 v[52:55], v[172:175], v[188:191], v[52:55]
	v_mfma_f32_16x16x32_bf16 v[48:51], v[180:183], v[188:191], v[48:51]
	v_mfma_f32_16x16x32_bf16 v[36:39], v[172:175], v[196:199], v[36:39]
	v_mfma_f32_16x16x32_bf16 v[32:35], v[180:183], v[196:199], v[32:35]
	v_mfma_f32_16x16x32_bf16 v[20:23], v[172:175], v[208:211], v[20:23]
	v_mfma_f32_16x16x32_bf16 v[16:19], v[180:183], v[208:211], v[16:19]
	v_mfma_f32_16x16x32_bf16 v[4:7], v[172:175], v[216:219], v[4:7]
	v_mfma_f32_16x16x32_bf16 v[0:3], v[180:183], v[216:219], v[0:3]
	s_barrier
	s_cbranch_scc0 .LBB0_1646
	s_setprio 0
	s_and_b64 vcc, exec, s[14:15]
	s_cbranch_vccz .LBB0_1649
	s_barrier
